# v31 plus: trailing half's re-offset barrier moved behind the next unit's tile-order index math (all 12 GEMM phases)
# baseline (speedup 1.0000x reference)
; #define LAS __attribute__((address_space(3)))
; __device__ __forceinline__ unsigned xb_add(unsigned* p, unsigned v) { return __hip_atomic_fetch_add(p, v, __ATOMIC_RELAXED, __HIP_MEMORY_SCOPE_AGENT); }
; __device__ __forceinline__ unsigned xb_xcc_id() { return (unsigned)__builtin_amdgcn_s_getreg((3 << 11) | 20) & 0xFu; }
; __device__ __forceinline__ XcdBarrier xcd_barrier_post(unsigned* bar, volatile LAS unsigned* st, unsigned total) {
;     XcdBarrier b; b.bar = bar; b.x = xb_xcc_id(); b.st = st; b.total = total;
;     if (threadIdx.x == 0) (void)xb_add(&bar[XB_XCNT(b.x)], 1u);
;     return b;
; }
; __global__ void __launch_bounds__(512, 2) fwd(Args a) {
;     extern __shared__ __attribute__((aligned(16))) unsigned char lds_raw[];
;     LAS unsigned char* lds = (LAS unsigned char*)lds_raw;
;     cg::grid_group grid = cg::this_grid();
;     volatile LAS unsigned* MISC = (volatile LAS unsigned*)(lds + 131072 + 320);
;     if (threadIdx.x < 32) MISC[threadIdx.x] = 0u;
;     __syncthreads();
;     XcdBarrier bar = xcd_barrier_post((unsigned*)a.ws + 4096, MISC + 8, gridDim.x);
_Z3fwd4Args:
	s_mov_b32 s99, 0
	s_load_dword s61, s[0:1], 0xe8
	s_add_u32 s6, s0, 0xe8
	v_and_b32_e32 v242, 0x3ff, v0
	s_addc_u32 s7, s1, 0
	v_cmp_gt_u32_e32 vcc, 32, v242
	s_and_saveexec_b64 s[4:5], vcc
	v_lshl_add_u32 v1, v242, 2, 0
	v_add_u32_e32 v1, 0x20140, v1
	v_mov_b32_e32 v2, 0
	ds_write_b32 v1, v2
	s_or_b64 exec, exec, s[4:5]
	s_load_dwordx2 s[26:27], s[0:1], 0xd8
	s_waitcnt lgkmcnt(0)
	s_barrier
	s_getreg_b32 s3, hwreg(HW_REG_XCC_ID, 0, 4)
	s_add_u32 s28, s26, 0x4000
	s_addc_u32 s29, s27, 0
	s_and_b32 s60, s3, 15
	v_cmp_eq_u32_e64 s[10:11], 0, v242
	s_and_saveexec_b64 s[4:5], s[10:11]
	s_cbranch_execz .LBB0_5
	s_mov_b64 s[8:9], exec
	v_mbcnt_lo_u32_b32 v1, s8, 0
	v_mbcnt_hi_u32_b32 v1, s9, v1
	v_cmp_eq_u32_e32 vcc, 0, v1
	s_and_b64 s[12:13], exec, vcc
	s_mov_b64 exec, s[12:13]
	s_cbranch_execz .LBB0_5
	s_lshl_b32 s3, s60, 8
	s_bcnt1_i32_b64 s8, s[8:9]
	v_mov_b32_e32 v1, s3
	v_mov_b32_e32 v2, s8
	global_atomic_add v1, v2, s[28:29] offset:1024

; #define PG8_STAGE(bufoff, gbase, voff) do { _Pragma("unroll") for (int _i = 0; _i < 2; ++_i) \
;         __builtin_amdgcn_global_load_lds((const unsigned*)((const char*)(gbase) + (voff)[_i]), (PG8_LAS unsigned*)(lds + (bufoff) + ldsw + _i * 8192), 16, 0, 0); } while (0)
; #define PG8_LDA(dst, b, h) do { _Pragma("unroll") for (int m = 0; m < 4; ++m) _Pragma("unroll") for (int k = 0; k < 2; ++k) dst[m][k] = *(const PG8_LAS bf16x8*)(lds + PG8_SA(b, h) + aoff + m * 2048 + k * 1024); } while (0)
; #define PG8_LDB(dst, b, h) do { _Pragma("unroll") for (int n = 0; n < 2; ++n) _Pragma("unroll") for (int k = 0; k < 2; ++k) dst[n][k] = *(const PG8_LAS bf16x8*)(lds + PG8_SB(b, h) + boff + n * 2048 + k * 1024); } while (0)
; #define PG8_WAIT_V(n) asm volatile("s_waitcnt vmcnt(" #n ")" ::: "memory")
; #define PG8_WAIT_L(n) asm volatile("s_waitcnt lgkmcnt(" #n ")" ::: "memory")
; #define PG8_BAR __builtin_amdgcn_s_barrier()
; #define PG8_SCHED __builtin_amdgcn_sched_barrier(0)
; template <class Epi, class Sched, bool ALIGN_EPI = false, bool SP2 = false>
; __device__ __forceinline__ void gemm_phase(PG8_LAS unsigned char* lds, const Gemm g, const Sched& S, const Epi& E) {
;     ...
;         const bool has_next = S.next(ui + 1, nxt);
;         const char* nA = has_next ? (const char*)g.A + (size_t)nxt.pm * tstep : cA; const char* nB = has_next ? (const char*)g.Bt + (size_t)nxt.pn * tstep : cB;
;         for (int t = 0; t < nt; t += 2) {
;             const bool last = (t == nt - 2);
;             if constexpr (Epi::PREFETCH) { if (t == nt - 4) E.prefetch(cur, lds + STAGE_BYTES + 1024, tid); }
;             const char* a1 = cA + (size_t)(t + 1) * kstep;
;             const char* a2 = last ? nA : cA + (size_t)(t + 2) * kstep; const char* b2 = last ? nB : cB + (size_t)(t + 2) * kstep;
;             const char* a3 = a2 + kstep; const char* b3 = b2 + kstep;
;             if (last && has_next) S.a_ready(nxt);
;             if constexpr (SP2) {
;             PG8_LDB(B0, 0, 0); PG8_LDB(B1, 0, 1); PG8_SCHED; PG8_LDA(At, 0, 0); PG8_STAGE(PG8_SA(1, 1), a1 + hstep, voffA);
;             PG8_WAIT_V(8); PG8_WAIT_L(0); PG8_BAR; PG8_MMA(0, 0, At, B0); PG8_MMA(0, 1, At, B1); PG8_BAR; PG8_SCHED;
;             PG8_LDA(At, 0, 1); PG8_STAGE(PG8_SB(0, 0), b2, voffB); PG8_STAGE(PG8_SB(0, 1), b2 + hstep, voffB); PG8_STAGE(PG8_SA(0, 0), a2, voffA);
.LBB0_231:
	s_ashr_i32 s21, s20, 31
	s_lshl_b64 s[22:23], s[20:21], 19
	s_add_u32 s22, s44, s22
	s_addc_u32 s23, s45, s23
	s_and_b64 s[34:35], s[4:5], exec
	s_cselect_b32 s21, s23, s39
	s_cselect_b32 s64, s22, s38
	s_ashr_i32 s19, s18, 31
	s_lshl_b64 s[34:35], s[18:19], 19
	s_add_u32 s34, s46, s34
	s_addc_u32 s35, s47, s35
	s_and_b64 s[42:43], s[4:5], exec
	s_cselect_b32 s19, s35, s41
	s_cselect_b32 s65, s34, s40
	s_add_u32 s38, s38, 0x40080
	s_addc_u32 s39, s39, 0
	s_add_u32 s66, s40, 0x100
	s_addc_u32 s67, s41, 0
	s_mov_b32 s68, -2
	s_cmp_eq_u32 s99, 0
	s_cbranch_scc1 .Lnobar_0
	s_mov_b32 s99, 0
	s_barrier
.Lnobar_0:
	ds_read_b128 v[154:157], v149
	ds_read_b128 v[158:161], v149 offset:1024
	ds_read_b128 v[162:165], v149 offset:2048
	ds_read_b128 v[166:169], v149 offset:3072
	ds_read_b128 v[170:173], v150
	ds_read_b128 v[174:177], v150 offset:1024
	ds_read_b128 v[178:181], v150 offset:2048
	ds_read_b128 v[182:185], v150 offset:3072
	s_add_u32 s40, s38, 0xfffc0080
	s_addc_u32 s41, s39, -1
	s_cmp_eq_u32 s68, 12
	s_cselect_b32 s43, s21, s41
	s_cselect_b32 s42, s64, s40
	s_cselect_b32 s41, s19, s67
	s_cselect_b32 s40, s65, s66
	v_lshl_add_u64 v[144:145], s[38:39], 0, v[136:137]
	s_add_i32 m0, s37, 0xc000
	ds_read_b128 v[186:189], v151
	ds_read_b128 v[190:193], v151 offset:1024
	ds_read_b128 v[194:197], v151 offset:2048
	ds_read_b128 v[198:201], v151 offset:3072
	ds_read_b128 v[202:205], v151 offset:4096
	ds_read_b128 v[206:209], v151 offset:5120
	ds_read_b128 v[210:213], v151 offset:6144
	ds_read_b128 v[214:217], v151 offset:7168
	global_load_lds_dwordx4 v[144:145], off
	v_lshl_add_u64 v[144:145], s[38:39], 0, v[138:139]
	s_add_i32 m0, s37, 0xe000
	s_nop 0
	global_load_lds_dwordx4 v[144:145], off
	s_waitcnt vmcnt(8)
	s_waitcnt lgkmcnt(0)
	s_barrier
	s_setprio 1
	v_mfma_f32_16x16x32_bf16 v[120:123], v[154:157], v[186:189], 0
	v_mfma_f32_16x16x32_bf16 v[116:119], v[162:165], v[186:189], 0
	v_mfma_f32_16x16x32_bf16 v[108:111], v[154:157], v[194:197], 0
	v_mfma_f32_16x16x32_bf16 v[100:103], v[162:165], v[194:197], 0
	v_mfma_f32_16x16x32_bf16 v[92:95], v[154:157], v[202:205], 0
	v_mfma_f32_16x16x32_bf16 v[84:87], v[162:165], v[202:205], 0
	v_mfma_f32_16x16x32_bf16 v[76:79], v[154:157], v[210:213], 0
	v_mfma_f32_16x16x32_bf16 v[68:71], v[162:165], v[210:213], 0
	v_mfma_f32_16x16x32_bf16 v[120:123], v[158:161], v[190:193], v[120:123]
	v_mfma_f32_16x16x32_bf16 v[116:119], v[166:169], v[190:193], v[116:119]
	v_mfma_f32_16x16x32_bf16 v[108:111], v[158:161], v[198:201], v[108:111]
	v_mfma_f32_16x16x32_bf16 v[100:103], v[166:169], v[198:201], v[100:103]
	v_mfma_f32_16x16x32_bf16 v[92:95], v[158:161], v[206:209], v[92:95]
	v_mfma_f32_16x16x32_bf16 v[84:87], v[166:169], v[206:209], v[84:87]
	v_mfma_f32_16x16x32_bf16 v[76:79], v[158:161], v[214:217], v[76:79]
	v_mfma_f32_16x16x32_bf16 v[68:71], v[166:169], v[214:217], v[68:71]
	v_mfma_f32_16x16x32_bf16 v[124:127], v[170:173], v[186:189], 0
	v_mfma_f32_16x16x32_bf16 v[112:115], v[178:181], v[186:189], 0
	v_mfma_f32_16x16x32_bf16 v[104:107], v[170:173], v[194:197], 0
	v_mfma_f32_16x16x32_bf16 v[96:99], v[178:181], v[194:197], 0
	v_mfma_f32_16x16x32_bf16 v[88:91], v[170:173], v[202:205], 0
	v_mfma_f32_16x16x32_bf16 v[80:83], v[178:181], v[202:205], 0
	v_mfma_f32_16x16x32_bf16 v[72:75], v[170:173], v[210:213], 0
	v_mfma_f32_16x16x32_bf16 v[64:67], v[178:181], v[210:213], 0
	v_mfma_f32_16x16x32_bf16 v[124:127], v[174:177], v[190:193], v[124:127]
	v_mfma_f32_16x16x32_bf16 v[112:115], v[182:185], v[190:193], v[112:115]
	v_mfma_f32_16x16x32_bf16 v[104:107], v[174:177], v[198:201], v[104:107]
	v_mfma_f32_16x16x32_bf16 v[96:99], v[182:185], v[198:201], v[96:99]
	v_mfma_f32_16x16x32_bf16 v[88:91], v[174:177], v[206:209], v[88:91]
	v_mfma_f32_16x16x32_bf16 v[80:83], v[182:185], v[206:209], v[80:83]
	v_mfma_f32_16x16x32_bf16 v[72:75], v[174:177], v[214:217], v[72:75]
	v_mfma_f32_16x16x32_bf16 v[64:67], v[182:185], v[214:217], v[64:67]
	s_barrier
	s_setprio 0
	s_add_i32 s69, s57, s48
	v_lshl_add_u64 v[144:145], s[40:41], 0, v[132:133]
	s_mov_b32 m0, s69
	ds_read_b128 v[186:189], v151 offset:16384
	ds_read_b128 v[190:193], v151 offset:17408
	ds_read_b128 v[194:197], v151 offset:18432
	ds_read_b128 v[198:201], v151 offset:19456
	ds_read_b128 v[202:205], v151 offset:20480
	ds_read_b128 v[206:209], v151 offset:21504
	ds_read_b128 v[210:213], v151 offset:22528
	ds_read_b128 v[214:217], v151 offset:23552
	global_load_lds_dwordx4 v[144:145], off
	s_add_i32 m0, s69, 0x2000
	s_add_u32 s70, s40, 0x40000
	v_lshl_add_u64 v[218:219], s[40:41], 0, v[128:129]
	s_addc_u32 s71, s41, 0
	s_add_i32 s69, s58, s48
	global_load_lds_dwordx4 v[218:219], off
	v_lshl_add_u64 v[220:221], s[70:71], 0, v[132:133]
	s_mov_b32 m0, s69
	v_lshl_add_u64 v[222:223], s[42:43], 0, v[130:131]
	global_load_lds_dwordx4 v[220:221], off
	v_lshl_add_u64 v[220:221], s[70:71], 0, v[128:129]
	s_add_i32 m0, s69, 0x2000
	s_nop 0
	global_load_lds_dwordx4 v[220:221], off
	v_lshl_add_u64 v[220:221], s[42:43], 0, v[134:135]
	s_mov_b32 m0, s37
	s_nop 0
	global_load_lds_dwordx4 v[220:221], off
	s_mov_b32 m0, s50
	s_nop 0
	global_load_lds_dwordx4 v[222:223], off
	s_waitcnt vmcnt(8)
	s_waitcnt lgkmcnt(0)
	s_barrier
; #define PG8_STAGE(bufoff, gbase, voff) do { _Pragma("unroll") for (int _i = 0; _i < 2; ++_i) \
;         __builtin_amdgcn_global_load_lds((const unsigned*)((const char*)(gbase) + (voff)[_i]), (PG8_LAS unsigned*)(lds + (bufoff) + ldsw + _i * 8192), 16, 0, 0); } while (0)
; #define PG8_LDA(dst, b, h) do { _Pragma("unroll") for (int m = 0; m < 4; ++m) _Pragma("unroll") for (int k = 0; k < 2; ++k) dst[m][k] = *(const PG8_LAS bf16x8*)(lds + PG8_SA(b, h) + aoff + m * 2048 + k * 1024); } while (0)
; #define PG8_LDB(dst, b, h) do { _Pragma("unroll") for (int n = 0; n < 2; ++n) _Pragma("unroll") for (int k = 0; k < 2; ++k) dst[n][k] = *(const PG8_LAS bf16x8*)(lds + PG8_SB(b, h) + boff + n * 2048 + k * 1024); } while (0)
; #define PG8_MMA(ai, bj, At, Bt) do { __builtin_amdgcn_s_setprio(1); _Pragma("unroll") for (int m = 0; m < 4; ++m) _Pragma("unroll") for (int n = 0; n < 2; ++n) _Pragma("unroll") for (int k = 0; k < 2; ++k) \
;         acc[ai][bj][m][n] = __builtin_amdgcn_mfma_f32_16x16x32_bf16(Bt[n][k], At[m][k], acc[ai][bj][m][n], 0, 0, 0); __builtin_amdgcn_s_setprio(0); } while (0)
; #define PG8_WAIT_V(n) asm volatile("s_waitcnt vmcnt(" #n ")" ::: "memory")
; #define PG8_WAIT_L(n) asm volatile("s_waitcnt lgkmcnt(" #n ")" ::: "memory")
; #define PG8_BAR __builtin_amdgcn_s_barrier()
; #define PG8_SCHED __builtin_amdgcn_sched_barrier(0)
; template <class Epi, class Sched, bool ALIGN_EPI = false, bool SP2 = false>
; __device__ __forceinline__ void gemm_phase(PG8_LAS unsigned char* lds, const Gemm g, const Sched& S, const Epi& E) {
;     ...
;             PG8_WAIT_V(8); PG8_WAIT_L(0); PG8_BAR; PG8_MMA(1, 0, At, B0); PG8_MMA(1, 1, At, B1); PG8_BAR; PG8_SCHED;
;             PG8_LDB(B0, 1, 0); PG8_LDB(B1, 1, 1); PG8_SCHED; PG8_LDA(At, 1, 0); PG8_STAGE(PG8_SA(0, 1), a2 + hstep, voffA);
;             PG8_WAIT_V(8); PG8_WAIT_L(0); PG8_BAR; PG8_MMA(0, 0, At, B0); PG8_MMA(0, 1, At, B1); PG8_BAR; PG8_SCHED;
	s_setprio 1
	v_mfma_f32_16x16x32_bf16 v[60:63], v[154:157], v[186:189], 0
	v_mfma_f32_16x16x32_bf16 v[52:55], v[162:165], v[186:189], 0
	v_mfma_f32_16x16x32_bf16 v[44:47], v[154:157], v[194:197], 0
	v_mfma_f32_16x16x32_bf16 v[36:39], v[162:165], v[194:197], 0
	v_mfma_f32_16x16x32_bf16 v[28:31], v[154:157], v[202:205], 0
	v_mfma_f32_16x16x32_bf16 v[20:23], v[162:165], v[202:205], 0
	v_mfma_f32_16x16x32_bf16 v[12:15], v[154:157], v[210:213], 0
	v_mfma_f32_16x16x32_bf16 v[4:7], v[162:165], v[210:213], 0
	v_mfma_f32_16x16x32_bf16 v[60:63], v[158:161], v[190:193], v[60:63]
	v_mfma_f32_16x16x32_bf16 v[52:55], v[166:169], v[190:193], v[52:55]
	v_mfma_f32_16x16x32_bf16 v[44:47], v[158:161], v[198:201], v[44:47]
	v_mfma_f32_16x16x32_bf16 v[36:39], v[166:169], v[198:201], v[36:39]
	v_mfma_f32_16x16x32_bf16 v[28:31], v[158:161], v[206:209], v[28:31]
	v_mfma_f32_16x16x32_bf16 v[20:23], v[166:169], v[206:209], v[20:23]
	v_mfma_f32_16x16x32_bf16 v[12:15], v[158:161], v[214:217], v[12:15]
	v_mfma_f32_16x16x32_bf16 v[4:7], v[166:169], v[214:217], v[4:7]
	v_mfma_f32_16x16x32_bf16 v[56:59], v[170:173], v[186:189], 0
	v_mfma_f32_16x16x32_bf16 v[48:51], v[178:181], v[186:189], 0
	v_mfma_f32_16x16x32_bf16 v[40:43], v[170:173], v[194:197], 0
	v_mfma_f32_16x16x32_bf16 v[32:35], v[178:181], v[194:197], 0
	v_mfma_f32_16x16x32_bf16 v[24:27], v[170:173], v[202:205], 0
	v_mfma_f32_16x16x32_bf16 v[16:19], v[178:181], v[202:205], 0
	v_mfma_f32_16x16x32_bf16 v[8:11], v[170:173], v[210:213], 0
	v_mfma_f32_16x16x32_bf16 v[0:3], v[178:181], v[210:213], 0
	v_mfma_f32_16x16x32_bf16 v[56:59], v[174:177], v[190:193], v[56:59]
	v_mfma_f32_16x16x32_bf16 v[48:51], v[182:185], v[190:193], v[48:51]
	v_mfma_f32_16x16x32_bf16 v[40:43], v[174:177], v[198:201], v[40:43]
	v_mfma_f32_16x16x32_bf16 v[32:35], v[182:185], v[198:201], v[32:35]
	v_mfma_f32_16x16x32_bf16 v[24:27], v[174:177], v[206:209], v[24:27]
	v_mfma_f32_16x16x32_bf16 v[16:19], v[182:185], v[206:209], v[16:19]
	v_mfma_f32_16x16x32_bf16 v[8:11], v[174:177], v[214:217], v[8:11]
	v_mfma_f32_16x16x32_bf16 v[0:3], v[182:185], v[214:217], v[0:3]
	s_barrier
	s_setprio 0
	s_add_i32 s69, 0, 0x18000
	v_add_u32_e32 v153, s69, v147
	s_add_i32 s70, 0, 0x1c000
	ds_read_b128 v[154:157], v153
	ds_read_b128 v[158:161], v153 offset:1024
	ds_read_b128 v[162:165], v153 offset:2048
	ds_read_b128 v[166:169], v153 offset:3072
	v_add_u32_e32 v153, s70, v147
	ds_read_b128 v[170:173], v153
	ds_read_b128 v[174:177], v153 offset:1024
	ds_read_b128 v[178:181], v153 offset:2048
	ds_read_b128 v[182:185], v153 offset:3072
	s_add_u32 s42, s42, 0x40000
	s_addc_u32 s43, s43, 0
	s_mov_b32 m0, s51
	v_lshl_add_u64 v[224:225], s[42:43], 0, v[134:135]
	ds_read_b128 v[186:189], v151 offset:32768
	ds_read_b128 v[190:193], v151 offset:33792
	ds_read_b128 v[194:197], v151 offset:34816
	ds_read_b128 v[198:201], v151 offset:35840
	ds_read_b128 v[202:205], v151 offset:36864
	ds_read_b128 v[206:209], v151 offset:37888
	ds_read_b128 v[210:213], v151 offset:38912
	ds_read_b128 v[214:217], v151 offset:39936
	global_load_lds_dwordx4 v[224:225], off
	v_lshl_add_u64 v[224:225], s[42:43], 0, v[130:131]
	s_mov_b32 m0, s52
	s_nop 0
	global_load_lds_dwordx4 v[224:225], off
	s_waitcnt vmcnt(8)
	s_waitcnt lgkmcnt(0)
	s_barrier
	s_setprio 1
	v_mfma_f32_16x16x32_bf16 v[120:123], v[154:157], v[186:189], v[120:123]
	v_mfma_f32_16x16x32_bf16 v[116:119], v[162:165], v[186:189], v[116:119]
	v_mfma_f32_16x16x32_bf16 v[108:111], v[154:157], v[194:197], v[108:111]
	v_mfma_f32_16x16x32_bf16 v[100:103], v[162:165], v[194:197], v[100:103]
	v_mfma_f32_16x16x32_bf16 v[92:95], v[154:157], v[202:205], v[92:95]
	v_mfma_f32_16x16x32_bf16 v[84:87], v[162:165], v[202:205], v[84:87]
	v_mfma_f32_16x16x32_bf16 v[76:79], v[154:157], v[210:213], v[76:79]
	v_mfma_f32_16x16x32_bf16 v[68:71], v[162:165], v[210:213], v[68:71]
	v_mfma_f32_16x16x32_bf16 v[120:123], v[158:161], v[190:193], v[120:123]
	v_mfma_f32_16x16x32_bf16 v[116:119], v[166:169], v[190:193], v[116:119]
	v_mfma_f32_16x16x32_bf16 v[108:111], v[158:161], v[198:201], v[108:111]
	v_mfma_f32_16x16x32_bf16 v[100:103], v[166:169], v[198:201], v[100:103]
	v_mfma_f32_16x16x32_bf16 v[92:95], v[158:161], v[206:209], v[92:95]
	v_mfma_f32_16x16x32_bf16 v[84:87], v[166:169], v[206:209], v[84:87]
	v_mfma_f32_16x16x32_bf16 v[76:79], v[158:161], v[214:217], v[76:79]
	v_mfma_f32_16x16x32_bf16 v[68:71], v[166:169], v[214:217], v[68:71]
	v_mfma_f32_16x16x32_bf16 v[124:127], v[170:173], v[186:189], v[124:127]
	v_mfma_f32_16x16x32_bf16 v[112:115], v[178:181], v[186:189], v[112:115]
	v_mfma_f32_16x16x32_bf16 v[104:107], v[170:173], v[194:197], v[104:107]
	v_mfma_f32_16x16x32_bf16 v[96:99], v[178:181], v[194:197], v[96:99]
	v_mfma_f32_16x16x32_bf16 v[88:91], v[170:173], v[202:205], v[88:91]
	v_mfma_f32_16x16x32_bf16 v[80:83], v[178:181], v[202:205], v[80:83]
	v_mfma_f32_16x16x32_bf16 v[72:75], v[170:173], v[210:213], v[72:75]
	v_mfma_f32_16x16x32_bf16 v[64:67], v[178:181], v[210:213], v[64:67]
	v_mfma_f32_16x16x32_bf16 v[124:127], v[174:177], v[190:193], v[124:127]
	v_mfma_f32_16x16x32_bf16 v[112:115], v[182:185], v[190:193], v[112:115]
	v_mfma_f32_16x16x32_bf16 v[104:107], v[174:177], v[198:201], v[104:107]
	v_mfma_f32_16x16x32_bf16 v[96:99], v[182:185], v[198:201], v[96:99]
	v_mfma_f32_16x16x32_bf16 v[88:91], v[174:177], v[206:209], v[88:91]
	v_mfma_f32_16x16x32_bf16 v[80:83], v[182:185], v[206:209], v[80:83]
	v_mfma_f32_16x16x32_bf16 v[72:75], v[174:177], v[214:217], v[72:75]
	v_mfma_f32_16x16x32_bf16 v[64:67], v[182:185], v[214:217], v[64:67]
	s_barrier
; #define PG8_STAGE(bufoff, gbase, voff) do { _Pragma("unroll") for (int _i = 0; _i < 2; ++_i) \
;         __builtin_amdgcn_global_load_lds((const unsigned*)((const char*)(gbase) + (voff)[_i]), (PG8_LAS unsigned*)(lds + (bufoff) + ldsw + _i * 8192), 16, 0, 0); } while (0)
; #define PG8_LDA(dst, b, h) do { _Pragma("unroll") for (int m = 0; m < 4; ++m) _Pragma("unroll") for (int k = 0; k < 2; ++k) dst[m][k] = *(const PG8_LAS bf16x8*)(lds + PG8_SA(b, h) + aoff + m * 2048 + k * 1024); } while (0)
; #define PG8_MMA(ai, bj, At, Bt) do { __builtin_amdgcn_s_setprio(1); _Pragma("unroll") for (int m = 0; m < 4; ++m) _Pragma("unroll") for (int n = 0; n < 2; ++n) _Pragma("unroll") for (int k = 0; k < 2; ++k) \
;         acc[ai][bj][m][n] = __builtin_amdgcn_mfma_f32_16x16x32_bf16(Bt[n][k], At[m][k], acc[ai][bj][m][n], 0, 0, 0); __builtin_amdgcn_s_setprio(0); } while (0)
; #define PG8_WAIT_V(n) asm volatile("s_waitcnt vmcnt(" #n ")" ::: "memory")
; #define PG8_WAIT_L(n) asm volatile("s_waitcnt lgkmcnt(" #n ")" ::: "memory")
; #define PG8_BAR __builtin_amdgcn_s_barrier()
; #define PG8_SCHED __builtin_amdgcn_sched_barrier(0)
; template <class Epi, class Sched, bool ALIGN_EPI = false, bool SP2 = false>
; __device__ __forceinline__ void gemm_phase(PG8_LAS unsigned char* lds, const Gemm g, const Sched& S, const Epi& E) {
;     ...
;         for (int t = 0; t < nt; t += 2) {
;     ...
;             PG8_LDA(At, 1, 1); PG8_STAGE(PG8_SB(1, 0), b3, voffB); PG8_STAGE(PG8_SB(1, 1), b3 + hstep, voffB); PG8_STAGE(PG8_SA(1, 0), a3, voffA);
;             PG8_WAIT_V(8); PG8_WAIT_L(0); PG8_BAR; PG8_MMA(1, 0, At, B0); PG8_MMA(1, 1, At, B1); PG8_BAR; PG8_SCHED;
	s_setprio 0
	s_add_i32 s42, s69, s48
	v_lshl_add_u64 v[144:145], v[144:145], 0, s[14:15]
	s_mov_b32 m0, s42
	ds_read_b128 v[186:189], v151 offset:49152
	ds_read_b128 v[190:193], v151 offset:50176
	ds_read_b128 v[194:197], v151 offset:51200
	ds_read_b128 v[198:201], v151 offset:52224
	ds_read_b128 v[202:205], v151 offset:53248
	ds_read_b128 v[206:209], v151 offset:54272
	ds_read_b128 v[210:213], v151 offset:55296
	ds_read_b128 v[214:217], v151 offset:56320
	global_load_lds_dwordx4 v[144:145], off
	s_add_i32 m0, s42, 0x2000
	s_add_u32 s40, s40, 0x40080
	v_lshl_add_u64 v[144:145], v[218:219], 0, s[14:15]
	s_addc_u32 s41, s41, 0
	s_add_i32 s42, s70, s48
	global_load_lds_dwordx4 v[144:145], off
	v_lshl_add_u64 v[144:145], s[40:41], 0, v[132:133]
	s_mov_b32 m0, s42
	s_nop 0
	global_load_lds_dwordx4 v[144:145], off
	v_lshl_add_u64 v[144:145], s[40:41], 0, v[128:129]
	s_add_i32 m0, s42, 0x2000
	s_nop 0
	global_load_lds_dwordx4 v[144:145], off
	v_lshl_add_u64 v[144:145], v[220:221], 0, s[14:15]
	s_mov_b32 m0, s54
	s_nop 0
	global_load_lds_dwordx4 v[144:145], off
	v_lshl_add_u64 v[144:145], v[222:223], 0, s[14:15]
	s_mov_b32 m0, s55
	s_nop 0
	global_load_lds_dwordx4 v[144:145], off
	s_waitcnt vmcnt(8)
	s_waitcnt lgkmcnt(0)
	s_barrier
	s_setprio 1
	v_mfma_f32_16x16x32_bf16 v[60:63], v[154:157], v[186:189], v[60:63]
	v_mfma_f32_16x16x32_bf16 v[52:55], v[162:165], v[186:189], v[52:55]
	v_mfma_f32_16x16x32_bf16 v[44:47], v[154:157], v[194:197], v[44:47]
	v_mfma_f32_16x16x32_bf16 v[36:39], v[162:165], v[194:197], v[36:39]
	v_mfma_f32_16x16x32_bf16 v[28:31], v[154:157], v[202:205], v[28:31]
	v_mfma_f32_16x16x32_bf16 v[20:23], v[162:165], v[202:205], v[20:23]
	v_mfma_f32_16x16x32_bf16 v[12:15], v[154:157], v[210:213], v[12:15]
	v_mfma_f32_16x16x32_bf16 v[4:7], v[162:165], v[210:213], v[4:7]
	v_mfma_f32_16x16x32_bf16 v[60:63], v[158:161], v[190:193], v[60:63]
	v_mfma_f32_16x16x32_bf16 v[52:55], v[166:169], v[190:193], v[52:55]
	v_mfma_f32_16x16x32_bf16 v[44:47], v[158:161], v[198:201], v[44:47]
	v_mfma_f32_16x16x32_bf16 v[36:39], v[166:169], v[198:201], v[36:39]
	v_mfma_f32_16x16x32_bf16 v[28:31], v[158:161], v[206:209], v[28:31]
	v_mfma_f32_16x16x32_bf16 v[20:23], v[166:169], v[206:209], v[20:23]
	v_mfma_f32_16x16x32_bf16 v[12:15], v[158:161], v[214:217], v[12:15]
	v_mfma_f32_16x16x32_bf16 v[4:7], v[166:169], v[214:217], v[4:7]
	v_mfma_f32_16x16x32_bf16 v[56:59], v[170:173], v[186:189], v[56:59]
	v_mfma_f32_16x16x32_bf16 v[48:51], v[178:181], v[186:189], v[48:51]
	v_mfma_f32_16x16x32_bf16 v[40:43], v[170:173], v[194:197], v[40:43]
	v_mfma_f32_16x16x32_bf16 v[32:35], v[178:181], v[194:197], v[32:35]
	v_mfma_f32_16x16x32_bf16 v[24:27], v[170:173], v[202:205], v[24:27]
	v_mfma_f32_16x16x32_bf16 v[16:19], v[178:181], v[202:205], v[16:19]
	v_mfma_f32_16x16x32_bf16 v[8:11], v[170:173], v[210:213], v[8:11]
	v_mfma_f32_16x16x32_bf16 v[0:3], v[178:181], v[210:213], v[0:3]
	v_mfma_f32_16x16x32_bf16 v[56:59], v[174:177], v[190:193], v[56:59]
	v_mfma_f32_16x16x32_bf16 v[48:51], v[182:185], v[190:193], v[48:51]
	v_mfma_f32_16x16x32_bf16 v[40:43], v[174:177], v[198:201], v[40:43]
	v_mfma_f32_16x16x32_bf16 v[32:35], v[182:185], v[198:201], v[32:35]
	v_mfma_f32_16x16x32_bf16 v[24:27], v[174:177], v[206:209], v[24:27]
	v_mfma_f32_16x16x32_bf16 v[16:19], v[182:185], v[206:209], v[16:19]
	v_mfma_f32_16x16x32_bf16 v[8:11], v[174:177], v[214:217], v[8:11]
	v_mfma_f32_16x16x32_bf16 v[0:3], v[182:185], v[214:217], v[0:3]
	s_barrier
	s_setprio 0
	s_add_i32 s68, s68, 2
	s_add_u32 s38, s38, 0x100
	s_addc_u32 s39, s39, 0
	s_add_u32 s66, s66, 0x100
	s_addc_u32 s67, s67, 0

; __device__ __forceinline__ float ld_agent(const rss_t* p) { return (float)__hip_atomic_load(p, __ATOMIC_RELAXED, __HIP_MEMORY_SCOPE_AGENT) * (1.0f / 16777216.0f); }
; __device__ __forceinline__ rss_t rss_fix(float ss) { return (rss_t)(ss * 16777216.0f); }
; __device__ __forceinline__ float rstd_of(const rss_t* rowss, int row) { return __builtin_amdgcn_rsqf(ld_agent(rowss + row) * (1.0f / 1024.0f) + 1e-6f); }
; __device__ __forceinline__ unsigned silu_pk(f32x2 g, f32x2 u, float k1, float k2) {
;     const f32x2 t = g * k1; f32x2 ex; ex.x = __builtin_amdgcn_exp2f(t.x); ex.y = __builtin_amdgcn_exp2f(t.y);
;     const f32x2 d = ex + 1.0f; f32x2 r; r.x = __builtin_amdgcn_rcpf(d.x); r.y = __builtin_amdgcn_rcpf(d.y);
;     const f32x2 o = (g * u) * (r * k2);
;     return cvt_pk_bf16(o.x, o.y);
; }
; __device__ __forceinline__ float silu_mul(float g, float u) { return g * __builtin_amdgcn_rcpf(1.0f + __builtin_amdgcn_exp2f(-1.4426950408889634f * g)) * u; }
;     __device__ __forceinline__ void operator()(const f32x4 (&acc)[2][2][4][2], const Unit& u, int wr, int wc, int fr, int fq) const {
;         const int row0 = u.pm * BM + wr * 64 + fr, col0 = u.pn * HALF + wc * 32 + 8 * fq;
;         float ssq[2][4];
; #pragma unroll
;         for (int ai = 0; ai < 2; ++ai)
; #pragma unroll
;             for (int m = 0; m < 4; ++m) ssq[ai][m] = ld_agent(rowss + row0 + ai * HALF + m * 16);
; #pragma unroll
;         for (int ai = 0; ai < 2; ++ai)
; #pragma unroll
;             for (int m = 0; m < 4; ++m) {
;                 const int row = row0 + ai * HALF + m * 16; const float rs = __builtin_amdgcn_rsqf(ssq[ai][m] * (1.0f / 1024.0f) + 1e-6f);
;                 const float k1 = -1.4426950408889634f * rs, k2 = rs * rs;
;                 u32x4 w;
; #pragma unroll
;                 for (int n = 0; n < 2; ++n) {
;                     const f32x4 gv = acc[ai][0][m][n], uv = acc[ai][1][m][n];
;                     const unsigned lo = silu_pk((f32x2){gv[0], gv[1]}, (f32x2){uv[0], uv[1]}, k1, k2), hi = silu_pk((f32x2){gv[2], gv[3]}, (f32x2){uv[2], uv[3]}, k1, k2);
;                     if (n == 0) { w.x = lo; w.y = hi; } else { w.z = lo; w.w = hi; }
;                 }
;                 *(u32x4*)(O + (size_t)row * ldc + col0) = w;
.LBB0_235:
	v_lshl_add_u32 v144, s36, 8, v146
	v_ashrrev_i32_e32 v145, 31, v144
	v_lshl_add_u64 v[154:155], v[144:145], 3, s[8:9]
	global_load_dwordx2 v[156:157], v[154:155], off sc1
	global_load_dwordx2 v[158:159], v[154:155], off offset:128 sc1
	global_load_dwordx2 v[160:161], v[154:155], off offset:256 sc1
	global_load_dwordx2 v[162:163], v[154:155], off offset:384 sc1
	global_load_dwordx2 v[164:165], v[154:155], off offset:1024 sc1
	global_load_dwordx2 v[166:167], v[154:155], off offset:1152 sc1
	global_load_dwordx2 v[168:169], v[154:155], off offset:1280 sc1
	s_nop 0
	global_load_dwordx2 v[154:155], v[154:155], off offset:1408 sc1
	v_pk_mul_f32 v[172:173], v[120:121], v[124:125]
	v_pk_mul_f32 v[126:127], v[122:123], v[126:127]
	v_pk_mul_f32 v[112:113], v[116:117], v[112:113]
	v_pk_mul_f32 v[114:115], v[118:119], v[114:115]
	v_lshl_or_b32 v170, s63, 7, v148
	v_ashrrev_i32_e32 v171, 31, v170
	v_pk_mul_f32 v[104:105], v[108:109], v[104:105]
	v_pk_mul_f32 v[106:107], v[110:111], v[106:107]
	v_pk_mul_f32 v[96:97], v[100:101], v[96:97]
	v_pk_mul_f32 v[98:99], v[102:103], v[98:99]
	v_pk_mul_f32 v[88:89], v[92:93], v[88:89]
	v_pk_mul_f32 v[90:91], v[94:95], v[90:91]
	v_pk_mul_f32 v[80:81], v[84:85], v[80:81]
	v_pk_mul_f32 v[82:83], v[86:87], v[82:83]
	v_pk_mul_f32 v[72:73], v[76:77], v[72:73]
	v_pk_mul_f32 v[74:75], v[78:79], v[74:75]
	v_pk_mul_f32 v[64:65], v[68:69], v[64:65]
	v_pk_mul_f32 v[66:67], v[70:71], v[66:67]
	v_pk_mul_f32 v[56:57], v[60:61], v[56:57]
	v_pk_mul_f32 v[58:59], v[62:63], v[58:59]
	v_pk_mul_f32 v[48:49], v[52:53], v[48:49]
	v_pk_mul_f32 v[50:51], v[54:55], v[50:51]
	v_pk_mul_f32 v[40:41], v[44:45], v[40:41]
	v_pk_mul_f32 v[42:43], v[46:47], v[42:43]
	v_pk_mul_f32 v[32:33], v[36:37], v[32:33]
	v_pk_mul_f32 v[34:35], v[38:39], v[34:35]
	v_pk_mul_f32 v[24:25], v[28:29], v[24:25]
	v_pk_mul_f32 v[26:27], v[30:31], v[26:27]
	v_pk_mul_f32 v[16:17], v[20:21], v[16:17]
	v_pk_mul_f32 v[18:19], v[22:23], v[18:19]
	v_pk_mul_f32 v[8:9], v[12:13], v[8:9]
	v_pk_mul_f32 v[10:11], v[14:15], v[10:11]
	v_pk_mul_f32 v[0:1], v[4:5], v[0:1]
	v_pk_mul_f32 v[2:3], v[6:7], v[2:3]
	s_andn2_b64 vcc, exec, s[4:5]
	s_mov_b64 s[4:5], -1
	s_waitcnt vmcnt(0)
	v_ffbh_u32_e32 v124, v157
	v_ffbh_u32_e32 v125, v159
	v_min_u32_e32 v178, 32, v124
	v_min_u32_e32 v179, 32, v125
	v_lshlrev_b64 v[124:125], v178, v[156:157]
	v_ffbh_u32_e32 v145, v161
	v_ffbh_u32_e32 v153, v163
	v_ffbh_u32_e32 v174, v165
	v_ffbh_u32_e32 v175, v167
	v_min_u32_e32 v124, 1, v124
	v_ffbh_u32_e32 v177, v155
	v_min_u32_e32 v145, 32, v145
	v_min_u32_e32 v153, 32, v153
	v_min_u32_e32 v174, 32, v174
	v_min_u32_e32 v175, 32, v175
	v_or_b32_e32 v124, v125, v124
	v_min_u32_e32 v177, 32, v177
	v_lshlrev_b64 v[156:157], v179, v[158:159]
	v_lshlrev_b64 v[158:159], v145, v[160:161]
	v_lshlrev_b64 v[160:161], v153, v[162:163]
	v_lshlrev_b64 v[162:163], v174, v[164:165]
	v_lshlrev_b64 v[164:165], v175, v[166:167]
	v_cvt_f32_u32_e32 v124, v124
	v_lshlrev_b64 v[154:155], v177, v[154:155]
	v_min_u32_e32 v156, 1, v156
	v_min_u32_e32 v158, 1, v158
	v_min_u32_e32 v160, 1, v160
	v_min_u32_e32 v162, 1, v162
	v_min_u32_e32 v164, 1, v164
	v_min_u32_e32 v154, 1, v154
	v_or_b32_e32 v125, v157, v156
	v_or_b32_e32 v156, v159, v158
	v_or_b32_e32 v157, v161, v160
	v_or_b32_e32 v158, v163, v162
	v_or_b32_e32 v159, v165, v164
	v_sub_u32_e32 v178, 32, v178
	v_or_b32_e32 v154, v155, v154
	v_cvt_f32_u32_e32 v155, v156
	v_cvt_f32_u32_e32 v156, v157
	v_cvt_f32_u32_e32 v157, v158
	v_cvt_f32_u32_e32 v158, v159
	v_ldexp_f32 v124, v124, v178
	v_mul_f32_e32 v124, 0x33800000, v124
	v_sub_u32_e32 v153, 32, v153
	v_sub_u32_e32 v175, 32, v175
	v_cvt_f32_u32_e32 v154, v154
	v_fmamk_f32 v124, v124, 0x3a800000, v152
	v_ffbh_u32_e32 v176, v169
	v_ldexp_f32 v153, v156, v153
	v_ldexp_f32 v156, v158, v175
	v_rsq_f32_e32 v158, v124
	v_min_u32_e32 v176, 32, v176
	v_sub_u32_e32 v145, 32, v145
	v_sub_u32_e32 v174, 32, v174
	v_lshlrev_b64 v[166:167], v176, v[168:169]
	v_sub_u32_e32 v169, 32, v177
	v_ldexp_f32 v145, v155, v145
	v_ldexp_f32 v155, v157, v174
	v_ldexp_f32 v154, v154, v169
	v_mul_f32_e32 v155, 0x33800000, v155
	v_mul_f32_e32 v124, 0x33800000, v154
	v_mul_f32_e32 v154, 0xbfb8aa3b, v158
	v_pk_mul_f32 v[122:123], v[122:123], v[154:155] op_sel_hi:[1,0]
	v_min_u32_e32 v166, 1, v166
	v_exp_f32_e32 v122, v122
	v_exp_f32_e32 v123, v123
	v_or_b32_e32 v160, v167, v166
	v_pk_mul_f32 v[120:121], v[120:121], v[154:155] op_sel_hi:[1,0]
	v_cvt_f32_u32_e32 v125, v125
	v_cvt_f32_u32_e32 v159, v160
	v_exp_f32_e32 v120, v120
	v_exp_f32_e32 v121, v121
	v_pk_add_f32 v[122:123], v[122:123], 1.0 op_sel_hi:[1,0]
	v_sub_u32_e32 v179, 32, v179
	v_rcp_f32_e32 v122, v122
	v_rcp_f32_e32 v123, v123
	v_sub_u32_e32 v168, 32, v176
	v_ldexp_f32 v125, v125, v179
	v_ldexp_f32 v157, v159, v168
	v_pk_add_f32 v[120:121], v[120:121], 1.0 op_sel_hi:[1,0]
	v_mul_f32_e32 v159, 0x33800000, v125
	v_mul_f32_e32 v160, 0x33800000, v156
	v_mul_f32_e32 v125, 0x33800000, v157
	v_pk_mul_f32 v[156:157], v[116:117], v[154:155] op_sel_hi:[1,0]
	v_rcp_f32_e32 v120, v120
	v_rcp_f32_e32 v121, v121
	v_mul_f32_e32 v158, v158, v158
	v_exp_f32_e32 v156, v156
	v_exp_f32_e32 v157, v157
	v_pk_mul_f32 v[122:123], v[158:159], v[122:123] op_sel_hi:[0,1]
	v_pk_mul_f32 v[122:123], v[126:127], v[122:123]
	v_pk_mul_f32 v[126:127], v[118:119], v[154:155] op_sel_hi:[1,0]
	v_pk_mul_f32 v[120:121], v[158:159], v[120:121] op_sel_hi:[0,1]
	v_exp_f32_e32 v126, v126
	v_exp_f32_e32 v127, v127
	v_pk_add_f32 v[156:157], v[156:157], 1.0 op_sel_hi:[1,0]
	v_pk_mul_f32 v[120:121], v[172:173], v[120:121]
	v_mul_f32_e32 v145, 0x33800000, v145
	v_cvt_pk_bf16_f32 v120, v120, v121
	v_cvt_pk_bf16_f32 v121, v122, v123
; __device__ __forceinline__ unsigned cvt_pk_bf16(float lo, float hi) { unsigned r; asm volatile("v_cvt_pk_bf16_f32 %0, %1, %2" : "=v"(r) : "v"(lo), "v"(hi)); return r; }
; __device__ __forceinline__ unsigned silu_pk(f32x2 g, f32x2 u, float k1, float k2) {
;     const f32x2 t = g * k1; f32x2 ex; ex.x = __builtin_amdgcn_exp2f(t.x); ex.y = __builtin_amdgcn_exp2f(t.y);
;     const f32x2 d = ex + 1.0f; f32x2 r; r.x = __builtin_amdgcn_rcpf(d.x); r.y = __builtin_amdgcn_rcpf(d.y);
;     const f32x2 o = (g * u) * (r * k2);
;     return cvt_pk_bf16(o.x, o.y);
;     __device__ __forceinline__ void operator()(const f32x4 (&acc)[2][2][4][2], const Unit& u, int wr, int wc, int fr, int fq) const {
;     ...
;             for (int m = 0; m < 4; ++m) {
;                 const int row = row0 + ai * HALF + m * 16; const float rs = __builtin_amdgcn_rsqf(ssq[ai][m] * (1.0f / 1024.0f) + 1e-6f);
;                 const float k1 = -1.4426950408889634f * rs, k2 = rs * rs;
;                 u32x4 w;
; #pragma unroll
;                 for (int n = 0; n < 2; ++n) {
;                     const f32x4 gv = acc[ai][0][m][n], uv = acc[ai][1][m][n];
;                     const unsigned lo = silu_pk((f32x2){gv[0], gv[1]}, (f32x2){uv[0], uv[1]}, k1, k2), hi = silu_pk((f32x2){gv[2], gv[3]}, (f32x2){uv[2], uv[3]}, k1, k2);
;                     if (n == 0) { w.x = lo; w.y = hi; } else { w.z = lo; w.w = hi; }
;                 }
;                 *(u32x4*)(O + (size_t)row * ldc + col0) = w;
	v_rcp_f32_e32 v122, v156
	v_rcp_f32_e32 v123, v157
	v_pk_add_f32 v[116:117], v[126:127], 1.0 op_sel_hi:[1,0]
	v_mul_f32_e32 v153, 0x33800000, v153
	v_rcp_f32_e32 v116, v116
	v_rcp_f32_e32 v117, v117
	v_pk_mul_f32 v[118:119], v[158:159], v[122:123] op_sel_hi:[0,1]
	v_pk_mul_f32 v[112:113], v[112:113], v[118:119]
	s_nop 0
	v_cvt_pk_bf16_f32 v122, v112, v113
	v_pk_mul_f32 v[112:113], v[158:159], v[116:117] op_sel_hi:[0,1]
	v_pk_mul_f32 v[112:113], v[114:115], v[112:113]
	v_fmamk_f32 v114, v159, 0x3a800000, v152
	v_rsq_f32_e32 v119, v114
	v_cvt_pk_bf16_f32 v123, v112, v113
	v_mov_b64_e32 v[112:113], s[12:13]
	v_mad_i64_i32 v[116:117], s[38:39], v144, s59, v[112:113]
	v_mul_f32_e32 v118, 0xbfb8aa3b, v119
	v_pk_mul_f32 v[126:127], v[108:109], v[118:119] op_sel_hi:[1,0]
	v_pk_mul_f32 v[108:109], v[110:111], v[118:119] op_sel_hi:[1,0]
	v_exp_f32_e32 v126, v126
	v_exp_f32_e32 v127, v127
	v_lshlrev_b64 v[114:115], 1, v[170:171]
	v_exp_f32_e32 v108, v108
	v_exp_f32_e32 v109, v109
	v_lshl_add_u64 v[116:117], v[116:117], 0, v[114:115]
	global_store_dwordx4 v[116:117], v[120:123], off
	v_mul_f32_e32 v116, v119, v119
	v_pk_add_f32 v[108:109], v[108:109], 1.0 op_sel_hi:[1,0]
	v_pk_add_f32 v[120:121], v[126:127], 1.0 op_sel_hi:[1,0]
	v_rcp_f32_e32 v108, v108
	v_rcp_f32_e32 v120, v120
	v_rcp_f32_e32 v121, v121
	v_rcp_f32_e32 v109, v109
	v_pk_mul_f32 v[110:111], v[116:117], v[120:121] op_sel_hi:[0,1]
	v_pk_mul_f32 v[104:105], v[104:105], v[110:111]
	v_pk_mul_f32 v[110:111], v[100:101], v[118:119] op_sel_hi:[1,0]
	v_pk_mul_f32 v[108:109], v[116:117], v[108:109] op_sel_hi:[0,1]
	v_exp_f32_e32 v110, v110
	v_exp_f32_e32 v111, v111
	v_pk_mul_f32 v[106:107], v[106:107], v[108:109]
	v_pk_mul_f32 v[108:109], v[102:103], v[118:119] op_sel_hi:[1,0]
	v_cvt_pk_bf16_f32 v104, v104, v105
	v_cvt_pk_bf16_f32 v105, v106, v107
	v_pk_add_f32 v[106:107], v[110:111], 1.0 op_sel_hi:[1,0]
	v_exp_f32_e32 v108, v108
	v_exp_f32_e32 v109, v109
	v_rcp_f32_e32 v106, v106
	v_rcp_f32_e32 v107, v107
	v_pk_add_f32 v[100:101], v[108:109], 1.0 op_sel_hi:[1,0]
	s_nop 0
	v_rcp_f32_e32 v100, v100
	v_rcp_f32_e32 v101, v101
	v_pk_mul_f32 v[102:103], v[116:117], v[106:107] op_sel_hi:[0,1]
	v_pk_mul_f32 v[96:97], v[96:97], v[102:103]
	s_nop 0
	v_cvt_pk_bf16_f32 v106, v96, v97
	v_pk_mul_f32 v[96:97], v[116:117], v[100:101] op_sel_hi:[0,1]
	v_pk_mul_f32 v[96:97], v[98:99], v[96:97]
	s_nop 0
	v_cvt_pk_bf16_f32 v107, v96, v97
	v_fmamk_f32 v96, v145, 0x3a800000, v152
	v_rsq_f32_e32 v99, v96
	v_or_b32_e32 v96, 16, v144
	v_mad_i64_i32 v[96:97], s[38:39], v96, s59, v[112:113]
	v_mul_f32_e32 v98, 0xbfb8aa3b, v99
	v_pk_mul_f32 v[100:101], v[92:93], v[98:99] op_sel_hi:[1,0]
	v_pk_mul_f32 v[92:93], v[94:95], v[98:99] op_sel_hi:[1,0]
	v_exp_f32_e32 v100, v100
	v_exp_f32_e32 v101, v101
	v_exp_f32_e32 v92, v92
	v_exp_f32_e32 v93, v93
	v_lshl_add_u64 v[96:97], v[96:97], 0, v[114:115]
	v_pk_add_f32 v[100:101], v[100:101], 1.0 op_sel_hi:[1,0]
	global_store_dwordx4 v[96:97], v[104:107], off
	v_rcp_f32_e32 v100, v100
	v_rcp_f32_e32 v101, v101
	v_pk_add_f32 v[92:93], v[92:93], 1.0 op_sel_hi:[1,0]
	v_mul_f32_e32 v96, v99, v99
	v_rcp_f32_e32 v92, v92
	v_rcp_f32_e32 v93, v93
	v_pk_mul_f32 v[94:95], v[96:97], v[100:101] op_sel_hi:[0,1]
	v_pk_mul_f32 v[88:89], v[88:89], v[94:95]
	v_pk_mul_f32 v[94:95], v[84:85], v[98:99] op_sel_hi:[1,0]
	v_pk_mul_f32 v[92:93], v[96:97], v[92:93] op_sel_hi:[0,1]
	v_exp_f32_e32 v94, v94
	v_exp_f32_e32 v95, v95
	v_pk_mul_f32 v[90:91], v[90:91], v[92:93]
	v_pk_mul_f32 v[92:93], v[86:87], v[98:99] op_sel_hi:[1,0]
	v_cvt_pk_bf16_f32 v88, v88, v89
	v_cvt_pk_bf16_f32 v89, v90, v91
	v_pk_add_f32 v[90:91], v[94:95], 1.0 op_sel_hi:[1,0]
	v_exp_f32_e32 v92, v92
	v_exp_f32_e32 v93, v93
	v_rcp_f32_e32 v90, v90
	v_rcp_f32_e32 v91, v91
	v_pk_add_f32 v[84:85], v[92:93], 1.0 op_sel_hi:[1,0]
	s_nop 0
	v_rcp_f32_e32 v84, v84
	v_rcp_f32_e32 v85, v85
	v_pk_mul_f32 v[86:87], v[96:97], v[90:91] op_sel_hi:[0,1]
	v_pk_mul_f32 v[80:81], v[80:81], v[86:87]
	s_nop 0
	v_cvt_pk_bf16_f32 v90, v80, v81
	v_pk_mul_f32 v[80:81], v[96:97], v[84:85] op_sel_hi:[0,1]
	v_pk_mul_f32 v[80:81], v[82:83], v[80:81]
	s_nop 0
	v_cvt_pk_bf16_f32 v91, v80, v81
	v_fmamk_f32 v80, v153, 0x3a800000, v152
	v_rsq_f32_e32 v83, v80
	v_or_b32_e32 v80, 32, v144
	v_mad_i64_i32 v[80:81], s[38:39], v80, s59, v[112:113]
	v_mul_f32_e32 v82, 0xbfb8aa3b, v83
	v_pk_mul_f32 v[84:85], v[76:77], v[82:83] op_sel_hi:[1,0]
	v_pk_mul_f32 v[76:77], v[78:79], v[82:83] op_sel_hi:[1,0]
	v_exp_f32_e32 v84, v84
	v_exp_f32_e32 v85, v85
	v_exp_f32_e32 v76, v76
	v_exp_f32_e32 v77, v77
	v_lshl_add_u64 v[80:81], v[80:81], 0, v[114:115]
	v_pk_add_f32 v[84:85], v[84:85], 1.0 op_sel_hi:[1,0]
	global_store_dwordx4 v[80:81], v[88:91], off
	v_rcp_f32_e32 v84, v84
	v_rcp_f32_e32 v85, v85
	v_pk_add_f32 v[76:77], v[76:77], 1.0 op_sel_hi:[1,0]
	v_mul_f32_e32 v80, v83, v83
	v_rcp_f32_e32 v76, v76
	v_rcp_f32_e32 v77, v77
	v_pk_mul_f32 v[78:79], v[80:81], v[84:85] op_sel_hi:[0,1]
	v_pk_mul_f32 v[72:73], v[72:73], v[78:79]
	v_pk_mul_f32 v[78:79], v[68:69], v[82:83] op_sel_hi:[1,0]
	v_pk_mul_f32 v[76:77], v[80:81], v[76:77] op_sel_hi:[0,1]
	v_exp_f32_e32 v78, v78
	v_exp_f32_e32 v79, v79
	v_pk_mul_f32 v[74:75], v[74:75], v[76:77]
	v_pk_mul_f32 v[76:77], v[70:71], v[82:83] op_sel_hi:[1,0]
	v_cvt_pk_bf16_f32 v72, v72, v73
	v_cvt_pk_bf16_f32 v73, v74, v75
	v_pk_add_f32 v[74:75], v[78:79], 1.0 op_sel_hi:[1,0]
	v_exp_f32_e32 v76, v76
	v_exp_f32_e32 v77, v77
	v_rcp_f32_e32 v74, v74
	v_rcp_f32_e32 v75, v75
	v_pk_add_f32 v[68:69], v[76:77], 1.0 op_sel_hi:[1,0]
	s_nop 0
	v_rcp_f32_e32 v68, v68
	v_rcp_f32_e32 v69, v69
	v_pk_mul_f32 v[70:71], v[80:81], v[74:75] op_sel_hi:[0,1]
; __device__ __forceinline__ unsigned cvt_pk_bf16(float lo, float hi) { unsigned r; asm volatile("v_cvt_pk_bf16_f32 %0, %1, %2" : "=v"(r) : "v"(lo), "v"(hi)); return r; }
; __device__ __forceinline__ unsigned silu_pk(f32x2 g, f32x2 u, float k1, float k2) {
;     const f32x2 t = g * k1; f32x2 ex; ex.x = __builtin_amdgcn_exp2f(t.x); ex.y = __builtin_amdgcn_exp2f(t.y);
;     const f32x2 d = ex + 1.0f; f32x2 r; r.x = __builtin_amdgcn_rcpf(d.x); r.y = __builtin_amdgcn_rcpf(d.y);
;     const f32x2 o = (g * u) * (r * k2);
;     return cvt_pk_bf16(o.x, o.y);
;     __device__ __forceinline__ void operator()(const f32x4 (&acc)[2][2][4][2], const Unit& u, int wr, int wc, int fr, int fq) const {
;     ...
;             for (int m = 0; m < 4; ++m) {
;                 const int row = row0 + ai * HALF + m * 16; const float rs = __builtin_amdgcn_rsqf(ssq[ai][m] * (1.0f / 1024.0f) + 1e-6f);
;                 const float k1 = -1.4426950408889634f * rs, k2 = rs * rs;
;                 u32x4 w;
; #pragma unroll
;                 for (int n = 0; n < 2; ++n) {
;                     const f32x4 gv = acc[ai][0][m][n], uv = acc[ai][1][m][n];
;                     const unsigned lo = silu_pk((f32x2){gv[0], gv[1]}, (f32x2){uv[0], uv[1]}, k1, k2), hi = silu_pk((f32x2){gv[2], gv[3]}, (f32x2){uv[2], uv[3]}, k1, k2);
;                     if (n == 0) { w.x = lo; w.y = hi; } else { w.z = lo; w.w = hi; }
;                 }
;                 *(u32x4*)(O + (size_t)row * ldc + col0) = w;
	v_pk_mul_f32 v[64:65], v[64:65], v[70:71]
	s_nop 0
	v_cvt_pk_bf16_f32 v74, v64, v65
	v_pk_mul_f32 v[64:65], v[80:81], v[68:69] op_sel_hi:[0,1]
	v_pk_mul_f32 v[64:65], v[66:67], v[64:65]
	s_nop 0
	v_cvt_pk_bf16_f32 v75, v64, v65
	v_fmamk_f32 v65, v155, 0x3a800000, v152
	v_rsq_f32_e32 v67, v65
	v_or_b32_e32 v64, 48, v144
	v_mad_i64_i32 v[64:65], s[38:39], v64, s59, v[112:113]
	v_mul_f32_e32 v66, 0xbfb8aa3b, v67
	v_pk_mul_f32 v[68:69], v[60:61], v[66:67] op_sel_hi:[1,0]
	v_pk_mul_f32 v[60:61], v[62:63], v[66:67] op_sel_hi:[1,0]
	v_exp_f32_e32 v68, v68
	v_exp_f32_e32 v69, v69
	v_exp_f32_e32 v60, v60
	v_exp_f32_e32 v61, v61
	v_lshl_add_u64 v[64:65], v[64:65], 0, v[114:115]
	v_pk_add_f32 v[68:69], v[68:69], 1.0 op_sel_hi:[1,0]
	global_store_dwordx4 v[64:65], v[72:75], off
	v_rcp_f32_e32 v68, v68
	v_rcp_f32_e32 v69, v69
	v_pk_add_f32 v[60:61], v[60:61], 1.0 op_sel_hi:[1,0]
	v_add_u32_e32 v65, 0x80, v144
	v_rcp_f32_e32 v60, v60
	v_rcp_f32_e32 v61, v61
	v_mul_f32_e32 v64, v67, v67
	v_pk_mul_f32 v[62:63], v[64:65], v[68:69] op_sel_hi:[0,1]
	v_pk_mul_f32 v[56:57], v[56:57], v[62:63]
	v_pk_mul_f32 v[62:63], v[52:53], v[66:67] op_sel_hi:[1,0]
	v_pk_mul_f32 v[60:61], v[64:65], v[60:61] op_sel_hi:[0,1]
	v_exp_f32_e32 v62, v62
	v_exp_f32_e32 v63, v63
	v_pk_mul_f32 v[58:59], v[58:59], v[60:61]
	v_pk_mul_f32 v[60:61], v[54:55], v[66:67] op_sel_hi:[1,0]
	v_cvt_pk_bf16_f32 v56, v56, v57
	v_cvt_pk_bf16_f32 v57, v58, v59
	v_pk_add_f32 v[58:59], v[62:63], 1.0 op_sel_hi:[1,0]
	v_exp_f32_e32 v60, v60
	v_exp_f32_e32 v61, v61
	v_rcp_f32_e32 v58, v58
	v_rcp_f32_e32 v59, v59
	v_pk_add_f32 v[52:53], v[60:61], 1.0 op_sel_hi:[1,0]
	s_nop 0
	v_rcp_f32_e32 v52, v52
	v_rcp_f32_e32 v53, v53
	v_pk_mul_f32 v[54:55], v[64:65], v[58:59] op_sel_hi:[0,1]
	v_pk_mul_f32 v[48:49], v[48:49], v[54:55]
	s_nop 0
	v_cvt_pk_bf16_f32 v58, v48, v49
	v_pk_mul_f32 v[48:49], v[64:65], v[52:53] op_sel_hi:[0,1]
	v_pk_mul_f32 v[48:49], v[50:51], v[48:49]
	v_fmamk_f32 v50, v160, 0x3a800000, v152
	v_rsq_f32_e32 v51, v50
	v_cvt_pk_bf16_f32 v59, v48, v49
	v_mad_i64_i32 v[48:49], s[38:39], v65, s59, v[112:113]
	v_mul_f32_e32 v50, 0xbfb8aa3b, v51
	v_pk_mul_f32 v[52:53], v[44:45], v[50:51] op_sel_hi:[1,0]
	v_pk_mul_f32 v[44:45], v[46:47], v[50:51] op_sel_hi:[1,0]
	v_exp_f32_e32 v52, v52
	v_exp_f32_e32 v53, v53
	v_exp_f32_e32 v44, v44
	v_exp_f32_e32 v45, v45
	v_lshl_add_u64 v[48:49], v[48:49], 0, v[114:115]
	v_pk_add_f32 v[52:53], v[52:53], 1.0 op_sel_hi:[1,0]
	global_store_dwordx4 v[48:49], v[56:59], off
	v_rcp_f32_e32 v52, v52
	v_rcp_f32_e32 v53, v53
	v_pk_add_f32 v[44:45], v[44:45], 1.0 op_sel_hi:[1,0]
	v_mul_f32_e32 v48, v51, v51
	v_rcp_f32_e32 v44, v44
	v_rcp_f32_e32 v45, v45
	v_pk_mul_f32 v[46:47], v[48:49], v[52:53] op_sel_hi:[0,1]
	v_pk_mul_f32 v[40:41], v[40:41], v[46:47]
	v_pk_mul_f32 v[46:47], v[36:37], v[50:51] op_sel_hi:[1,0]
	v_pk_mul_f32 v[44:45], v[48:49], v[44:45] op_sel_hi:[0,1]
	v_exp_f32_e32 v46, v46
	v_exp_f32_e32 v47, v47
	v_pk_mul_f32 v[42:43], v[42:43], v[44:45]
	v_pk_mul_f32 v[44:45], v[38:39], v[50:51] op_sel_hi:[1,0]
	v_cvt_pk_bf16_f32 v40, v40, v41
	v_cvt_pk_bf16_f32 v41, v42, v43
	v_pk_add_f32 v[42:43], v[46:47], 1.0 op_sel_hi:[1,0]
	v_exp_f32_e32 v44, v44
	v_exp_f32_e32 v45, v45
	v_rcp_f32_e32 v42, v42
	v_rcp_f32_e32 v43, v43
	v_pk_add_f32 v[36:37], v[44:45], 1.0 op_sel_hi:[1,0]
	s_nop 0
	v_rcp_f32_e32 v36, v36
	v_rcp_f32_e32 v37, v37
	v_pk_mul_f32 v[38:39], v[48:49], v[42:43] op_sel_hi:[0,1]
	v_pk_mul_f32 v[32:33], v[32:33], v[38:39]
	s_nop 0
	v_cvt_pk_bf16_f32 v42, v32, v33
	v_pk_mul_f32 v[32:33], v[48:49], v[36:37] op_sel_hi:[0,1]
	v_pk_mul_f32 v[32:33], v[34:35], v[32:33]
	s_nop 0
	v_cvt_pk_bf16_f32 v43, v32, v33
; __device__ __forceinline__ unsigned cvt_pk_bf16(float lo, float hi) { unsigned r; asm volatile("v_cvt_pk_bf16_f32 %0, %1, %2" : "=v"(r) : "v"(lo), "v"(hi)); return r; }
; #define PG8_BAR __builtin_amdgcn_s_barrier()
; __device__ __forceinline__ unsigned silu_pk(f32x2 g, f32x2 u, float k1, float k2) {
;     const f32x2 t = g * k1; f32x2 ex; ex.x = __builtin_amdgcn_exp2f(t.x); ex.y = __builtin_amdgcn_exp2f(t.y);
;     const f32x2 d = ex + 1.0f; f32x2 r; r.x = __builtin_amdgcn_rcpf(d.x); r.y = __builtin_amdgcn_rcpf(d.y);
;     const f32x2 o = (g * u) * (r * k2);
;     return cvt_pk_bf16(o.x, o.y);
;     __device__ __forceinline__ void operator()(const f32x4 (&acc)[2][2][4][2], const Unit& u, int wr, int wc, int fr, int fq) const {
;     ...
;             for (int m = 0; m < 4; ++m) {
;                 const int row = row0 + ai * HALF + m * 16; const float rs = __builtin_amdgcn_rsqf(ssq[ai][m] * (1.0f / 1024.0f) + 1e-6f);
;                 const float k1 = -1.4426950408889634f * rs, k2 = rs * rs;
;                 u32x4 w;
; #pragma unroll
;                 for (int n = 0; n < 2; ++n) {
;                     const f32x4 gv = acc[ai][0][m][n], uv = acc[ai][1][m][n];
;                     const unsigned lo = silu_pk((f32x2){gv[0], gv[1]}, (f32x2){uv[0], uv[1]}, k1, k2), hi = silu_pk((f32x2){gv[2], gv[3]}, (f32x2){uv[2], uv[3]}, k1, k2);
;                     if (n == 0) { w.x = lo; w.y = hi; } else { w.z = lo; w.w = hi; }
;                 }
;                 *(u32x4*)(O + (size_t)row * ldc + col0) = w;
; template <class Epi, class Sched, bool ALIGN_EPI = false, bool SP2 = false>
; __device__ __forceinline__ void gemm_phase(PG8_LAS unsigned char* lds, const Gemm g, const Sched& S, const Epi& E) {
;     ...
;         if constexpr (!Epi::AFTER_DRAIN) { E(acc, cur, wr, wc, fr, fq); S.done(cur); }
;         if (!has_next) break;
; #pragma unroll
;         for (int a = 0; a < 2; ++a)
; #pragma unroll
;             for (int b = 0; b < 2; ++b)
; #pragma unroll
;                 for (int m = 0; m < 4; ++m)
; #pragma unroll
;                     for (int n = 0; n < 2; ++n) acc[a][b][m][n] = (f32x4){0.f, 0.f, 0.f, 0.f};
;         cur = nxt; cA = nA; cB = nB; ++ui;
;         if constexpr (ALIGN_EPI) { if (wr == 1) PG8_BAR; }
	v_fmamk_f32 v32, v125, 0x3a800000, v152
	v_rsq_f32_e32 v35, v32
	v_add_u32_e32 v32, 0x90, v144
	v_mad_i64_i32 v[32:33], s[38:39], v32, s59, v[112:113]
	v_mul_f32_e32 v34, 0xbfb8aa3b, v35
	v_pk_mul_f32 v[36:37], v[28:29], v[34:35] op_sel_hi:[1,0]
	v_pk_mul_f32 v[28:29], v[30:31], v[34:35] op_sel_hi:[1,0]
	v_exp_f32_e32 v36, v36
	v_exp_f32_e32 v37, v37
	v_exp_f32_e32 v28, v28
	v_exp_f32_e32 v29, v29
	v_lshl_add_u64 v[32:33], v[32:33], 0, v[114:115]
	v_pk_add_f32 v[36:37], v[36:37], 1.0 op_sel_hi:[1,0]
	global_store_dwordx4 v[32:33], v[40:43], off
	v_rcp_f32_e32 v36, v36
	v_rcp_f32_e32 v37, v37
	v_pk_add_f32 v[28:29], v[28:29], 1.0 op_sel_hi:[1,0]
	v_mul_f32_e32 v32, v35, v35
	v_rcp_f32_e32 v28, v28
	v_rcp_f32_e32 v29, v29
	v_pk_mul_f32 v[30:31], v[32:33], v[36:37] op_sel_hi:[0,1]
	v_pk_mul_f32 v[24:25], v[24:25], v[30:31]
	v_pk_mul_f32 v[30:31], v[20:21], v[34:35] op_sel_hi:[1,0]
	v_pk_mul_f32 v[28:29], v[32:33], v[28:29] op_sel_hi:[0,1]
	v_exp_f32_e32 v30, v30
	v_exp_f32_e32 v31, v31
	v_pk_mul_f32 v[26:27], v[26:27], v[28:29]
	v_pk_mul_f32 v[28:29], v[22:23], v[34:35] op_sel_hi:[1,0]
	v_cvt_pk_bf16_f32 v24, v24, v25
	v_cvt_pk_bf16_f32 v25, v26, v27
	v_pk_add_f32 v[26:27], v[30:31], 1.0 op_sel_hi:[1,0]
	v_exp_f32_e32 v28, v28
	v_exp_f32_e32 v29, v29
	v_rcp_f32_e32 v26, v26
	v_rcp_f32_e32 v27, v27
	v_pk_add_f32 v[20:21], v[28:29], 1.0 op_sel_hi:[1,0]
	s_nop 0
	v_rcp_f32_e32 v20, v20
	v_rcp_f32_e32 v21, v21
	v_pk_mul_f32 v[22:23], v[32:33], v[26:27] op_sel_hi:[0,1]
	v_pk_mul_f32 v[16:17], v[16:17], v[22:23]
	s_nop 0
	v_cvt_pk_bf16_f32 v26, v16, v17
	v_pk_mul_f32 v[16:17], v[32:33], v[20:21] op_sel_hi:[0,1]
	v_pk_mul_f32 v[16:17], v[18:19], v[16:17]
	s_nop 0
	v_cvt_pk_bf16_f32 v27, v16, v17
	v_fmamk_f32 v16, v124, 0x3a800000, v152
	v_rsq_f32_e32 v19, v16
	v_add_u32_e32 v16, 0xa0, v144
	v_mad_i64_i32 v[16:17], s[38:39], v16, s59, v[112:113]
	v_mul_f32_e32 v18, 0xbfb8aa3b, v19
	v_pk_mul_f32 v[20:21], v[12:13], v[18:19] op_sel_hi:[1,0]
	v_pk_mul_f32 v[12:13], v[14:15], v[18:19] op_sel_hi:[1,0]
	v_exp_f32_e32 v20, v20
	v_exp_f32_e32 v21, v21
	v_exp_f32_e32 v12, v12
	v_exp_f32_e32 v13, v13
	v_lshl_add_u64 v[16:17], v[16:17], 0, v[114:115]
	v_pk_add_f32 v[20:21], v[20:21], 1.0 op_sel_hi:[1,0]
	global_store_dwordx4 v[16:17], v[24:27], off
	v_rcp_f32_e32 v20, v20
	v_rcp_f32_e32 v21, v21
	v_pk_add_f32 v[12:13], v[12:13], 1.0 op_sel_hi:[1,0]
	v_mul_f32_e32 v16, v19, v19
	v_rcp_f32_e32 v12, v12
	v_rcp_f32_e32 v13, v13
	v_pk_mul_f32 v[14:15], v[16:17], v[20:21] op_sel_hi:[0,1]
	v_pk_mul_f32 v[8:9], v[8:9], v[14:15]
	v_pk_mul_f32 v[14:15], v[4:5], v[18:19] op_sel_hi:[1,0]
	v_pk_mul_f32 v[12:13], v[16:17], v[12:13] op_sel_hi:[0,1]
	v_exp_f32_e32 v14, v14
	v_exp_f32_e32 v15, v15
	v_pk_mul_f32 v[10:11], v[10:11], v[12:13]
	v_pk_mul_f32 v[12:13], v[6:7], v[18:19] op_sel_hi:[1,0]
	v_cvt_pk_bf16_f32 v8, v8, v9
	v_cvt_pk_bf16_f32 v9, v10, v11
	v_pk_add_f32 v[10:11], v[14:15], 1.0 op_sel_hi:[1,0]
	v_exp_f32_e32 v12, v12
	v_exp_f32_e32 v13, v13
	v_rcp_f32_e32 v10, v10
	v_rcp_f32_e32 v11, v11
	v_pk_add_f32 v[4:5], v[12:13], 1.0 op_sel_hi:[1,0]
	s_nop 0
	v_rcp_f32_e32 v4, v4
	v_rcp_f32_e32 v5, v5
	v_pk_mul_f32 v[6:7], v[16:17], v[10:11] op_sel_hi:[0,1]
	v_pk_mul_f32 v[0:1], v[0:1], v[6:7]
	s_nop 0
	v_cvt_pk_bf16_f32 v10, v0, v1
	v_pk_mul_f32 v[0:1], v[16:17], v[4:5] op_sel_hi:[0,1]
	v_pk_mul_f32 v[0:1], v[2:3], v[0:1]
	s_nop 0
	v_cvt_pk_bf16_f32 v11, v0, v1
	v_add_u32_e32 v0, 0xb0, v144
	v_mad_i64_i32 v[0:1], s[38:39], v0, s59, v[112:113]
	v_lshl_add_u64 v[0:1], v[0:1], 0, v[114:115]
	global_store_dwordx4 v[0:1], v[8:11], off
	s_cbranch_vccnz .LBB0_228
	s_andn2_b64 vcc, exec, s[6:7]
	s_cbranch_vccnz .LBB0_227
	s_mov_b32 s99, 1
	s_branch .LBB0_227

; #define PG8_STAGE(bufoff, gbase, voff) do { _Pragma("unroll") for (int _i = 0; _i < 2; ++_i) \
;         __builtin_amdgcn_global_load_lds((const unsigned*)((const char*)(gbase) + (voff)[_i]), (PG8_LAS unsigned*)(lds + (bufoff) + ldsw + _i * 8192), 16, 0, 0); } while (0)
; #define PG8_LDA(dst, b, h) do { _Pragma("unroll") for (int m = 0; m < 4; ++m) _Pragma("unroll") for (int k = 0; k < 2; ++k) dst[m][k] = *(const PG8_LAS bf16x8*)(lds + PG8_SA(b, h) + aoff + m * 2048 + k * 1024); } while (0)
; #define PG8_LDB(dst, b, h) do { _Pragma("unroll") for (int n = 0; n < 2; ++n) _Pragma("unroll") for (int k = 0; k < 2; ++k) dst[n][k] = *(const PG8_LAS bf16x8*)(lds + PG8_SB(b, h) + boff + n * 2048 + k * 1024); } while (0)
; #define PG8_WAIT_V(n) asm volatile("s_waitcnt vmcnt(" #n ")" ::: "memory")
; #define PG8_WAIT_L(n) asm volatile("s_waitcnt lgkmcnt(" #n ")" ::: "memory")
; #define PG8_BAR __builtin_amdgcn_s_barrier()
; #define PG8_SCHED __builtin_amdgcn_sched_barrier(0)
; template <class Epi, class Sched, bool ALIGN_EPI = false, bool SP2 = false>
; __device__ __forceinline__ void gemm_phase(PG8_LAS unsigned char* lds, const Gemm g, const Sched& S, const Epi& E) {
;     ...
;         const bool has_next = S.next(ui + 1, nxt);
;         const char* nA = has_next ? (const char*)g.A + (size_t)nxt.pm * tstep : cA; const char* nB = has_next ? (const char*)g.Bt + (size_t)nxt.pn * tstep : cB;
;         for (int t = 0; t < nt; t += 2) {
;             const bool last = (t == nt - 2);
;             if constexpr (Epi::PREFETCH) { if (t == nt - 4) E.prefetch(cur, lds + STAGE_BYTES + 1024, tid); }
;             const char* a1 = cA + (size_t)(t + 1) * kstep;
;             const char* a2 = last ? nA : cA + (size_t)(t + 2) * kstep; const char* b2 = last ? nB : cB + (size_t)(t + 2) * kstep;
;             const char* a3 = a2 + kstep; const char* b3 = b2 + kstep;
;             if (last && has_next) S.a_ready(nxt);
;             if constexpr (SP2) {
;             PG8_LDB(B0, 0, 0); PG8_LDB(B1, 0, 1); PG8_SCHED; PG8_LDA(At, 0, 0); PG8_STAGE(PG8_SA(1, 1), a1 + hstep, voffA);
;             PG8_WAIT_V(8); PG8_WAIT_L(0); PG8_BAR; PG8_MMA(0, 0, At, B0); PG8_MMA(0, 1, At, B1); PG8_BAR; PG8_SCHED;
;             PG8_LDA(At, 0, 1); PG8_STAGE(PG8_SB(0, 0), b2, voffB); PG8_STAGE(PG8_SB(0, 1), b2 + hstep, voffB); PG8_STAGE(PG8_SA(0, 0), a2, voffA);
.LBB0_405:
	s_add_u32 s34, s34, 0xb0080
	s_addc_u32 s35, s35, 0
	s_add_u32 s59, s36, 0x100
	s_addc_u32 s63, s37, 0
	s_mov_b32 s64, -2
	s_cmp_eq_u32 s99, 0
	s_cbranch_scc1 .Lnobar_1
	s_mov_b32 s99, 0
	s_barrier
.Lnobar_1:
	ds_read_b128 v[112:115], v246
	ds_read_b128 v[116:119], v246 offset:1024
	ds_read_b128 v[120:123], v246 offset:2048
	ds_read_b128 v[124:127], v246 offset:3072
	ds_read_b128 v[136:139], v247
	ds_read_b128 v[140:143], v247 offset:1024
	ds_read_b128 v[152:155], v247 offset:2048
	ds_read_b128 v[156:159], v247 offset:3072
	s_add_u32 s36, s34, 0xfff50080
	s_addc_u32 s37, s35, -1
	s_cmp_eq_u32 s64, 40
	s_cselect_b32 s39, s9, s37
	s_cselect_b32 s38, s8, s36
	s_cselect_b32 s37, s23, s63
	s_cselect_b32 s36, s22, s59
	v_lshl_add_u64 v[206:207], s[34:35], 0, v[200:201]
	s_add_i32 m0, s45, 0xc000
	ds_read_b128 v[160:163], v248
	ds_read_b128 v[164:167], v248 offset:1024
	ds_read_b128 v[168:171], v248 offset:2048
	ds_read_b128 v[172:175], v248 offset:3072
	ds_read_b128 v[176:179], v248 offset:4096
	ds_read_b128 v[180:183], v248 offset:5120
	ds_read_b128 v[184:187], v248 offset:6144
	ds_read_b128 v[188:191], v248 offset:7168
	global_load_lds_dwordx4 v[206:207], off
	v_lshl_add_u64 v[206:207], s[34:35], 0, v[202:203]
	s_add_i32 m0, s45, 0xe000
	s_nop 0
	global_load_lds_dwordx4 v[206:207], off
	s_waitcnt vmcnt(8)
	s_waitcnt lgkmcnt(0)
	s_barrier
	s_setprio 1
	v_mfma_f32_16x16x32_bf16 v[148:151], v[112:115], v[160:163], 0
	v_mfma_f32_16x16x32_bf16 v[144:147], v[120:123], v[160:163], 0
	v_mfma_f32_16x16x32_bf16 v[108:111], v[112:115], v[168:171], 0
	v_mfma_f32_16x16x32_bf16 v[104:107], v[120:123], v[168:171], 0
	v_mfma_f32_16x16x32_bf16 v[92:95], v[112:115], v[176:179], 0
	v_mfma_f32_16x16x32_bf16 v[88:91], v[120:123], v[176:179], 0
	v_mfma_f32_16x16x32_bf16 v[76:79], v[112:115], v[184:187], 0
	v_mfma_f32_16x16x32_bf16 v[72:75], v[120:123], v[184:187], 0
	v_mfma_f32_16x16x32_bf16 v[148:151], v[116:119], v[164:167], v[148:151]
	v_mfma_f32_16x16x32_bf16 v[144:147], v[124:127], v[164:167], v[144:147]
	v_mfma_f32_16x16x32_bf16 v[108:111], v[116:119], v[172:175], v[108:111]
	v_mfma_f32_16x16x32_bf16 v[104:107], v[124:127], v[172:175], v[104:107]
	v_mfma_f32_16x16x32_bf16 v[92:95], v[116:119], v[180:183], v[92:95]
	v_mfma_f32_16x16x32_bf16 v[88:91], v[124:127], v[180:183], v[88:91]
	v_mfma_f32_16x16x32_bf16 v[76:79], v[116:119], v[188:191], v[76:79]
	v_mfma_f32_16x16x32_bf16 v[72:75], v[124:127], v[188:191], v[72:75]
	v_mfma_f32_16x16x32_bf16 v[132:135], v[136:139], v[160:163], 0
	v_mfma_f32_16x16x32_bf16 v[128:131], v[152:155], v[160:163], 0
	v_mfma_f32_16x16x32_bf16 v[100:103], v[136:139], v[168:171], 0
	v_mfma_f32_16x16x32_bf16 v[96:99], v[152:155], v[168:171], 0
	v_mfma_f32_16x16x32_bf16 v[84:87], v[136:139], v[176:179], 0
	v_mfma_f32_16x16x32_bf16 v[80:83], v[152:155], v[176:179], 0
	v_mfma_f32_16x16x32_bf16 v[68:71], v[136:139], v[184:187], 0
	v_mfma_f32_16x16x32_bf16 v[64:67], v[152:155], v[184:187], 0
	v_mfma_f32_16x16x32_bf16 v[132:135], v[140:143], v[164:167], v[132:135]
	v_mfma_f32_16x16x32_bf16 v[128:131], v[156:159], v[164:167], v[128:131]
	v_mfma_f32_16x16x32_bf16 v[100:103], v[140:143], v[172:175], v[100:103]
	v_mfma_f32_16x16x32_bf16 v[96:99], v[156:159], v[172:175], v[96:99]
	v_mfma_f32_16x16x32_bf16 v[84:87], v[140:143], v[180:183], v[84:87]
	v_mfma_f32_16x16x32_bf16 v[80:83], v[156:159], v[180:183], v[80:83]
	v_mfma_f32_16x16x32_bf16 v[68:71], v[140:143], v[188:191], v[68:71]
	v_mfma_f32_16x16x32_bf16 v[64:67], v[156:159], v[188:191], v[64:67]
	s_barrier
	s_setprio 0
	s_add_i32 s65, s53, s44
	v_lshl_add_u64 v[206:207], s[36:37], 0, v[194:195]
	s_mov_b32 m0, s65
	ds_read_b128 v[160:163], v248 offset:16384
	ds_read_b128 v[164:167], v248 offset:17408
	ds_read_b128 v[168:171], v248 offset:18432
	ds_read_b128 v[172:175], v248 offset:19456
	ds_read_b128 v[176:179], v248 offset:20480
	ds_read_b128 v[180:183], v248 offset:21504
	ds_read_b128 v[184:187], v248 offset:22528
	ds_read_b128 v[188:191], v248 offset:23552
	global_load_lds_dwordx4 v[206:207], off
	s_add_i32 m0, s65, 0x2000
	s_add_u32 s66, s36, 0xb0000
	v_lshl_add_u64 v[208:209], s[36:37], 0, v[198:199]
	s_addc_u32 s67, s37, 0
	s_add_i32 s65, s54, s44
	global_load_lds_dwordx4 v[208:209], off
	v_lshl_add_u64 v[210:211], s[66:67], 0, v[194:195]
	s_mov_b32 m0, s65
	v_lshl_add_u64 v[212:213], s[38:39], 0, v[196:197]
	global_load_lds_dwordx4 v[210:211], off
	v_lshl_add_u64 v[210:211], s[66:67], 0, v[198:199]
	s_add_i32 m0, s65, 0x2000
	s_nop 0
	global_load_lds_dwordx4 v[210:211], off
	v_lshl_add_u64 v[210:211], s[38:39], 0, v[192:193]
	s_mov_b32 m0, s45
	s_nop 0
	global_load_lds_dwordx4 v[210:211], off
	s_mov_b32 m0, s46
	s_nop 0
	global_load_lds_dwordx4 v[212:213], off
	s_waitcnt vmcnt(8)
	s_waitcnt lgkmcnt(0)
	s_barrier
; #define PG8_STAGE(bufoff, gbase, voff) do { _Pragma("unroll") for (int _i = 0; _i < 2; ++_i) \
;         __builtin_amdgcn_global_load_lds((const unsigned*)((const char*)(gbase) + (voff)[_i]), (PG8_LAS unsigned*)(lds + (bufoff) + ldsw + _i * 8192), 16, 0, 0); } while (0)
; #define PG8_LDA(dst, b, h) do { _Pragma("unroll") for (int m = 0; m < 4; ++m) _Pragma("unroll") for (int k = 0; k < 2; ++k) dst[m][k] = *(const PG8_LAS bf16x8*)(lds + PG8_SA(b, h) + aoff + m * 2048 + k * 1024); } while (0)
; #define PG8_LDB(dst, b, h) do { _Pragma("unroll") for (int n = 0; n < 2; ++n) _Pragma("unroll") for (int k = 0; k < 2; ++k) dst[n][k] = *(const PG8_LAS bf16x8*)(lds + PG8_SB(b, h) + boff + n * 2048 + k * 1024); } while (0)
; #define PG8_MMA(ai, bj, At, Bt) do { __builtin_amdgcn_s_setprio(1); _Pragma("unroll") for (int m = 0; m < 4; ++m) _Pragma("unroll") for (int n = 0; n < 2; ++n) _Pragma("unroll") for (int k = 0; k < 2; ++k) \
;         acc[ai][bj][m][n] = __builtin_amdgcn_mfma_f32_16x16x32_bf16(Bt[n][k], At[m][k], acc[ai][bj][m][n], 0, 0, 0); __builtin_amdgcn_s_setprio(0); } while (0)
; #define PG8_WAIT_V(n) asm volatile("s_waitcnt vmcnt(" #n ")" ::: "memory")
; #define PG8_WAIT_L(n) asm volatile("s_waitcnt lgkmcnt(" #n ")" ::: "memory")
; #define PG8_BAR __builtin_amdgcn_s_barrier()
; #define PG8_SCHED __builtin_amdgcn_sched_barrier(0)
; template <class Epi, class Sched, bool ALIGN_EPI = false, bool SP2 = false>
; __device__ __forceinline__ void gemm_phase(PG8_LAS unsigned char* lds, const Gemm g, const Sched& S, const Epi& E) {
;     ...
;             PG8_WAIT_V(8); PG8_WAIT_L(0); PG8_BAR; PG8_MMA(1, 0, At, B0); PG8_MMA(1, 1, At, B1); PG8_BAR; PG8_SCHED;
;             PG8_LDB(B0, 1, 0); PG8_LDB(B1, 1, 1); PG8_SCHED; PG8_LDA(At, 1, 0); PG8_STAGE(PG8_SA(0, 1), a2 + hstep, voffA);
;             PG8_WAIT_V(8); PG8_WAIT_L(0); PG8_BAR; PG8_MMA(0, 0, At, B0); PG8_MMA(0, 1, At, B1); PG8_BAR; PG8_SCHED;
	s_setprio 1
	v_mfma_f32_16x16x32_bf16 v[60:63], v[112:115], v[160:163], 0
	v_mfma_f32_16x16x32_bf16 v[56:59], v[120:123], v[160:163], 0
	v_mfma_f32_16x16x32_bf16 v[44:47], v[112:115], v[168:171], 0
	v_mfma_f32_16x16x32_bf16 v[40:43], v[120:123], v[168:171], 0
	v_mfma_f32_16x16x32_bf16 v[28:31], v[112:115], v[176:179], 0
	v_mfma_f32_16x16x32_bf16 v[24:27], v[120:123], v[176:179], 0
	v_mfma_f32_16x16x32_bf16 v[12:15], v[112:115], v[184:187], 0
	v_mfma_f32_16x16x32_bf16 v[8:11], v[120:123], v[184:187], 0
	v_mfma_f32_16x16x32_bf16 v[60:63], v[116:119], v[164:167], v[60:63]
	v_mfma_f32_16x16x32_bf16 v[56:59], v[124:127], v[164:167], v[56:59]
	v_mfma_f32_16x16x32_bf16 v[44:47], v[116:119], v[172:175], v[44:47]
	v_mfma_f32_16x16x32_bf16 v[40:43], v[124:127], v[172:175], v[40:43]
	v_mfma_f32_16x16x32_bf16 v[28:31], v[116:119], v[180:183], v[28:31]
	v_mfma_f32_16x16x32_bf16 v[24:27], v[124:127], v[180:183], v[24:27]
	v_mfma_f32_16x16x32_bf16 v[12:15], v[116:119], v[188:191], v[12:15]
	v_mfma_f32_16x16x32_bf16 v[8:11], v[124:127], v[188:191], v[8:11]
	v_mfma_f32_16x16x32_bf16 v[52:55], v[136:139], v[160:163], 0
	v_mfma_f32_16x16x32_bf16 v[48:51], v[152:155], v[160:163], 0
	v_mfma_f32_16x16x32_bf16 v[36:39], v[136:139], v[168:171], 0
	v_mfma_f32_16x16x32_bf16 v[32:35], v[152:155], v[168:171], 0
	v_mfma_f32_16x16x32_bf16 v[20:23], v[136:139], v[176:179], 0
	v_mfma_f32_16x16x32_bf16 v[16:19], v[152:155], v[176:179], 0
	v_mfma_f32_16x16x32_bf16 v[4:7], v[136:139], v[184:187], 0
	v_mfma_f32_16x16x32_bf16 v[0:3], v[152:155], v[184:187], 0
	v_mfma_f32_16x16x32_bf16 v[52:55], v[140:143], v[164:167], v[52:55]
	v_mfma_f32_16x16x32_bf16 v[48:51], v[156:159], v[164:167], v[48:51]
	v_mfma_f32_16x16x32_bf16 v[36:39], v[140:143], v[172:175], v[36:39]
	v_mfma_f32_16x16x32_bf16 v[32:35], v[156:159], v[172:175], v[32:35]
	v_mfma_f32_16x16x32_bf16 v[20:23], v[140:143], v[180:183], v[20:23]
	v_mfma_f32_16x16x32_bf16 v[16:19], v[156:159], v[180:183], v[16:19]
	v_mfma_f32_16x16x32_bf16 v[4:7], v[140:143], v[188:191], v[4:7]
	v_mfma_f32_16x16x32_bf16 v[0:3], v[156:159], v[188:191], v[0:3]
	s_barrier
	s_setprio 0
	s_add_i32 s65, 0, 0x18000
	s_add_i32 s66, 0, 0x1c000
	v_add_u32_e32 v124, s65, v244
	v_add_u32_e32 v156, s66, v244
	ds_read_b128 v[112:115], v124
	ds_read_b128 v[116:119], v124 offset:1024
	ds_read_b128 v[120:123], v124 offset:2048
	ds_read_b128 v[124:127], v124 offset:3072
	ds_read_b128 v[136:139], v156
	ds_read_b128 v[140:143], v156 offset:1024
	ds_read_b128 v[152:155], v156 offset:2048
	ds_read_b128 v[156:159], v156 offset:3072
	s_add_u32 s38, s38, 0xb0000
	s_addc_u32 s39, s39, 0
	s_mov_b32 m0, s47
	v_lshl_add_u64 v[214:215], s[38:39], 0, v[192:193]
	ds_read_b128 v[160:163], v248 offset:32768
	ds_read_b128 v[164:167], v248 offset:33792
	ds_read_b128 v[168:171], v248 offset:34816
	ds_read_b128 v[172:175], v248 offset:35840
	ds_read_b128 v[176:179], v248 offset:36864
	ds_read_b128 v[180:183], v248 offset:37888
	ds_read_b128 v[184:187], v248 offset:38912
	ds_read_b128 v[188:191], v248 offset:39936
	global_load_lds_dwordx4 v[214:215], off
	v_lshl_add_u64 v[214:215], s[38:39], 0, v[196:197]
	s_mov_b32 m0, s48
	s_nop 0
	global_load_lds_dwordx4 v[214:215], off
	s_waitcnt vmcnt(8)
	s_waitcnt lgkmcnt(0)
	s_barrier
	s_setprio 1
	v_mfma_f32_16x16x32_bf16 v[148:151], v[112:115], v[160:163], v[148:151]
	v_mfma_f32_16x16x32_bf16 v[144:147], v[120:123], v[160:163], v[144:147]
	v_mfma_f32_16x16x32_bf16 v[108:111], v[112:115], v[168:171], v[108:111]
	v_mfma_f32_16x16x32_bf16 v[104:107], v[120:123], v[168:171], v[104:107]
	v_mfma_f32_16x16x32_bf16 v[92:95], v[112:115], v[176:179], v[92:95]
	v_mfma_f32_16x16x32_bf16 v[88:91], v[120:123], v[176:179], v[88:91]
	v_mfma_f32_16x16x32_bf16 v[76:79], v[112:115], v[184:187], v[76:79]
	v_mfma_f32_16x16x32_bf16 v[72:75], v[120:123], v[184:187], v[72:75]
	v_mfma_f32_16x16x32_bf16 v[148:151], v[116:119], v[164:167], v[148:151]
	v_mfma_f32_16x16x32_bf16 v[144:147], v[124:127], v[164:167], v[144:147]
	v_mfma_f32_16x16x32_bf16 v[108:111], v[116:119], v[172:175], v[108:111]
	v_mfma_f32_16x16x32_bf16 v[104:107], v[124:127], v[172:175], v[104:107]
	v_mfma_f32_16x16x32_bf16 v[92:95], v[116:119], v[180:183], v[92:95]
	v_mfma_f32_16x16x32_bf16 v[88:91], v[124:127], v[180:183], v[88:91]
	v_mfma_f32_16x16x32_bf16 v[76:79], v[116:119], v[188:191], v[76:79]
	v_mfma_f32_16x16x32_bf16 v[72:75], v[124:127], v[188:191], v[72:75]
	v_mfma_f32_16x16x32_bf16 v[132:135], v[136:139], v[160:163], v[132:135]
	v_mfma_f32_16x16x32_bf16 v[128:131], v[152:155], v[160:163], v[128:131]
	v_mfma_f32_16x16x32_bf16 v[100:103], v[136:139], v[168:171], v[100:103]
	v_mfma_f32_16x16x32_bf16 v[96:99], v[152:155], v[168:171], v[96:99]
	v_mfma_f32_16x16x32_bf16 v[84:87], v[136:139], v[176:179], v[84:87]
	v_mfma_f32_16x16x32_bf16 v[80:83], v[152:155], v[176:179], v[80:83]
	v_mfma_f32_16x16x32_bf16 v[68:71], v[136:139], v[184:187], v[68:71]
	v_mfma_f32_16x16x32_bf16 v[64:67], v[152:155], v[184:187], v[64:67]
	v_mfma_f32_16x16x32_bf16 v[132:135], v[140:143], v[164:167], v[132:135]
	v_mfma_f32_16x16x32_bf16 v[128:131], v[156:159], v[164:167], v[128:131]
	v_mfma_f32_16x16x32_bf16 v[100:103], v[140:143], v[172:175], v[100:103]
	v_mfma_f32_16x16x32_bf16 v[96:99], v[156:159], v[172:175], v[96:99]
	v_mfma_f32_16x16x32_bf16 v[84:87], v[140:143], v[180:183], v[84:87]
	v_mfma_f32_16x16x32_bf16 v[80:83], v[156:159], v[180:183], v[80:83]
	v_mfma_f32_16x16x32_bf16 v[68:71], v[140:143], v[188:191], v[68:71]
	v_mfma_f32_16x16x32_bf16 v[64:67], v[156:159], v[188:191], v[64:67]
	s_barrier
; #define PG8_STAGE(bufoff, gbase, voff) do { _Pragma("unroll") for (int _i = 0; _i < 2; ++_i) \
;         __builtin_amdgcn_global_load_lds((const unsigned*)((const char*)(gbase) + (voff)[_i]), (PG8_LAS unsigned*)(lds + (bufoff) + ldsw + _i * 8192), 16, 0, 0); } while (0)
; #define PG8_LDA(dst, b, h) do { _Pragma("unroll") for (int m = 0; m < 4; ++m) _Pragma("unroll") for (int k = 0; k < 2; ++k) dst[m][k] = *(const PG8_LAS bf16x8*)(lds + PG8_SA(b, h) + aoff + m * 2048 + k * 1024); } while (0)
; #define PG8_MMA(ai, bj, At, Bt) do { __builtin_amdgcn_s_setprio(1); _Pragma("unroll") for (int m = 0; m < 4; ++m) _Pragma("unroll") for (int n = 0; n < 2; ++n) _Pragma("unroll") for (int k = 0; k < 2; ++k) \
;         acc[ai][bj][m][n] = __builtin_amdgcn_mfma_f32_16x16x32_bf16(Bt[n][k], At[m][k], acc[ai][bj][m][n], 0, 0, 0); __builtin_amdgcn_s_setprio(0); } while (0)
; #define PG8_WAIT_V(n) asm volatile("s_waitcnt vmcnt(" #n ")" ::: "memory")
; #define PG8_WAIT_L(n) asm volatile("s_waitcnt lgkmcnt(" #n ")" ::: "memory")
; #define PG8_BAR __builtin_amdgcn_s_barrier()
; #define PG8_SCHED __builtin_amdgcn_sched_barrier(0)
; template <class Epi, class Sched, bool ALIGN_EPI = false, bool SP2 = false>
; __device__ __forceinline__ void gemm_phase(PG8_LAS unsigned char* lds, const Gemm g, const Sched& S, const Epi& E) {
;     ...
;         for (int t = 0; t < nt; t += 2) {
;     ...
;             PG8_LDA(At, 1, 1); PG8_STAGE(PG8_SB(1, 0), b3, voffB); PG8_STAGE(PG8_SB(1, 1), b3 + hstep, voffB); PG8_STAGE(PG8_SA(1, 0), a3, voffA);
;             PG8_WAIT_V(8); PG8_WAIT_L(0); PG8_BAR; PG8_MMA(1, 0, At, B0); PG8_MMA(1, 1, At, B1); PG8_BAR; PG8_SCHED;
	s_setprio 0
	s_add_i32 s38, s65, s44
	v_lshl_add_u64 v[206:207], v[206:207], 0, s[18:19]
	s_mov_b32 m0, s38
	ds_read_b128 v[160:163], v248 offset:49152
	ds_read_b128 v[164:167], v248 offset:50176
	ds_read_b128 v[168:171], v248 offset:51200
	ds_read_b128 v[172:175], v248 offset:52224
	ds_read_b128 v[176:179], v248 offset:53248
	ds_read_b128 v[180:183], v248 offset:54272
	ds_read_b128 v[184:187], v248 offset:55296
	ds_read_b128 v[188:191], v248 offset:56320
	global_load_lds_dwordx4 v[206:207], off
	s_add_i32 m0, s38, 0x2000
	s_add_u32 s36, s36, 0xb0080
	v_lshl_add_u64 v[206:207], v[208:209], 0, s[18:19]
	s_addc_u32 s37, s37, 0
	s_add_i32 s38, s66, s44
	global_load_lds_dwordx4 v[206:207], off
	v_lshl_add_u64 v[206:207], s[36:37], 0, v[194:195]
	s_mov_b32 m0, s38
	s_nop 0
	global_load_lds_dwordx4 v[206:207], off
	v_lshl_add_u64 v[206:207], s[36:37], 0, v[198:199]
	s_add_i32 m0, s38, 0x2000
	s_nop 0
	global_load_lds_dwordx4 v[206:207], off
	v_lshl_add_u64 v[206:207], v[210:211], 0, s[18:19]
	s_mov_b32 m0, s50
	s_nop 0
	global_load_lds_dwordx4 v[206:207], off
	v_lshl_add_u64 v[206:207], v[212:213], 0, s[18:19]
	s_mov_b32 m0, s51
	s_nop 0
	global_load_lds_dwordx4 v[206:207], off
	s_waitcnt vmcnt(8)
	s_waitcnt lgkmcnt(0)
	s_barrier
	s_setprio 1
	v_mfma_f32_16x16x32_bf16 v[60:63], v[112:115], v[160:163], v[60:63]
	v_mfma_f32_16x16x32_bf16 v[56:59], v[120:123], v[160:163], v[56:59]
	v_mfma_f32_16x16x32_bf16 v[44:47], v[112:115], v[168:171], v[44:47]
	v_mfma_f32_16x16x32_bf16 v[40:43], v[120:123], v[168:171], v[40:43]
	v_mfma_f32_16x16x32_bf16 v[28:31], v[112:115], v[176:179], v[28:31]
	v_mfma_f32_16x16x32_bf16 v[24:27], v[120:123], v[176:179], v[24:27]
	v_mfma_f32_16x16x32_bf16 v[12:15], v[112:115], v[184:187], v[12:15]
	v_mfma_f32_16x16x32_bf16 v[8:11], v[120:123], v[184:187], v[8:11]
	v_mfma_f32_16x16x32_bf16 v[60:63], v[116:119], v[164:167], v[60:63]
	v_mfma_f32_16x16x32_bf16 v[56:59], v[124:127], v[164:167], v[56:59]
	v_mfma_f32_16x16x32_bf16 v[44:47], v[116:119], v[172:175], v[44:47]
	v_mfma_f32_16x16x32_bf16 v[40:43], v[124:127], v[172:175], v[40:43]
	v_mfma_f32_16x16x32_bf16 v[28:31], v[116:119], v[180:183], v[28:31]
	v_mfma_f32_16x16x32_bf16 v[24:27], v[124:127], v[180:183], v[24:27]
	v_mfma_f32_16x16x32_bf16 v[12:15], v[116:119], v[188:191], v[12:15]
	v_mfma_f32_16x16x32_bf16 v[8:11], v[124:127], v[188:191], v[8:11]
	v_mfma_f32_16x16x32_bf16 v[52:55], v[136:139], v[160:163], v[52:55]
	v_mfma_f32_16x16x32_bf16 v[48:51], v[152:155], v[160:163], v[48:51]
	v_mfma_f32_16x16x32_bf16 v[36:39], v[136:139], v[168:171], v[36:39]
	v_mfma_f32_16x16x32_bf16 v[32:35], v[152:155], v[168:171], v[32:35]
	v_mfma_f32_16x16x32_bf16 v[20:23], v[136:139], v[176:179], v[20:23]
	v_mfma_f32_16x16x32_bf16 v[16:19], v[152:155], v[176:179], v[16:19]
	v_mfma_f32_16x16x32_bf16 v[4:7], v[136:139], v[184:187], v[4:7]
	v_mfma_f32_16x16x32_bf16 v[0:3], v[152:155], v[184:187], v[0:3]
	v_mfma_f32_16x16x32_bf16 v[52:55], v[140:143], v[164:167], v[52:55]
	v_mfma_f32_16x16x32_bf16 v[48:51], v[156:159], v[164:167], v[48:51]
	v_mfma_f32_16x16x32_bf16 v[36:39], v[140:143], v[172:175], v[36:39]
	v_mfma_f32_16x16x32_bf16 v[32:35], v[156:159], v[172:175], v[32:35]
	v_mfma_f32_16x16x32_bf16 v[20:23], v[140:143], v[180:183], v[20:23]
	v_mfma_f32_16x16x32_bf16 v[16:19], v[156:159], v[180:183], v[16:19]
	v_mfma_f32_16x16x32_bf16 v[4:7], v[140:143], v[188:191], v[4:7]
	v_mfma_f32_16x16x32_bf16 v[0:3], v[156:159], v[188:191], v[0:3]
	s_barrier
	s_setprio 0
	s_add_i32 s64, s64, 2
	s_add_u32 s34, s34, 0x100
	s_addc_u32 s35, s35, 0
	s_add_u32 s59, s59, 0x100
	s_addc_u32 s63, s63, 0

; #define PG8_BAR __builtin_amdgcn_s_barrier()
; template <class Epi, class Sched, bool ALIGN_EPI = false, bool SP2 = false>
; __device__ __forceinline__ void gemm_phase(PG8_LAS unsigned char* lds, const Gemm g, const Sched& S, const Epi& E) {
;     ...
;         if constexpr (!Epi::AFTER_DRAIN) { E(acc, cur, wr, wc, fr, fq); S.done(cur); }
;         if (!has_next) break;
; #pragma unroll
;         for (int a = 0; a < 2; ++a)
; #pragma unroll
;             for (int b = 0; b < 2; ++b)
; #pragma unroll
;                 for (int m = 0; m < 4; ++m)
; #pragma unroll
;                     for (int n = 0; n < 2; ++n) acc[a][b][m][n] = (f32x4){0.f, 0.f, 0.f, 0.f};
;         cur = nxt; cA = nA; cB = nB; ++ui;
;         if constexpr (ALIGN_EPI) { if (wr == 1) PG8_BAR; }
;     }
.LBB0_425:
	s_or_b64 exec, exec, s[34:35]
	s_and_b64 vcc, exec, s[6:7]
	s_mov_b64 s[6:7], -1
	s_cbranch_vccnz .LBB0_394
	s_andn2_b64 vcc, exec, s[12:13]
	s_cbranch_vccnz .LBB0_393
	s_mov_b32 s99, 1
	s_branch .LBB0_393

; #define PG8_STAGE(bufoff, gbase, voff) do { _Pragma("unroll") for (int _i = 0; _i < 2; ++_i) \
;         __builtin_amdgcn_global_load_lds((const unsigned*)((const char*)(gbase) + (voff)[_i]), (PG8_LAS unsigned*)(lds + (bufoff) + ldsw + _i * 8192), 16, 0, 0); } while (0)
; #define PG8_LDA(dst, b, h) do { _Pragma("unroll") for (int m = 0; m < 4; ++m) _Pragma("unroll") for (int k = 0; k < 2; ++k) dst[m][k] = *(const PG8_LAS bf16x8*)(lds + PG8_SA(b, h) + aoff + m * 2048 + k * 1024); } while (0)
; #define PG8_LDB(dst, b, h) do { _Pragma("unroll") for (int n = 0; n < 2; ++n) _Pragma("unroll") for (int k = 0; k < 2; ++k) dst[n][k] = *(const PG8_LAS bf16x8*)(lds + PG8_SB(b, h) + boff + n * 2048 + k * 1024); } while (0)
; #define PG8_WAIT_V(n) asm volatile("s_waitcnt vmcnt(" #n ")" ::: "memory")
; #define PG8_WAIT_L(n) asm volatile("s_waitcnt lgkmcnt(" #n ")" ::: "memory")
; #define PG8_BAR __builtin_amdgcn_s_barrier()
; #define PG8_SCHED __builtin_amdgcn_sched_barrier(0)
; template <class Epi, class Sched, bool ALIGN_EPI = false, bool SP2 = false>
; __device__ __forceinline__ void gemm_phase(PG8_LAS unsigned char* lds, const Gemm g, const Sched& S, const Epi& E) {
;     ...
;         const bool has_next = S.next(ui + 1, nxt);
;         const char* nA = has_next ? (const char*)g.A + (size_t)nxt.pm * tstep : cA; const char* nB = has_next ? (const char*)g.Bt + (size_t)nxt.pn * tstep : cB;
;         for (int t = 0; t < nt; t += 2) {
;             const bool last = (t == nt - 2);
;             if constexpr (Epi::PREFETCH) { if (t == nt - 4) E.prefetch(cur, lds + STAGE_BYTES + 1024, tid); }
;             const char* a1 = cA + (size_t)(t + 1) * kstep;
;             const char* a2 = last ? nA : cA + (size_t)(t + 2) * kstep; const char* b2 = last ? nB : cB + (size_t)(t + 2) * kstep;
;             const char* a3 = a2 + kstep; const char* b3 = b2 + kstep;
;             if (last && has_next) S.a_ready(nxt);
;             if constexpr (SP2) {
;             PG8_LDB(B0, 0, 0); PG8_LDB(B1, 0, 1); PG8_SCHED; PG8_LDA(At, 0, 0); PG8_STAGE(PG8_SA(1, 1), a1 + hstep, voffA);
;             PG8_WAIT_V(8); PG8_WAIT_L(0); PG8_BAR; PG8_MMA(0, 0, At, B0); PG8_MMA(0, 1, At, B1); PG8_BAR; PG8_SCHED;
;             PG8_LDA(At, 0, 1); PG8_STAGE(PG8_SB(0, 0), b2, voffB); PG8_STAGE(PG8_SB(0, 1), b2 + hstep, voffB); PG8_STAGE(PG8_SA(0, 0), a2, voffA);
.LBB0_592:
	s_ashr_i32 s37, s36, 31
	s_lshl_b64 s[38:39], s[36:37], 19
	s_add_u32 s38, s53, s38
	s_addc_u32 s39, s54, s39
	s_and_b64 s[40:41], s[4:5], exec
	s_cselect_b32 s37, s39, s45
	s_cselect_b32 s76, s38, s44
	s_ashr_i32 s35, s34, 31
	s_lshl_b64 s[40:41], s[34:35], 19
	s_add_u32 s40, s50, s40
	s_addc_u32 s41, s51, s41
	s_and_b64 s[48:49], s[4:5], exec
	s_cselect_b32 s35, s41, s47
	s_cselect_b32 s77, s40, s46
	s_add_u32 s44, s44, 0x40080
	s_addc_u32 s45, s45, 0
	s_add_u32 s78, s46, 0x100
	s_addc_u32 s79, s47, 0
	s_mov_b32 s80, -2
	s_cmp_eq_u32 s99, 0
	s_cbranch_scc1 .Lnobar_2
	s_mov_b32 s99, 0
	s_barrier
.Lnobar_2:
	ds_read_b128 v[144:147], v151
	ds_read_b128 v[156:159], v151 offset:1024
	ds_read_b128 v[160:163], v151 offset:2048
	ds_read_b128 v[164:167], v151 offset:3072
	ds_read_b128 v[168:171], v152
	ds_read_b128 v[172:175], v152 offset:1024
	ds_read_b128 v[176:179], v152 offset:2048
	ds_read_b128 v[180:183], v152 offset:3072
	s_add_u32 s46, s44, 0xfffc0080
	s_addc_u32 s47, s45, -1
	s_cmp_eq_u32 s80, 12
	s_cselect_b32 s49, s37, s47
	s_cselect_b32 s48, s76, s46
	s_cselect_b32 s47, s35, s79
	s_cselect_b32 s46, s77, s78
	v_lshl_add_u64 v[216:217], s[44:45], 0, v[136:137]
	s_add_i32 m0, s43, 0xc000
	ds_read_b128 v[184:187], v153
	ds_read_b128 v[188:191], v153 offset:1024
	ds_read_b128 v[192:195], v153 offset:2048
	ds_read_b128 v[196:199], v153 offset:3072
	ds_read_b128 v[200:203], v153 offset:4096
	ds_read_b128 v[204:207], v153 offset:5120
	ds_read_b128 v[208:211], v153 offset:6144
	ds_read_b128 v[212:215], v153 offset:7168
	global_load_lds_dwordx4 v[216:217], off
	v_lshl_add_u64 v[216:217], s[44:45], 0, v[138:139]
	s_add_i32 m0, s43, 0xe000
	s_nop 0
	global_load_lds_dwordx4 v[216:217], off
	s_waitcnt vmcnt(8)
	s_waitcnt lgkmcnt(0)
	s_barrier
	s_setprio 1
	v_mfma_f32_16x16x32_bf16 v[124:127], v[144:147], v[184:187], 0
	v_mfma_f32_16x16x32_bf16 v[120:123], v[160:163], v[184:187], 0
	v_mfma_f32_16x16x32_bf16 v[108:111], v[144:147], v[192:195], 0
	v_mfma_f32_16x16x32_bf16 v[104:107], v[160:163], v[192:195], 0
	v_mfma_f32_16x16x32_bf16 v[92:95], v[144:147], v[200:203], 0
	v_mfma_f32_16x16x32_bf16 v[88:91], v[160:163], v[200:203], 0
	v_mfma_f32_16x16x32_bf16 v[76:79], v[144:147], v[208:211], 0
	v_mfma_f32_16x16x32_bf16 v[72:75], v[160:163], v[208:211], 0
	v_mfma_f32_16x16x32_bf16 v[124:127], v[156:159], v[188:191], v[124:127]
	v_mfma_f32_16x16x32_bf16 v[120:123], v[164:167], v[188:191], v[120:123]
	v_mfma_f32_16x16x32_bf16 v[108:111], v[156:159], v[196:199], v[108:111]
	v_mfma_f32_16x16x32_bf16 v[104:107], v[164:167], v[196:199], v[104:107]
	v_mfma_f32_16x16x32_bf16 v[92:95], v[156:159], v[204:207], v[92:95]
	v_mfma_f32_16x16x32_bf16 v[88:91], v[164:167], v[204:207], v[88:91]
	v_mfma_f32_16x16x32_bf16 v[76:79], v[156:159], v[212:215], v[76:79]
	v_mfma_f32_16x16x32_bf16 v[72:75], v[164:167], v[212:215], v[72:75]
	v_mfma_f32_16x16x32_bf16 v[116:119], v[168:171], v[184:187], 0
	v_mfma_f32_16x16x32_bf16 v[112:115], v[176:179], v[184:187], 0
	v_mfma_f32_16x16x32_bf16 v[100:103], v[168:171], v[192:195], 0
	v_mfma_f32_16x16x32_bf16 v[96:99], v[176:179], v[192:195], 0
	v_mfma_f32_16x16x32_bf16 v[84:87], v[168:171], v[200:203], 0
	v_mfma_f32_16x16x32_bf16 v[80:83], v[176:179], v[200:203], 0
	v_mfma_f32_16x16x32_bf16 v[68:71], v[168:171], v[208:211], 0
	v_mfma_f32_16x16x32_bf16 v[64:67], v[176:179], v[208:211], 0
	v_mfma_f32_16x16x32_bf16 v[116:119], v[172:175], v[188:191], v[116:119]
	v_mfma_f32_16x16x32_bf16 v[112:115], v[180:183], v[188:191], v[112:115]
	v_mfma_f32_16x16x32_bf16 v[100:103], v[172:175], v[196:199], v[100:103]
	v_mfma_f32_16x16x32_bf16 v[96:99], v[180:183], v[196:199], v[96:99]
	v_mfma_f32_16x16x32_bf16 v[84:87], v[172:175], v[204:207], v[84:87]
	v_mfma_f32_16x16x32_bf16 v[80:83], v[180:183], v[204:207], v[80:83]
	v_mfma_f32_16x16x32_bf16 v[68:71], v[172:175], v[212:215], v[68:71]
	v_mfma_f32_16x16x32_bf16 v[64:67], v[180:183], v[212:215], v[64:67]
	s_barrier
	s_setprio 0
	s_add_i32 s81, s69, s52
	v_lshl_add_u64 v[216:217], s[46:47], 0, v[132:133]
	s_mov_b32 m0, s81
	ds_read_b128 v[184:187], v153 offset:16384
	ds_read_b128 v[188:191], v153 offset:17408
	ds_read_b128 v[192:195], v153 offset:18432
	ds_read_b128 v[196:199], v153 offset:19456
	ds_read_b128 v[200:203], v153 offset:20480
	ds_read_b128 v[204:207], v153 offset:21504
	ds_read_b128 v[208:211], v153 offset:22528
	ds_read_b128 v[212:215], v153 offset:23552
	global_load_lds_dwordx4 v[216:217], off
	s_add_i32 m0, s81, 0x2000
	s_add_u32 s82, s46, 0x40000
	v_lshl_add_u64 v[218:219], s[46:47], 0, v[128:129]
	s_addc_u32 s83, s47, 0
	s_add_i32 s81, s70, s52
	global_load_lds_dwordx4 v[218:219], off
	v_lshl_add_u64 v[220:221], s[82:83], 0, v[132:133]
	s_mov_b32 m0, s81
	v_lshl_add_u64 v[222:223], s[48:49], 0, v[130:131]
	global_load_lds_dwordx4 v[220:221], off
	v_lshl_add_u64 v[220:221], s[82:83], 0, v[128:129]
	s_add_i32 m0, s81, 0x2000
	s_nop 0
	global_load_lds_dwordx4 v[220:221], off
	v_lshl_add_u64 v[220:221], s[48:49], 0, v[134:135]
	s_mov_b32 m0, s43
	s_nop 0
	global_load_lds_dwordx4 v[220:221], off
	s_mov_b32 m0, s56
	s_nop 0
	global_load_lds_dwordx4 v[222:223], off
	s_waitcnt vmcnt(8)
	s_waitcnt lgkmcnt(0)
	s_barrier
; #define PG8_STAGE(bufoff, gbase, voff) do { _Pragma("unroll") for (int _i = 0; _i < 2; ++_i) \
;         __builtin_amdgcn_global_load_lds((const unsigned*)((const char*)(gbase) + (voff)[_i]), (PG8_LAS unsigned*)(lds + (bufoff) + ldsw + _i * 8192), 16, 0, 0); } while (0)
; #define PG8_LDA(dst, b, h) do { _Pragma("unroll") for (int m = 0; m < 4; ++m) _Pragma("unroll") for (int k = 0; k < 2; ++k) dst[m][k] = *(const PG8_LAS bf16x8*)(lds + PG8_SA(b, h) + aoff + m * 2048 + k * 1024); } while (0)
; #define PG8_LDB(dst, b, h) do { _Pragma("unroll") for (int n = 0; n < 2; ++n) _Pragma("unroll") for (int k = 0; k < 2; ++k) dst[n][k] = *(const PG8_LAS bf16x8*)(lds + PG8_SB(b, h) + boff + n * 2048 + k * 1024); } while (0)
; #define PG8_MMA(ai, bj, At, Bt) do { __builtin_amdgcn_s_setprio(1); _Pragma("unroll") for (int m = 0; m < 4; ++m) _Pragma("unroll") for (int n = 0; n < 2; ++n) _Pragma("unroll") for (int k = 0; k < 2; ++k) \
;         acc[ai][bj][m][n] = __builtin_amdgcn_mfma_f32_16x16x32_bf16(Bt[n][k], At[m][k], acc[ai][bj][m][n], 0, 0, 0); __builtin_amdgcn_s_setprio(0); } while (0)
; #define PG8_WAIT_V(n) asm volatile("s_waitcnt vmcnt(" #n ")" ::: "memory")
; #define PG8_WAIT_L(n) asm volatile("s_waitcnt lgkmcnt(" #n ")" ::: "memory")
; #define PG8_BAR __builtin_amdgcn_s_barrier()
; #define PG8_SCHED __builtin_amdgcn_sched_barrier(0)
; template <class Epi, class Sched, bool ALIGN_EPI = false, bool SP2 = false>
; __device__ __forceinline__ void gemm_phase(PG8_LAS unsigned char* lds, const Gemm g, const Sched& S, const Epi& E) {
;     ...
;             PG8_WAIT_V(8); PG8_WAIT_L(0); PG8_BAR; PG8_MMA(1, 0, At, B0); PG8_MMA(1, 1, At, B1); PG8_BAR; PG8_SCHED;
;             PG8_LDB(B0, 1, 0); PG8_LDB(B1, 1, 1); PG8_SCHED; PG8_LDA(At, 1, 0); PG8_STAGE(PG8_SA(0, 1), a2 + hstep, voffA);
;             PG8_WAIT_V(8); PG8_WAIT_L(0); PG8_BAR; PG8_MMA(0, 0, At, B0); PG8_MMA(0, 1, At, B1); PG8_BAR; PG8_SCHED;
	s_setprio 1
	v_mfma_f32_16x16x32_bf16 v[60:63], v[144:147], v[184:187], 0
	v_mfma_f32_16x16x32_bf16 v[56:59], v[160:163], v[184:187], 0
	v_mfma_f32_16x16x32_bf16 v[44:47], v[144:147], v[192:195], 0
	v_mfma_f32_16x16x32_bf16 v[40:43], v[160:163], v[192:195], 0
	v_mfma_f32_16x16x32_bf16 v[28:31], v[144:147], v[200:203], 0
	v_mfma_f32_16x16x32_bf16 v[24:27], v[160:163], v[200:203], 0
	v_mfma_f32_16x16x32_bf16 v[12:15], v[144:147], v[208:211], 0
	v_mfma_f32_16x16x32_bf16 v[8:11], v[160:163], v[208:211], 0
	v_mfma_f32_16x16x32_bf16 v[60:63], v[156:159], v[188:191], v[60:63]
	v_mfma_f32_16x16x32_bf16 v[56:59], v[164:167], v[188:191], v[56:59]
	v_mfma_f32_16x16x32_bf16 v[44:47], v[156:159], v[196:199], v[44:47]
	v_mfma_f32_16x16x32_bf16 v[40:43], v[164:167], v[196:199], v[40:43]
	v_mfma_f32_16x16x32_bf16 v[28:31], v[156:159], v[204:207], v[28:31]
	v_mfma_f32_16x16x32_bf16 v[24:27], v[164:167], v[204:207], v[24:27]
	v_mfma_f32_16x16x32_bf16 v[12:15], v[156:159], v[212:215], v[12:15]
	v_mfma_f32_16x16x32_bf16 v[8:11], v[164:167], v[212:215], v[8:11]
	v_mfma_f32_16x16x32_bf16 v[52:55], v[168:171], v[184:187], 0
	v_mfma_f32_16x16x32_bf16 v[48:51], v[176:179], v[184:187], 0
	v_mfma_f32_16x16x32_bf16 v[36:39], v[168:171], v[192:195], 0
	v_mfma_f32_16x16x32_bf16 v[32:35], v[176:179], v[192:195], 0
	v_mfma_f32_16x16x32_bf16 v[20:23], v[168:171], v[200:203], 0
	v_mfma_f32_16x16x32_bf16 v[16:19], v[176:179], v[200:203], 0
	v_mfma_f32_16x16x32_bf16 v[4:7], v[168:171], v[208:211], 0
	v_mfma_f32_16x16x32_bf16 v[0:3], v[176:179], v[208:211], 0
	v_mfma_f32_16x16x32_bf16 v[52:55], v[172:175], v[188:191], v[52:55]
	v_mfma_f32_16x16x32_bf16 v[48:51], v[180:183], v[188:191], v[48:51]
	v_mfma_f32_16x16x32_bf16 v[36:39], v[172:175], v[196:199], v[36:39]
	v_mfma_f32_16x16x32_bf16 v[32:35], v[180:183], v[196:199], v[32:35]
	v_mfma_f32_16x16x32_bf16 v[20:23], v[172:175], v[204:207], v[20:23]
	v_mfma_f32_16x16x32_bf16 v[16:19], v[180:183], v[204:207], v[16:19]
	v_mfma_f32_16x16x32_bf16 v[4:7], v[172:175], v[212:215], v[4:7]
	v_mfma_f32_16x16x32_bf16 v[0:3], v[180:183], v[212:215], v[0:3]
	s_barrier
	s_setprio 0
	s_add_i32 s81, 0, 0x18000
	s_add_i32 s82, 0, 0x1c000
	v_add_u32_e32 v164, s81, v149
	v_add_u32_e32 v180, s82, v149
	ds_read_b128 v[144:147], v164
	ds_read_b128 v[156:159], v164 offset:1024
	ds_read_b128 v[160:163], v164 offset:2048
	ds_read_b128 v[164:167], v164 offset:3072
	ds_read_b128 v[168:171], v180
	ds_read_b128 v[172:175], v180 offset:1024
	ds_read_b128 v[176:179], v180 offset:2048
	ds_read_b128 v[180:183], v180 offset:3072
	s_add_u32 s48, s48, 0x40000
	s_addc_u32 s49, s49, 0
	s_mov_b32 m0, s57
	v_lshl_add_u64 v[224:225], s[48:49], 0, v[134:135]
	ds_read_b128 v[184:187], v153 offset:32768
	ds_read_b128 v[188:191], v153 offset:33792
	ds_read_b128 v[192:195], v153 offset:34816
	ds_read_b128 v[196:199], v153 offset:35840
	ds_read_b128 v[200:203], v153 offset:36864
	ds_read_b128 v[204:207], v153 offset:37888
	ds_read_b128 v[208:211], v153 offset:38912
	ds_read_b128 v[212:215], v153 offset:39936
	global_load_lds_dwordx4 v[224:225], off
	v_lshl_add_u64 v[224:225], s[48:49], 0, v[130:131]
	s_mov_b32 m0, s58
	s_nop 0
	global_load_lds_dwordx4 v[224:225], off
	s_waitcnt vmcnt(8)
	s_waitcnt lgkmcnt(0)
	s_barrier
	s_setprio 1
	v_mfma_f32_16x16x32_bf16 v[124:127], v[144:147], v[184:187], v[124:127]
	v_mfma_f32_16x16x32_bf16 v[120:123], v[160:163], v[184:187], v[120:123]
	v_mfma_f32_16x16x32_bf16 v[108:111], v[144:147], v[192:195], v[108:111]
	v_mfma_f32_16x16x32_bf16 v[104:107], v[160:163], v[192:195], v[104:107]
	v_mfma_f32_16x16x32_bf16 v[92:95], v[144:147], v[200:203], v[92:95]
	v_mfma_f32_16x16x32_bf16 v[88:91], v[160:163], v[200:203], v[88:91]
	v_mfma_f32_16x16x32_bf16 v[76:79], v[144:147], v[208:211], v[76:79]
	v_mfma_f32_16x16x32_bf16 v[72:75], v[160:163], v[208:211], v[72:75]
	v_mfma_f32_16x16x32_bf16 v[124:127], v[156:159], v[188:191], v[124:127]
	v_mfma_f32_16x16x32_bf16 v[120:123], v[164:167], v[188:191], v[120:123]
	v_mfma_f32_16x16x32_bf16 v[108:111], v[156:159], v[196:199], v[108:111]
	v_mfma_f32_16x16x32_bf16 v[104:107], v[164:167], v[196:199], v[104:107]
	v_mfma_f32_16x16x32_bf16 v[92:95], v[156:159], v[204:207], v[92:95]
	v_mfma_f32_16x16x32_bf16 v[88:91], v[164:167], v[204:207], v[88:91]
	v_mfma_f32_16x16x32_bf16 v[76:79], v[156:159], v[212:215], v[76:79]
	v_mfma_f32_16x16x32_bf16 v[72:75], v[164:167], v[212:215], v[72:75]
	v_mfma_f32_16x16x32_bf16 v[116:119], v[168:171], v[184:187], v[116:119]
	v_mfma_f32_16x16x32_bf16 v[112:115], v[176:179], v[184:187], v[112:115]
	v_mfma_f32_16x16x32_bf16 v[100:103], v[168:171], v[192:195], v[100:103]
	v_mfma_f32_16x16x32_bf16 v[96:99], v[176:179], v[192:195], v[96:99]
	v_mfma_f32_16x16x32_bf16 v[84:87], v[168:171], v[200:203], v[84:87]
	v_mfma_f32_16x16x32_bf16 v[80:83], v[176:179], v[200:203], v[80:83]
	v_mfma_f32_16x16x32_bf16 v[68:71], v[168:171], v[208:211], v[68:71]
	v_mfma_f32_16x16x32_bf16 v[64:67], v[176:179], v[208:211], v[64:67]
	v_mfma_f32_16x16x32_bf16 v[116:119], v[172:175], v[188:191], v[116:119]
	v_mfma_f32_16x16x32_bf16 v[112:115], v[180:183], v[188:191], v[112:115]
	v_mfma_f32_16x16x32_bf16 v[100:103], v[172:175], v[196:199], v[100:103]
	v_mfma_f32_16x16x32_bf16 v[96:99], v[180:183], v[196:199], v[96:99]
	v_mfma_f32_16x16x32_bf16 v[84:87], v[172:175], v[204:207], v[84:87]
	v_mfma_f32_16x16x32_bf16 v[80:83], v[180:183], v[204:207], v[80:83]
	v_mfma_f32_16x16x32_bf16 v[68:71], v[172:175], v[212:215], v[68:71]
	v_mfma_f32_16x16x32_bf16 v[64:67], v[180:183], v[212:215], v[64:67]
	s_barrier
; #define PG8_STAGE(bufoff, gbase, voff) do { _Pragma("unroll") for (int _i = 0; _i < 2; ++_i) \
;         __builtin_amdgcn_global_load_lds((const unsigned*)((const char*)(gbase) + (voff)[_i]), (PG8_LAS unsigned*)(lds + (bufoff) + ldsw + _i * 8192), 16, 0, 0); } while (0)
; #define PG8_LDA(dst, b, h) do { _Pragma("unroll") for (int m = 0; m < 4; ++m) _Pragma("unroll") for (int k = 0; k < 2; ++k) dst[m][k] = *(const PG8_LAS bf16x8*)(lds + PG8_SA(b, h) + aoff + m * 2048 + k * 1024); } while (0)
; #define PG8_MMA(ai, bj, At, Bt) do { __builtin_amdgcn_s_setprio(1); _Pragma("unroll") for (int m = 0; m < 4; ++m) _Pragma("unroll") for (int n = 0; n < 2; ++n) _Pragma("unroll") for (int k = 0; k < 2; ++k) \
;         acc[ai][bj][m][n] = __builtin_amdgcn_mfma_f32_16x16x32_bf16(Bt[n][k], At[m][k], acc[ai][bj][m][n], 0, 0, 0); __builtin_amdgcn_s_setprio(0); } while (0)
; #define PG8_WAIT_V(n) asm volatile("s_waitcnt vmcnt(" #n ")" ::: "memory")
; #define PG8_WAIT_L(n) asm volatile("s_waitcnt lgkmcnt(" #n ")" ::: "memory")
; #define PG8_BAR __builtin_amdgcn_s_barrier()
; #define PG8_SCHED __builtin_amdgcn_sched_barrier(0)
; template <class Epi, class Sched, bool ALIGN_EPI = false, bool SP2 = false>
; __device__ __forceinline__ void gemm_phase(PG8_LAS unsigned char* lds, const Gemm g, const Sched& S, const Epi& E) {
;     ...
;         for (int t = 0; t < nt; t += 2) {
;     ...
;             PG8_LDA(At, 1, 1); PG8_STAGE(PG8_SB(1, 0), b3, voffB); PG8_STAGE(PG8_SB(1, 1), b3 + hstep, voffB); PG8_STAGE(PG8_SA(1, 0), a3, voffA);
;             PG8_WAIT_V(8); PG8_WAIT_L(0); PG8_BAR; PG8_MMA(1, 0, At, B0); PG8_MMA(1, 1, At, B1); PG8_BAR; PG8_SCHED;
	s_setprio 0
	s_add_i32 s48, s81, s52
	v_lshl_add_u64 v[216:217], v[216:217], 0, s[14:15]
	s_mov_b32 m0, s48
	ds_read_b128 v[184:187], v153 offset:49152
	ds_read_b128 v[188:191], v153 offset:50176
	ds_read_b128 v[192:195], v153 offset:51200
	ds_read_b128 v[196:199], v153 offset:52224
	ds_read_b128 v[200:203], v153 offset:53248
	ds_read_b128 v[204:207], v153 offset:54272
	ds_read_b128 v[208:211], v153 offset:55296
	ds_read_b128 v[212:215], v153 offset:56320
	global_load_lds_dwordx4 v[216:217], off
	s_add_i32 m0, s48, 0x2000
	s_add_u32 s46, s46, 0x40080
	v_lshl_add_u64 v[216:217], v[218:219], 0, s[14:15]
	s_addc_u32 s47, s47, 0
	s_add_i32 s48, s82, s52
	global_load_lds_dwordx4 v[216:217], off
	v_lshl_add_u64 v[216:217], s[46:47], 0, v[132:133]
	s_mov_b32 m0, s48
	s_nop 0
	global_load_lds_dwordx4 v[216:217], off
	v_lshl_add_u64 v[216:217], s[46:47], 0, v[128:129]
	s_add_i32 m0, s48, 0x2000
	s_nop 0
	global_load_lds_dwordx4 v[216:217], off
	v_lshl_add_u64 v[216:217], v[220:221], 0, s[14:15]
	s_mov_b32 m0, s65
	s_nop 0
	global_load_lds_dwordx4 v[216:217], off
	v_lshl_add_u64 v[216:217], v[222:223], 0, s[14:15]
	s_mov_b32 m0, s66
	s_nop 0
	global_load_lds_dwordx4 v[216:217], off
	s_waitcnt vmcnt(8)
	s_waitcnt lgkmcnt(0)
	s_barrier
	s_setprio 1
	v_mfma_f32_16x16x32_bf16 v[60:63], v[144:147], v[184:187], v[60:63]
	v_mfma_f32_16x16x32_bf16 v[56:59], v[160:163], v[184:187], v[56:59]
	v_mfma_f32_16x16x32_bf16 v[44:47], v[144:147], v[192:195], v[44:47]
	v_mfma_f32_16x16x32_bf16 v[40:43], v[160:163], v[192:195], v[40:43]
	v_mfma_f32_16x16x32_bf16 v[28:31], v[144:147], v[200:203], v[28:31]
	v_mfma_f32_16x16x32_bf16 v[24:27], v[160:163], v[200:203], v[24:27]
	v_mfma_f32_16x16x32_bf16 v[12:15], v[144:147], v[208:211], v[12:15]
	v_mfma_f32_16x16x32_bf16 v[8:11], v[160:163], v[208:211], v[8:11]
	v_mfma_f32_16x16x32_bf16 v[60:63], v[156:159], v[188:191], v[60:63]
	v_mfma_f32_16x16x32_bf16 v[56:59], v[164:167], v[188:191], v[56:59]
	v_mfma_f32_16x16x32_bf16 v[44:47], v[156:159], v[196:199], v[44:47]
	v_mfma_f32_16x16x32_bf16 v[40:43], v[164:167], v[196:199], v[40:43]
	v_mfma_f32_16x16x32_bf16 v[28:31], v[156:159], v[204:207], v[28:31]
	v_mfma_f32_16x16x32_bf16 v[24:27], v[164:167], v[204:207], v[24:27]
	v_mfma_f32_16x16x32_bf16 v[12:15], v[156:159], v[212:215], v[12:15]
	v_mfma_f32_16x16x32_bf16 v[8:11], v[164:167], v[212:215], v[8:11]
	v_mfma_f32_16x16x32_bf16 v[52:55], v[168:171], v[184:187], v[52:55]
	v_mfma_f32_16x16x32_bf16 v[48:51], v[176:179], v[184:187], v[48:51]
	v_mfma_f32_16x16x32_bf16 v[36:39], v[168:171], v[192:195], v[36:39]
	v_mfma_f32_16x16x32_bf16 v[32:35], v[176:179], v[192:195], v[32:35]
	v_mfma_f32_16x16x32_bf16 v[20:23], v[168:171], v[200:203], v[20:23]
	v_mfma_f32_16x16x32_bf16 v[16:19], v[176:179], v[200:203], v[16:19]
	v_mfma_f32_16x16x32_bf16 v[4:7], v[168:171], v[208:211], v[4:7]
	v_mfma_f32_16x16x32_bf16 v[0:3], v[176:179], v[208:211], v[0:3]
	v_mfma_f32_16x16x32_bf16 v[52:55], v[172:175], v[188:191], v[52:55]
	v_mfma_f32_16x16x32_bf16 v[48:51], v[180:183], v[188:191], v[48:51]
	v_mfma_f32_16x16x32_bf16 v[36:39], v[172:175], v[196:199], v[36:39]
	v_mfma_f32_16x16x32_bf16 v[32:35], v[180:183], v[196:199], v[32:35]
	v_mfma_f32_16x16x32_bf16 v[20:23], v[172:175], v[204:207], v[20:23]
	v_mfma_f32_16x16x32_bf16 v[16:19], v[180:183], v[204:207], v[16:19]
	v_mfma_f32_16x16x32_bf16 v[4:7], v[172:175], v[212:215], v[4:7]
	v_mfma_f32_16x16x32_bf16 v[0:3], v[180:183], v[212:215], v[0:3]
	s_barrier
	s_setprio 0
	s_add_i32 s80, s80, 2
	s_add_u32 s44, s44, 0x100
	s_addc_u32 s45, s45, 0
	s_add_u32 s78, s78, 0x100
	s_addc_u32 s79, s79, 0

; __device__ __forceinline__ unsigned cvt_pk_bf16(float lo, float hi) { unsigned r; asm volatile("v_cvt_pk_bf16_f32 %0, %1, %2" : "=v"(r) : "v"(lo), "v"(hi)); return r; }
; __device__ __forceinline__ float ld_agent(const rss_t* p) { return (float)__hip_atomic_load(p, __ATOMIC_RELAXED, __HIP_MEMORY_SCOPE_AGENT) * (1.0f / 16777216.0f); }
;     __device__ __forceinline__ void operator()(const f32x4 (&acc)[2][2][4][2], const Unit& u, int wr, int wc, int fr, int fq) const {
;         const int row0 = u.pm * BM + wr * 64 + fr; int colt = u.pn * BM; bf16_t* base = O;
;         if (split_cols) { const int t = colt / split_cols; base += (size_t)t * split_stride; colt -= t * split_cols; }
;         const float sc = (u.pn < qtiles) ? qscale : 1.0f;
;         const int col0 = colt + wc * 32 + 8 * fq;
;         float ssq[2][4];
; #pragma unroll
;         for (int ai = 0; ai < 2; ++ai)
; #pragma unroll
;             for (int m = 0; m < 4; ++m) ssq[ai][m] = ld_agent(rowss + row0 + ai * HALF + m * 16);
; #pragma unroll
;         for (int ai = 0; ai < 2; ++ai)
; #pragma unroll
;             for (int m = 0; m < 4; ++m) {
;                 const int row = row0 + ai * HALF + m * 16; const float rs = __builtin_amdgcn_rsqf(ssq[ai][m] * (1.0f / 1024.0f) + 1e-6f) * sc;
;                 bf16_t* rowp = base + (size_t)row * ldc + col0;
; #pragma unroll
;                 for (int bj = 0; bj < 2; ++bj) { const f32x4 v0 = acc[ai][bj][m][0] * rs, v1 = acc[ai][bj][m][1] * rs;
;                     u32x4 w; w.x = cvt_pk_bf16(v0[0], v0[1]); w.y = cvt_pk_bf16(v0[2], v0[3]); w.z = cvt_pk_bf16(v1[0], v1[1]); w.w = cvt_pk_bf16(v1[2], v1[3]);
;                     *(u32x4*)(rowp + bj * HALF) = w; }
.LBB0_596:
	v_lshl_add_u32 v146, s42, 8, v148
	v_ashrrev_i32_e32 v147, 31, v146
	v_lshl_add_u64 v[144:145], v[146:147], 3, s[6:7]
	global_load_dwordx2 v[156:157], v[144:145], off sc1
	global_load_dwordx2 v[158:159], v[144:145], off offset:128 sc1
	global_load_dwordx2 v[160:161], v[144:145], off offset:256 sc1
	global_load_dwordx2 v[162:163], v[144:145], off offset:384 sc1
	global_load_dwordx2 v[164:165], v[144:145], off offset:1024 sc1
	global_load_dwordx2 v[166:167], v[144:145], off offset:1152 sc1
	global_load_dwordx2 v[168:169], v[144:145], off offset:1280 sc1
	s_nop 0
	global_load_dwordx2 v[144:145], v[144:145], off offset:1408 sc1
	s_ashr_i32 s37, s75, 31
	s_lshr_b32 s37, s37, 30
	s_add_i32 s37, s75, s37
	s_ashr_i32 s44, s37, 2
	s_ashr_i32 s45, s44, 31
	s_lshl_b64 s[46:47], s[44:45], s68
	s_lshl_b32 s35, s75, 8
	s_lshl_b64 s[46:47], s[46:47], 1
	s_add_u32 s46, s63, s46
	s_addc_u32 s47, s64, s47
	s_lshl_b32 s37, s44, 10
	s_sub_i32 s35, s35, s37
	s_cmp_lt_i32 s75, 4
	s_cselect_b64 vcc, -1, 0
	s_waitcnt vmcnt(0)
	v_ffbh_u32_e32 v170, v157
	v_min_u32_e32 v170, 32, v170
	v_ffbh_u32_e32 v171, v159
	v_ffbh_u32_e32 v172, v161
	v_ffbh_u32_e32 v173, v163
	v_lshlrev_b64 v[156:157], v170, v[156:157]
	v_min_u32_e32 v171, 32, v171
	v_ffbh_u32_e32 v177, v145
	v_min_u32_e32 v177, 32, v177
	v_min_u32_e32 v172, 32, v172
	v_min_u32_e32 v173, 32, v173
	v_lshlrev_b64 v[144:145], v177, v[144:145]
	v_min_u32_e32 v156, 1, v156
	v_lshlrev_b64 v[158:159], v171, v[158:159]
	v_lshlrev_b64 v[160:161], v172, v[160:161]
	v_lshlrev_b64 v[162:163], v173, v[162:163]
	v_min_u32_e32 v144, 1, v144
	v_or_b32_e32 v156, v157, v156
	v_min_u32_e32 v158, 1, v158
	v_min_u32_e32 v160, 1, v160
	v_min_u32_e32 v162, 1, v162
	v_or_b32_e32 v144, v145, v144
	v_cvt_f32_u32_e32 v145, v156
	v_ffbh_u32_e32 v174, v165
	v_or_b32_e32 v157, v159, v158
	v_or_b32_e32 v158, v161, v160
	v_or_b32_e32 v159, v163, v162
	v_cvt_f32_u32_e32 v144, v144
	v_ffbh_u32_e32 v175, v167
	v_ffbh_u32_e32 v176, v169
	v_min_u32_e32 v174, 32, v174
	v_cvt_f32_u32_e32 v156, v157
	v_cvt_f32_u32_e32 v157, v158
	v_cvt_f32_u32_e32 v158, v159
	v_min_u32_e32 v175, 32, v175
	v_min_u32_e32 v176, 32, v176
	v_sub_u32_e32 v170, 32, v170
	v_lshlrev_b64 v[164:165], v174, v[164:165]
	v_lshlrev_b64 v[166:167], v175, v[166:167]
	v_lshlrev_b64 v[168:169], v176, v[168:169]
	v_sub_u32_e32 v177, 32, v177
	v_min_u32_e32 v164, 1, v164
	v_ldexp_f32 v145, v145, v170
	v_sub_u32_e32 v173, 32, v173
	v_min_u32_e32 v166, 1, v166
	v_min_u32_e32 v168, 1, v168
	v_or_b32_e32 v160, v165, v164
	v_ldexp_f32 v144, v144, v177
	v_mul_f32_e32 v145, 0x33800000, v145
	v_or_b32_e32 v161, v167, v166
	v_or_b32_e32 v162, v169, v168
	v_cvt_f32_u32_e32 v159, v160
	v_ldexp_f32 v158, v158, v173
	v_mul_f32_e32 v167, 0x33800000, v144
	v_fmamk_f32 v144, v145, 0x3a800000, v154
	v_cvt_f32_u32_e32 v160, v161
	v_cvt_f32_u32_e32 v161, v162
	v_mul_f32_e32 v164, 0x33800000, v158
	v_rsq_f32_e32 v158, v144
	v_sub_u32_e32 v171, 32, v171
	v_sub_u32_e32 v172, 32, v172
	v_sub_u32_e32 v174, 32, v174
	v_or_b32_e32 v144, s35, v150
	v_sub_u32_e32 v175, 32, v175
	v_sub_u32_e32 v176, 32, v176
	v_ldexp_f32 v156, v156, v171
	v_ldexp_f32 v157, v157, v172
	v_ldexp_f32 v159, v159, v174
	v_cndmask_b32_e32 v168, 1.0, v155, vcc
	v_ashrrev_i32_e32 v145, 31, v144
	v_ldexp_f32 v160, v160, v175
	v_ldexp_f32 v161, v161, v176
	v_mul_f32_e32 v162, 0x33800000, v156
	v_mul_f32_e32 v163, 0x33800000, v157
	v_mul_f32_e32 v159, 0x33800000, v159
	v_lshl_add_u64 v[156:157], v[144:145], 1, s[46:47]
	v_mul_f32_e32 v158, v168, v158
	v_lshlrev_b64 v[144:145], 11, v[146:147]
	v_mul_f32_e32 v165, 0x33800000, v160
	v_mul_f32_e32 v166, 0x33800000, v161
	v_lshl_add_u64 v[144:145], v[156:157], 0, v[144:145]
	v_pk_mul_f32 v[126:127], v[126:127], v[158:159] op_sel_hi:[1,0]
	v_pk_mul_f32 v[124:125], v[124:125], v[158:159] op_sel_hi:[1,0]
	v_pk_mul_f32 v[160:161], v[122:123], v[158:159] op_sel_hi:[1,0]
	v_pk_mul_f32 v[122:123], v[120:121], v[158:159] op_sel_hi:[1,0]
	v_cvt_pk_bf16_f32 v120, v124, v125
	v_cvt_pk_bf16_f32 v121, v126, v127
	v_pk_mul_f32 v[118:119], v[118:119], v[158:159] op_sel_hi:[1,0]
	v_cvt_pk_bf16_f32 v122, v122, v123
	v_cvt_pk_bf16_f32 v123, v160, v161
	global_store_dwordx4 v[144:145], v[120:123], off
	v_pk_mul_f32 v[116:117], v[116:117], v[158:159] op_sel_hi:[1,0]
	s_nop 0
	v_pk_mul_f32 v[120:121], v[114:115], v[158:159] op_sel_hi:[1,0]
	v_pk_mul_f32 v[114:115], v[112:113], v[158:159] op_sel_hi:[1,0]
	v_cvt_pk_bf16_f32 v112, v116, v117
	v_cvt_pk_bf16_f32 v113, v118, v119
	s_nop 0
	v_cvt_pk_bf16_f32 v114, v114, v115
	v_fmamk_f32 v115, v162, 0x3a800000, v154
	v_rsq_f32_e32 v116, v115
	v_cvt_pk_bf16_f32 v115, v120, v121
	global_store_dwordx4 v[144:145], v[112:115], off offset:256
	s_nop 1
	v_or_b32_e32 v112, 16, v146
	v_ashrrev_i32_e32 v113, 31, v112
	v_mul_f32_e32 v114, v168, v116
	v_lshlrev_b64 v[112:113], 11, v[112:113]
	v_lshl_add_u64 v[112:113], v[156:157], 0, v[112:113]
	v_pk_mul_f32 v[110:111], v[110:111], v[114:115] op_sel_hi:[1,0]
	v_pk_mul_f32 v[108:109], v[108:109], v[114:115] op_sel_hi:[1,0]
	v_pk_mul_f32 v[116:117], v[106:107], v[114:115] op_sel_hi:[1,0]
	v_pk_mul_f32 v[106:107], v[104:105], v[114:115] op_sel_hi:[1,0]
	v_cvt_pk_bf16_f32 v104, v108, v109
	v_cvt_pk_bf16_f32 v105, v110, v111
	v_pk_mul_f32 v[102:103], v[102:103], v[114:115] op_sel_hi:[1,0]
	v_cvt_pk_bf16_f32 v106, v106, v107
	v_cvt_pk_bf16_f32 v107, v116, v117
	global_store_dwordx4 v[112:113], v[104:107], off
	v_pk_mul_f32 v[100:101], v[100:101], v[114:115] op_sel_hi:[1,0]
	s_nop 0
	v_pk_mul_f32 v[104:105], v[98:99], v[114:115] op_sel_hi:[1,0]
	v_pk_mul_f32 v[98:99], v[96:97], v[114:115] op_sel_hi:[1,0]
	v_cvt_pk_bf16_f32 v96, v100, v101
; __device__ __forceinline__ unsigned cvt_pk_bf16(float lo, float hi) { unsigned r; asm volatile("v_cvt_pk_bf16_f32 %0, %1, %2" : "=v"(r) : "v"(lo), "v"(hi)); return r; }
; #define PG8_BAR __builtin_amdgcn_s_barrier()
;     __device__ __forceinline__ void operator()(const f32x4 (&acc)[2][2][4][2], const Unit& u, int wr, int wc, int fr, int fq) const {
;     ...
;         for (int ai = 0; ai < 2; ++ai)
; #pragma unroll
;             for (int m = 0; m < 4; ++m) {
;                 const int row = row0 + ai * HALF + m * 16; const float rs = __builtin_amdgcn_rsqf(ssq[ai][m] * (1.0f / 1024.0f) + 1e-6f) * sc;
;                 bf16_t* rowp = base + (size_t)row * ldc + col0;
; #pragma unroll
;                 for (int bj = 0; bj < 2; ++bj) { const f32x4 v0 = acc[ai][bj][m][0] * rs, v1 = acc[ai][bj][m][1] * rs;
;                     u32x4 w; w.x = cvt_pk_bf16(v0[0], v0[1]); w.y = cvt_pk_bf16(v0[2], v0[3]); w.z = cvt_pk_bf16(v1[0], v1[1]); w.w = cvt_pk_bf16(v1[2], v1[3]);
;                     *(u32x4*)(rowp + bj * HALF) = w; }
; template <class Epi, class Sched, bool ALIGN_EPI = false, bool SP2 = false>
; __device__ __forceinline__ void gemm_phase(PG8_LAS unsigned char* lds, const Gemm g, const Sched& S, const Epi& E) {
;     ...
;         if constexpr (!Epi::AFTER_DRAIN) { E(acc, cur, wr, wc, fr, fq); S.done(cur); }
;         if (!has_next) break;
; #pragma unroll
;         for (int a = 0; a < 2; ++a)
; #pragma unroll
;             for (int b = 0; b < 2; ++b)
; #pragma unroll
;                 for (int m = 0; m < 4; ++m)
; #pragma unroll
;                     for (int n = 0; n < 2; ++n) acc[a][b][m][n] = (f32x4){0.f, 0.f, 0.f, 0.f};
;         cur = nxt; cA = nA; cB = nB; ++ui;
;         if constexpr (ALIGN_EPI) { if (wr == 1) PG8_BAR; }
	v_cvt_pk_bf16_f32 v97, v102, v103
	s_nop 0
	v_cvt_pk_bf16_f32 v98, v98, v99
	v_fmamk_f32 v99, v163, 0x3a800000, v154
	v_rsq_f32_e32 v100, v99
	v_cvt_pk_bf16_f32 v99, v104, v105
	global_store_dwordx4 v[112:113], v[96:99], off offset:256
	s_nop 1
	v_or_b32_e32 v96, 32, v146
	v_ashrrev_i32_e32 v97, 31, v96
	v_mul_f32_e32 v98, v168, v100
	v_lshlrev_b64 v[96:97], 11, v[96:97]
	v_lshl_add_u64 v[96:97], v[156:157], 0, v[96:97]
	v_pk_mul_f32 v[94:95], v[94:95], v[98:99] op_sel_hi:[1,0]
	v_pk_mul_f32 v[92:93], v[92:93], v[98:99] op_sel_hi:[1,0]
	v_pk_mul_f32 v[100:101], v[90:91], v[98:99] op_sel_hi:[1,0]
	v_pk_mul_f32 v[90:91], v[88:89], v[98:99] op_sel_hi:[1,0]
	v_cvt_pk_bf16_f32 v88, v92, v93
	v_cvt_pk_bf16_f32 v89, v94, v95
	v_pk_mul_f32 v[86:87], v[86:87], v[98:99] op_sel_hi:[1,0]
	v_cvt_pk_bf16_f32 v90, v90, v91
	v_cvt_pk_bf16_f32 v91, v100, v101
	global_store_dwordx4 v[96:97], v[88:91], off
	v_pk_mul_f32 v[84:85], v[84:85], v[98:99] op_sel_hi:[1,0]
	s_nop 0
	v_pk_mul_f32 v[88:89], v[82:83], v[98:99] op_sel_hi:[1,0]
	v_pk_mul_f32 v[82:83], v[80:81], v[98:99] op_sel_hi:[1,0]
	v_cvt_pk_bf16_f32 v80, v84, v85
	v_cvt_pk_bf16_f32 v81, v86, v87
	s_nop 0
	v_cvt_pk_bf16_f32 v82, v82, v83
	v_fmamk_f32 v83, v164, 0x3a800000, v154
	v_rsq_f32_e32 v84, v83
	v_cvt_pk_bf16_f32 v83, v88, v89
	global_store_dwordx4 v[96:97], v[80:83], off offset:256
	s_nop 1
	v_or_b32_e32 v80, 48, v146
	v_ashrrev_i32_e32 v81, 31, v80
	v_mul_f32_e32 v82, v168, v84
	v_lshlrev_b64 v[80:81], 11, v[80:81]
	v_lshl_add_u64 v[80:81], v[156:157], 0, v[80:81]
	v_pk_mul_f32 v[78:79], v[78:79], v[82:83] op_sel_hi:[1,0]
	v_pk_mul_f32 v[76:77], v[76:77], v[82:83] op_sel_hi:[1,0]
	v_pk_mul_f32 v[84:85], v[74:75], v[82:83] op_sel_hi:[1,0]
	v_pk_mul_f32 v[74:75], v[72:73], v[82:83] op_sel_hi:[1,0]
	v_cvt_pk_bf16_f32 v72, v76, v77
	v_cvt_pk_bf16_f32 v73, v78, v79
	v_pk_mul_f32 v[68:69], v[68:69], v[82:83] op_sel_hi:[1,0]
	v_cvt_pk_bf16_f32 v74, v74, v75
	v_cvt_pk_bf16_f32 v75, v84, v85
	global_store_dwordx4 v[80:81], v[72:75], off
	v_pk_mul_f32 v[70:71], v[70:71], v[82:83] op_sel_hi:[1,0]
	s_nop 0
	v_pk_mul_f32 v[72:73], v[66:67], v[82:83] op_sel_hi:[1,0]
	v_pk_mul_f32 v[66:67], v[64:65], v[82:83] op_sel_hi:[1,0]
	v_cvt_pk_bf16_f32 v64, v68, v69
	v_fmamk_f32 v68, v159, 0x3a800000, v154
	v_rsq_f32_e32 v68, v68
	v_cvt_pk_bf16_f32 v65, v70, v71
	v_cvt_pk_bf16_f32 v66, v66, v67
	v_cvt_pk_bf16_f32 v67, v72, v73
	global_store_dwordx4 v[80:81], v[64:67], off offset:256
	s_nop 1
	v_mul_f32_e32 v64, v168, v68
	v_pk_mul_f32 v[60:61], v[60:61], v[64:65] op_sel_hi:[1,0]
	v_pk_mul_f32 v[68:69], v[58:59], v[64:65] op_sel_hi:[1,0]
	v_pk_mul_f32 v[58:59], v[56:57], v[64:65] op_sel_hi:[1,0]
	v_cvt_pk_bf16_f32 v56, v60, v61
	v_add_co_u32_e32 v60, vcc, s71, v144
	v_pk_mul_f32 v[62:63], v[62:63], v[64:65] op_sel_hi:[1,0]
	s_nop 0
	v_addc_co_u32_e32 v61, vcc, 0, v145, vcc
	v_cvt_pk_bf16_f32 v57, v62, v63
	v_pk_mul_f32 v[52:53], v[52:53], v[64:65] op_sel_hi:[1,0]
	v_cvt_pk_bf16_f32 v58, v58, v59
	v_cvt_pk_bf16_f32 v59, v68, v69
	global_store_dwordx4 v[60:61], v[56:59], off
	v_lshl_add_u64 v[66:67], v[144:145], 0, s[8:9]
	v_pk_mul_f32 v[54:55], v[54:55], v[64:65] op_sel_hi:[1,0]
	v_pk_mul_f32 v[56:57], v[50:51], v[64:65] op_sel_hi:[1,0]
	v_pk_mul_f32 v[50:51], v[48:49], v[64:65] op_sel_hi:[1,0]
	v_cvt_pk_bf16_f32 v48, v52, v53
	v_fmamk_f32 v52, v165, 0x3a800000, v154
	v_rsq_f32_e32 v52, v52
	v_cvt_pk_bf16_f32 v49, v54, v55
	v_cvt_pk_bf16_f32 v50, v50, v51
	v_cvt_pk_bf16_f32 v51, v56, v57
	global_store_dwordx4 v[66:67], v[48:51], off offset:256
	s_nop 1
	v_mul_f32_e32 v48, v168, v52
	v_pk_mul_f32 v[44:45], v[44:45], v[48:49] op_sel_hi:[1,0]
	v_pk_mul_f32 v[52:53], v[42:43], v[48:49] op_sel_hi:[1,0]
	v_pk_mul_f32 v[42:43], v[40:41], v[48:49] op_sel_hi:[1,0]
	v_cvt_pk_bf16_f32 v40, v44, v45
	v_add_co_u32_e32 v44, vcc, s72, v144
	v_pk_mul_f32 v[46:47], v[46:47], v[48:49] op_sel_hi:[1,0]
	s_nop 0
	v_addc_co_u32_e32 v45, vcc, 0, v145, vcc
	v_cvt_pk_bf16_f32 v41, v46, v47
	v_pk_mul_f32 v[36:37], v[36:37], v[48:49] op_sel_hi:[1,0]
	v_cvt_pk_bf16_f32 v42, v42, v43
	v_cvt_pk_bf16_f32 v43, v52, v53
	global_store_dwordx4 v[44:45], v[40:43], off
	v_lshl_add_u64 v[50:51], v[144:145], 0, s[18:19]
	v_pk_mul_f32 v[38:39], v[38:39], v[48:49] op_sel_hi:[1,0]
	v_pk_mul_f32 v[40:41], v[34:35], v[48:49] op_sel_hi:[1,0]
	v_pk_mul_f32 v[34:35], v[32:33], v[48:49] op_sel_hi:[1,0]
	v_cvt_pk_bf16_f32 v32, v36, v37
	v_fmamk_f32 v36, v166, 0x3a800000, v154
	v_rsq_f32_e32 v36, v36
	v_cvt_pk_bf16_f32 v33, v38, v39
	v_cvt_pk_bf16_f32 v34, v34, v35
	v_cvt_pk_bf16_f32 v35, v40, v41
	global_store_dwordx4 v[50:51], v[32:35], off offset:256
	s_nop 1
	v_mul_f32_e32 v32, v168, v36
	v_pk_mul_f32 v[28:29], v[28:29], v[32:33] op_sel_hi:[1,0]
	v_pk_mul_f32 v[36:37], v[26:27], v[32:33] op_sel_hi:[1,0]
	v_pk_mul_f32 v[26:27], v[24:25], v[32:33] op_sel_hi:[1,0]
	v_cvt_pk_bf16_f32 v24, v28, v29
	v_add_co_u32_e32 v28, vcc, s73, v144
	v_pk_mul_f32 v[30:31], v[30:31], v[32:33] op_sel_hi:[1,0]
	s_nop 0
	v_addc_co_u32_e32 v29, vcc, 0, v145, vcc
	v_cvt_pk_bf16_f32 v25, v30, v31
	v_pk_mul_f32 v[20:21], v[20:21], v[32:33] op_sel_hi:[1,0]
	v_cvt_pk_bf16_f32 v26, v26, v27
	v_cvt_pk_bf16_f32 v27, v36, v37
	global_store_dwordx4 v[28:29], v[24:27], off
	v_lshl_add_u64 v[34:35], v[144:145], 0, s[20:21]
	v_pk_mul_f32 v[22:23], v[22:23], v[32:33] op_sel_hi:[1,0]
	v_pk_mul_f32 v[24:25], v[18:19], v[32:33] op_sel_hi:[1,0]
	v_pk_mul_f32 v[18:19], v[16:17], v[32:33] op_sel_hi:[1,0]
	v_cvt_pk_bf16_f32 v16, v20, v21
	v_fmamk_f32 v20, v167, 0x3a800000, v154
	v_rsq_f32_e32 v20, v20
	v_cvt_pk_bf16_f32 v17, v22, v23
	v_cvt_pk_bf16_f32 v18, v18, v19
	v_cvt_pk_bf16_f32 v19, v24, v25
	global_store_dwordx4 v[34:35], v[16:19], off offset:256
	s_nop 1
	v_mul_f32_e32 v16, v168, v20
	v_pk_mul_f32 v[12:13], v[12:13], v[16:17] op_sel_hi:[1,0]
	v_pk_mul_f32 v[20:21], v[10:11], v[16:17] op_sel_hi:[1,0]
	v_pk_mul_f32 v[10:11], v[8:9], v[16:17] op_sel_hi:[1,0]
	v_cvt_pk_bf16_f32 v8, v12, v13
	v_add_co_u32_e32 v12, vcc, s74, v144
	v_pk_mul_f32 v[14:15], v[14:15], v[16:17] op_sel_hi:[1,0]
	s_nop 0
	v_addc_co_u32_e32 v13, vcc, 0, v145, vcc
	v_cvt_pk_bf16_f32 v9, v14, v15
	v_lshl_add_u64 v[18:19], v[144:145], 0, s[22:23]
	v_cvt_pk_bf16_f32 v10, v10, v11
	v_cvt_pk_bf16_f32 v11, v20, v21
	global_store_dwordx4 v[12:13], v[8:11], off
	s_andn2_b64 vcc, exec, s[4:5]
	s_mov_b64 s[4:5], -1
	v_pk_mul_f32 v[8:9], v[2:3], v[16:17] op_sel_hi:[1,0]
	v_pk_mul_f32 v[2:3], v[0:1], v[16:17] op_sel_hi:[1,0]
	v_pk_mul_f32 v[6:7], v[6:7], v[16:17] op_sel_hi:[1,0]
	v_pk_mul_f32 v[4:5], v[4:5], v[16:17] op_sel_hi:[1,0]
	s_nop 0
	v_cvt_pk_bf16_f32 v0, v4, v5
	v_cvt_pk_bf16_f32 v1, v6, v7
	v_cvt_pk_bf16_f32 v2, v2, v3
	v_cvt_pk_bf16_f32 v3, v8, v9
	global_store_dwordx4 v[18:19], v[0:3], off offset:256
	s_cbranch_vccnz .LBB0_589
	s_andn2_b64 vcc, exec, s[12:13]
	s_cbranch_vccnz .LBB0_588
	s_mov_b32 s99, 1
	s_branch .LBB0_588

; #define PG8_STAGE(bufoff, gbase, voff) do { _Pragma("unroll") for (int _i = 0; _i < 2; ++_i) \
;         __builtin_amdgcn_global_load_lds((const unsigned*)((const char*)(gbase) + (voff)[_i]), (PG8_LAS unsigned*)(lds + (bufoff) + ldsw + _i * 8192), 16, 0, 0); } while (0)
; #define PG8_LDA(dst, b, h) do { _Pragma("unroll") for (int m = 0; m < 4; ++m) _Pragma("unroll") for (int k = 0; k < 2; ++k) dst[m][k] = *(const PG8_LAS bf16x8*)(lds + PG8_SA(b, h) + aoff + m * 2048 + k * 1024); } while (0)
; #define PG8_LDB(dst, b, h) do { _Pragma("unroll") for (int n = 0; n < 2; ++n) _Pragma("unroll") for (int k = 0; k < 2; ++k) dst[n][k] = *(const PG8_LAS bf16x8*)(lds + PG8_SB(b, h) + boff + n * 2048 + k * 1024); } while (0)
; #define PG8_WAIT_V(n) asm volatile("s_waitcnt vmcnt(" #n ")" ::: "memory")
; #define PG8_BAR __builtin_amdgcn_s_barrier()
; template <class Epi, class Sched, bool ALIGN_EPI = false, bool SP2 = false>
; __device__ __forceinline__ void gemm_phase(PG8_LAS unsigned char* lds, const Gemm g, const Sched& S, const Epi& E) {
;     ...
;         const bool has_next = S.next(ui + 1, nxt);
;         const char* nA = has_next ? (const char*)g.A + (size_t)nxt.pm * tstep : cA; const char* nB = has_next ? (const char*)g.Bt + (size_t)nxt.pn * tstep : cB;
;         for (int t = 0; t < nt; t += 2) {
;             const bool last = (t == nt - 2);
;             if constexpr (Epi::PREFETCH) { if (t == nt - 4) E.prefetch(cur, lds + STAGE_BYTES + 1024, tid); }
;             const char* a1 = cA + (size_t)(t + 1) * kstep;
;             const char* a2 = last ? nA : cA + (size_t)(t + 2) * kstep; const char* b2 = last ? nB : cB + (size_t)(t + 2) * kstep;
;             const char* a3 = a2 + kstep; const char* b3 = b2 + kstep;
;             if (last && has_next) S.a_ready(nxt);
;             if constexpr (SP2) {
;             PG8_LDB(B0, 0, 0); PG8_LDB(B1, 0, 1); PG8_SCHED; PG8_LDA(At, 0, 0); PG8_STAGE(PG8_SA(1, 1), a1 + hstep, voffA);
;             PG8_WAIT_V(8); PG8_WAIT_L(0); PG8_BAR; PG8_MMA(0, 0, At, B0); PG8_MMA(0, 1, At, B1); PG8_BAR; PG8_SCHED;
;             PG8_LDA(At, 0, 1); PG8_STAGE(PG8_SB(0, 0), b2, voffB); PG8_STAGE(PG8_SB(0, 1), b2 + hstep, voffB); PG8_STAGE(PG8_SA(0, 0), a2, voffA);
;             PG8_WAIT_V(8); PG8_WAIT_L(0); PG8_BAR; PG8_MMA(1, 0, At, B0); PG8_MMA(1, 1, At, B1); PG8_BAR; PG8_SCHED;
;     ...
;         if constexpr (ALIGN_EPI) { if (wr == 1) PG8_BAR; }
.LBB0_1011:
	s_ashr_i32 s23, s22, 31
	s_lshl_b64 s[34:35], s[22:23], 19
	s_add_u32 s34, s48, s34
	s_addc_u32 s35, s49, s35
	s_and_b64 s[36:37], s[6:7], exec
	s_cselect_b32 s23, s35, s43
	s_cselect_b32 s39, s34, s42
	s_ashr_i32 s21, s20, 31
	s_lshl_b64 s[36:37], s[20:21], 19
	s_add_u32 s36, s50, s36
	s_addc_u32 s37, s51, s37
	s_and_b64 s[46:47], s[6:7], exec
	s_cselect_b32 s21, s37, s45
	s_cselect_b32 s65, s36, s44
	s_add_u32 s42, s42, 0x40080
	s_addc_u32 s43, s43, 0
	s_add_u32 s66, s44, 0x100
	s_addc_u32 s67, s45, 0
	s_mov_b32 s68, -2
	s_cmp_eq_u32 s99, 0
	s_cbranch_scc1 .Lnobar_3
	s_mov_b32 s99, 0
	s_barrier
.Lnobar_3:
	ds_read_b128 v[112:115], v246
	ds_read_b128 v[116:119], v246 offset:1024
	ds_read_b128 v[120:123], v246 offset:2048
	ds_read_b128 v[124:127], v246 offset:3072
	ds_read_b128 v[136:139], v247
	ds_read_b128 v[140:143], v247 offset:1024
	ds_read_b128 v[152:155], v247 offset:2048
	ds_read_b128 v[156:159], v247 offset:3072
	s_add_u32 s44, s42, 0xfffc0080
	s_addc_u32 s45, s43, -1
	s_cmp_eq_u32 s68, 12
	s_cselect_b32 s47, s23, s45
	s_cselect_b32 s46, s39, s44
	s_cselect_b32 s45, s21, s67
	s_cselect_b32 s44, s65, s66
	v_lshl_add_u64 v[206:207], s[42:43], 0, v[200:201]
	s_add_i32 m0, s41, 0xc000
	ds_read_b128 v[160:163], v248
	ds_read_b128 v[164:167], v248 offset:1024
	ds_read_b128 v[168:171], v248 offset:2048
	ds_read_b128 v[172:175], v248 offset:3072
	ds_read_b128 v[176:179], v248 offset:4096
	ds_read_b128 v[180:183], v248 offset:5120
	ds_read_b128 v[184:187], v248 offset:6144
	ds_read_b128 v[188:191], v248 offset:7168
	global_load_lds_dwordx4 v[206:207], off
	v_lshl_add_u64 v[206:207], s[42:43], 0, v[202:203]
	s_add_i32 m0, s41, 0xe000
	s_nop 0
	global_load_lds_dwordx4 v[206:207], off
	s_waitcnt vmcnt(8)
	s_waitcnt lgkmcnt(0)
	s_barrier
	s_setprio 1
	v_mfma_f32_16x16x32_bf16 v[148:151], v[112:115], v[160:163], 0
	v_mfma_f32_16x16x32_bf16 v[144:147], v[120:123], v[160:163], 0
	v_mfma_f32_16x16x32_bf16 v[108:111], v[112:115], v[168:171], 0
	v_mfma_f32_16x16x32_bf16 v[104:107], v[120:123], v[168:171], 0
	v_mfma_f32_16x16x32_bf16 v[92:95], v[112:115], v[176:179], 0
	v_mfma_f32_16x16x32_bf16 v[88:91], v[120:123], v[176:179], 0
	v_mfma_f32_16x16x32_bf16 v[76:79], v[112:115], v[184:187], 0
	v_mfma_f32_16x16x32_bf16 v[72:75], v[120:123], v[184:187], 0
	v_mfma_f32_16x16x32_bf16 v[148:151], v[116:119], v[164:167], v[148:151]
	v_mfma_f32_16x16x32_bf16 v[144:147], v[124:127], v[164:167], v[144:147]
	v_mfma_f32_16x16x32_bf16 v[108:111], v[116:119], v[172:175], v[108:111]
	v_mfma_f32_16x16x32_bf16 v[104:107], v[124:127], v[172:175], v[104:107]
	v_mfma_f32_16x16x32_bf16 v[92:95], v[116:119], v[180:183], v[92:95]
	v_mfma_f32_16x16x32_bf16 v[88:91], v[124:127], v[180:183], v[88:91]
	v_mfma_f32_16x16x32_bf16 v[76:79], v[116:119], v[188:191], v[76:79]
	v_mfma_f32_16x16x32_bf16 v[72:75], v[124:127], v[188:191], v[72:75]
	v_mfma_f32_16x16x32_bf16 v[132:135], v[136:139], v[160:163], 0
	v_mfma_f32_16x16x32_bf16 v[128:131], v[152:155], v[160:163], 0
	v_mfma_f32_16x16x32_bf16 v[100:103], v[136:139], v[168:171], 0
	v_mfma_f32_16x16x32_bf16 v[96:99], v[152:155], v[168:171], 0
	v_mfma_f32_16x16x32_bf16 v[84:87], v[136:139], v[176:179], 0
	v_mfma_f32_16x16x32_bf16 v[80:83], v[152:155], v[176:179], 0
	v_mfma_f32_16x16x32_bf16 v[68:71], v[136:139], v[184:187], 0
	v_mfma_f32_16x16x32_bf16 v[64:67], v[152:155], v[184:187], 0
	v_mfma_f32_16x16x32_bf16 v[132:135], v[140:143], v[164:167], v[132:135]
	v_mfma_f32_16x16x32_bf16 v[128:131], v[156:159], v[164:167], v[128:131]
	v_mfma_f32_16x16x32_bf16 v[100:103], v[140:143], v[172:175], v[100:103]
	v_mfma_f32_16x16x32_bf16 v[96:99], v[156:159], v[172:175], v[96:99]
	v_mfma_f32_16x16x32_bf16 v[84:87], v[140:143], v[180:183], v[84:87]
	v_mfma_f32_16x16x32_bf16 v[80:83], v[156:159], v[180:183], v[80:83]
	v_mfma_f32_16x16x32_bf16 v[68:71], v[140:143], v[188:191], v[68:71]
	v_mfma_f32_16x16x32_bf16 v[64:67], v[156:159], v[188:191], v[64:67]
	s_barrier
	s_setprio 0
	s_add_i32 s69, s63, s52
	v_lshl_add_u64 v[206:207], s[44:45], 0, v[194:195]
	s_mov_b32 m0, s69
	ds_read_b128 v[160:163], v248 offset:16384
	ds_read_b128 v[164:167], v248 offset:17408
	ds_read_b128 v[168:171], v248 offset:18432
	ds_read_b128 v[172:175], v248 offset:19456
	ds_read_b128 v[176:179], v248 offset:20480
	ds_read_b128 v[180:183], v248 offset:21504
	ds_read_b128 v[184:187], v248 offset:22528
	ds_read_b128 v[188:191], v248 offset:23552
	global_load_lds_dwordx4 v[206:207], off
	s_add_i32 m0, s69, 0x2000
	s_add_u32 s70, s44, 0x40000
	v_lshl_add_u64 v[208:209], s[44:45], 0, v[198:199]
	s_addc_u32 s71, s45, 0
	s_add_i32 s69, s64, s52
	global_load_lds_dwordx4 v[208:209], off
	v_lshl_add_u64 v[210:211], s[70:71], 0, v[194:195]
	s_mov_b32 m0, s69
	v_lshl_add_u64 v[212:213], s[46:47], 0, v[196:197]
	global_load_lds_dwordx4 v[210:211], off
	v_lshl_add_u64 v[210:211], s[70:71], 0, v[198:199]
	s_add_i32 m0, s69, 0x2000
	s_nop 0
	global_load_lds_dwordx4 v[210:211], off
	v_lshl_add_u64 v[210:211], s[46:47], 0, v[192:193]
	s_mov_b32 m0, s41
	s_nop 0
	global_load_lds_dwordx4 v[210:211], off
	s_mov_b32 m0, s53
	s_nop 0
	global_load_lds_dwordx4 v[212:213], off
	s_waitcnt vmcnt(8)
	s_waitcnt lgkmcnt(0)
	s_barrier
; #define PG8_STAGE(bufoff, gbase, voff) do { _Pragma("unroll") for (int _i = 0; _i < 2; ++_i) \
;         __builtin_amdgcn_global_load_lds((const unsigned*)((const char*)(gbase) + (voff)[_i]), (PG8_LAS unsigned*)(lds + (bufoff) + ldsw + _i * 8192), 16, 0, 0); } while (0)
; #define PG8_LDA(dst, b, h) do { _Pragma("unroll") for (int m = 0; m < 4; ++m) _Pragma("unroll") for (int k = 0; k < 2; ++k) dst[m][k] = *(const PG8_LAS bf16x8*)(lds + PG8_SA(b, h) + aoff + m * 2048 + k * 1024); } while (0)
; #define PG8_LDB(dst, b, h) do { _Pragma("unroll") for (int n = 0; n < 2; ++n) _Pragma("unroll") for (int k = 0; k < 2; ++k) dst[n][k] = *(const PG8_LAS bf16x8*)(lds + PG8_SB(b, h) + boff + n * 2048 + k * 1024); } while (0)
; #define PG8_MMA(ai, bj, At, Bt) do { __builtin_amdgcn_s_setprio(1); _Pragma("unroll") for (int m = 0; m < 4; ++m) _Pragma("unroll") for (int n = 0; n < 2; ++n) _Pragma("unroll") for (int k = 0; k < 2; ++k) \
;         acc[ai][bj][m][n] = __builtin_amdgcn_mfma_f32_16x16x32_bf16(Bt[n][k], At[m][k], acc[ai][bj][m][n], 0, 0, 0); __builtin_amdgcn_s_setprio(0); } while (0)
; #define PG8_WAIT_V(n) asm volatile("s_waitcnt vmcnt(" #n ")" ::: "memory")
; #define PG8_WAIT_L(n) asm volatile("s_waitcnt lgkmcnt(" #n ")" ::: "memory")
; #define PG8_BAR __builtin_amdgcn_s_barrier()
; #define PG8_SCHED __builtin_amdgcn_sched_barrier(0)
; template <class Epi, class Sched, bool ALIGN_EPI = false, bool SP2 = false>
; __device__ __forceinline__ void gemm_phase(PG8_LAS unsigned char* lds, const Gemm g, const Sched& S, const Epi& E) {
;     ...
;             PG8_WAIT_V(8); PG8_WAIT_L(0); PG8_BAR; PG8_MMA(1, 0, At, B0); PG8_MMA(1, 1, At, B1); PG8_BAR; PG8_SCHED;
;             PG8_LDB(B0, 1, 0); PG8_LDB(B1, 1, 1); PG8_SCHED; PG8_LDA(At, 1, 0); PG8_STAGE(PG8_SA(0, 1), a2 + hstep, voffA);
;             PG8_WAIT_V(8); PG8_WAIT_L(0); PG8_BAR; PG8_MMA(0, 0, At, B0); PG8_MMA(0, 1, At, B1); PG8_BAR; PG8_SCHED;
;             PG8_LDA(At, 1, 1); PG8_STAGE(PG8_SB(1, 0), b3, voffB); PG8_STAGE(PG8_SB(1, 1), b3 + hstep, voffB); PG8_STAGE(PG8_SA(1, 0), a3, voffA);
	s_setprio 1
	v_mfma_f32_16x16x32_bf16 v[60:63], v[112:115], v[160:163], 0
	v_mfma_f32_16x16x32_bf16 v[56:59], v[120:123], v[160:163], 0
	v_mfma_f32_16x16x32_bf16 v[44:47], v[112:115], v[168:171], 0
	v_mfma_f32_16x16x32_bf16 v[40:43], v[120:123], v[168:171], 0
	v_mfma_f32_16x16x32_bf16 v[28:31], v[112:115], v[176:179], 0
	v_mfma_f32_16x16x32_bf16 v[24:27], v[120:123], v[176:179], 0
	v_mfma_f32_16x16x32_bf16 v[12:15], v[112:115], v[184:187], 0
	v_mfma_f32_16x16x32_bf16 v[8:11], v[120:123], v[184:187], 0
	v_mfma_f32_16x16x32_bf16 v[60:63], v[116:119], v[164:167], v[60:63]
	v_mfma_f32_16x16x32_bf16 v[56:59], v[124:127], v[164:167], v[56:59]
	v_mfma_f32_16x16x32_bf16 v[44:47], v[116:119], v[172:175], v[44:47]
	v_mfma_f32_16x16x32_bf16 v[40:43], v[124:127], v[172:175], v[40:43]
	v_mfma_f32_16x16x32_bf16 v[28:31], v[116:119], v[180:183], v[28:31]
	v_mfma_f32_16x16x32_bf16 v[24:27], v[124:127], v[180:183], v[24:27]
	v_mfma_f32_16x16x32_bf16 v[12:15], v[116:119], v[188:191], v[12:15]
	v_mfma_f32_16x16x32_bf16 v[8:11], v[124:127], v[188:191], v[8:11]
	v_mfma_f32_16x16x32_bf16 v[52:55], v[136:139], v[160:163], 0
	v_mfma_f32_16x16x32_bf16 v[48:51], v[152:155], v[160:163], 0
	v_mfma_f32_16x16x32_bf16 v[36:39], v[136:139], v[168:171], 0
	v_mfma_f32_16x16x32_bf16 v[32:35], v[152:155], v[168:171], 0
	v_mfma_f32_16x16x32_bf16 v[20:23], v[136:139], v[176:179], 0
	v_mfma_f32_16x16x32_bf16 v[16:19], v[152:155], v[176:179], 0
	v_mfma_f32_16x16x32_bf16 v[4:7], v[136:139], v[184:187], 0
	v_mfma_f32_16x16x32_bf16 v[0:3], v[152:155], v[184:187], 0
	v_mfma_f32_16x16x32_bf16 v[52:55], v[140:143], v[164:167], v[52:55]
	v_mfma_f32_16x16x32_bf16 v[48:51], v[156:159], v[164:167], v[48:51]
	v_mfma_f32_16x16x32_bf16 v[36:39], v[140:143], v[172:175], v[36:39]
	v_mfma_f32_16x16x32_bf16 v[32:35], v[156:159], v[172:175], v[32:35]
	v_mfma_f32_16x16x32_bf16 v[20:23], v[140:143], v[180:183], v[20:23]
	v_mfma_f32_16x16x32_bf16 v[16:19], v[156:159], v[180:183], v[16:19]
	v_mfma_f32_16x16x32_bf16 v[4:7], v[140:143], v[188:191], v[4:7]
	v_mfma_f32_16x16x32_bf16 v[0:3], v[156:159], v[188:191], v[0:3]
	s_barrier
	s_setprio 0
	s_add_i32 s69, 0, 0x18000
	s_add_i32 s70, 0, 0x1c000
	v_add_u32_e32 v124, s69, v244
	v_add_u32_e32 v156, s70, v244
	ds_read_b128 v[112:115], v124
	ds_read_b128 v[116:119], v124 offset:1024
	ds_read_b128 v[120:123], v124 offset:2048
	ds_read_b128 v[124:127], v124 offset:3072
	ds_read_b128 v[136:139], v156
	ds_read_b128 v[140:143], v156 offset:1024
	ds_read_b128 v[152:155], v156 offset:2048
	ds_read_b128 v[156:159], v156 offset:3072
	s_add_u32 s46, s46, 0x40000
	s_addc_u32 s47, s47, 0
	s_mov_b32 m0, s54
	v_lshl_add_u64 v[214:215], s[46:47], 0, v[192:193]
	ds_read_b128 v[160:163], v248 offset:32768
	ds_read_b128 v[164:167], v248 offset:33792
	ds_read_b128 v[168:171], v248 offset:34816
	ds_read_b128 v[172:175], v248 offset:35840
	ds_read_b128 v[176:179], v248 offset:36864
	ds_read_b128 v[180:183], v248 offset:37888
	ds_read_b128 v[184:187], v248 offset:38912
	ds_read_b128 v[188:191], v248 offset:39936
	global_load_lds_dwordx4 v[214:215], off
	v_lshl_add_u64 v[214:215], s[46:47], 0, v[196:197]
	s_mov_b32 m0, s55
	s_nop 0
	global_load_lds_dwordx4 v[214:215], off
	s_waitcnt vmcnt(8)
	s_waitcnt lgkmcnt(0)
	s_barrier
	s_setprio 1
	v_mfma_f32_16x16x32_bf16 v[148:151], v[112:115], v[160:163], v[148:151]
	v_mfma_f32_16x16x32_bf16 v[144:147], v[120:123], v[160:163], v[144:147]
	v_mfma_f32_16x16x32_bf16 v[108:111], v[112:115], v[168:171], v[108:111]
	v_mfma_f32_16x16x32_bf16 v[104:107], v[120:123], v[168:171], v[104:107]
	v_mfma_f32_16x16x32_bf16 v[92:95], v[112:115], v[176:179], v[92:95]
	v_mfma_f32_16x16x32_bf16 v[88:91], v[120:123], v[176:179], v[88:91]
	v_mfma_f32_16x16x32_bf16 v[76:79], v[112:115], v[184:187], v[76:79]
	v_mfma_f32_16x16x32_bf16 v[72:75], v[120:123], v[184:187], v[72:75]
	v_mfma_f32_16x16x32_bf16 v[148:151], v[116:119], v[164:167], v[148:151]
	v_mfma_f32_16x16x32_bf16 v[144:147], v[124:127], v[164:167], v[144:147]
	v_mfma_f32_16x16x32_bf16 v[108:111], v[116:119], v[172:175], v[108:111]
	v_mfma_f32_16x16x32_bf16 v[104:107], v[124:127], v[172:175], v[104:107]
	v_mfma_f32_16x16x32_bf16 v[92:95], v[116:119], v[180:183], v[92:95]
	v_mfma_f32_16x16x32_bf16 v[88:91], v[124:127], v[180:183], v[88:91]
	v_mfma_f32_16x16x32_bf16 v[76:79], v[116:119], v[188:191], v[76:79]
	v_mfma_f32_16x16x32_bf16 v[72:75], v[124:127], v[188:191], v[72:75]
	v_mfma_f32_16x16x32_bf16 v[132:135], v[136:139], v[160:163], v[132:135]
	v_mfma_f32_16x16x32_bf16 v[128:131], v[152:155], v[160:163], v[128:131]
	v_mfma_f32_16x16x32_bf16 v[100:103], v[136:139], v[168:171], v[100:103]
	v_mfma_f32_16x16x32_bf16 v[96:99], v[152:155], v[168:171], v[96:99]
	v_mfma_f32_16x16x32_bf16 v[84:87], v[136:139], v[176:179], v[84:87]
	v_mfma_f32_16x16x32_bf16 v[80:83], v[152:155], v[176:179], v[80:83]
	v_mfma_f32_16x16x32_bf16 v[68:71], v[136:139], v[184:187], v[68:71]
	v_mfma_f32_16x16x32_bf16 v[64:67], v[152:155], v[184:187], v[64:67]
	v_mfma_f32_16x16x32_bf16 v[132:135], v[140:143], v[164:167], v[132:135]
	v_mfma_f32_16x16x32_bf16 v[128:131], v[156:159], v[164:167], v[128:131]
	v_mfma_f32_16x16x32_bf16 v[100:103], v[140:143], v[172:175], v[100:103]
	v_mfma_f32_16x16x32_bf16 v[96:99], v[156:159], v[172:175], v[96:99]
	v_mfma_f32_16x16x32_bf16 v[84:87], v[140:143], v[180:183], v[84:87]
	v_mfma_f32_16x16x32_bf16 v[80:83], v[156:159], v[180:183], v[80:83]
	v_mfma_f32_16x16x32_bf16 v[68:71], v[140:143], v[188:191], v[68:71]
	v_mfma_f32_16x16x32_bf16 v[64:67], v[156:159], v[188:191], v[64:67]
	s_barrier
; #define PG8_STAGE(bufoff, gbase, voff) do { _Pragma("unroll") for (int _i = 0; _i < 2; ++_i) \
;         __builtin_amdgcn_global_load_lds((const unsigned*)((const char*)(gbase) + (voff)[_i]), (PG8_LAS unsigned*)(lds + (bufoff) + ldsw + _i * 8192), 16, 0, 0); } while (0)
; #define PG8_LDA(dst, b, h) do { _Pragma("unroll") for (int m = 0; m < 4; ++m) _Pragma("unroll") for (int k = 0; k < 2; ++k) dst[m][k] = *(const PG8_LAS bf16x8*)(lds + PG8_SA(b, h) + aoff + m * 2048 + k * 1024); } while (0)
; #define PG8_MMA(ai, bj, At, Bt) do { __builtin_amdgcn_s_setprio(1); _Pragma("unroll") for (int m = 0; m < 4; ++m) _Pragma("unroll") for (int n = 0; n < 2; ++n) _Pragma("unroll") for (int k = 0; k < 2; ++k) \
;         acc[ai][bj][m][n] = __builtin_amdgcn_mfma_f32_16x16x32_bf16(Bt[n][k], At[m][k], acc[ai][bj][m][n], 0, 0, 0); __builtin_amdgcn_s_setprio(0); } while (0)
; #define PG8_WAIT_V(n) asm volatile("s_waitcnt vmcnt(" #n ")" ::: "memory")
; #define PG8_WAIT_L(n) asm volatile("s_waitcnt lgkmcnt(" #n ")" ::: "memory")
; #define PG8_BAR __builtin_amdgcn_s_barrier()
; #define PG8_SCHED __builtin_amdgcn_sched_barrier(0)
; template <class Epi, class Sched, bool ALIGN_EPI = false, bool SP2 = false>
; __device__ __forceinline__ void gemm_phase(PG8_LAS unsigned char* lds, const Gemm g, const Sched& S, const Epi& E) {
;     ...
;             PG8_LDA(At, 1, 1); PG8_STAGE(PG8_SB(1, 0), b3, voffB); PG8_STAGE(PG8_SB(1, 1), b3 + hstep, voffB); PG8_STAGE(PG8_SA(1, 0), a3, voffA);
;             PG8_WAIT_V(8); PG8_WAIT_L(0); PG8_BAR; PG8_MMA(1, 0, At, B0); PG8_MMA(1, 1, At, B1); PG8_BAR; PG8_SCHED;
	s_setprio 0
	s_add_i32 s46, s69, s52
	v_lshl_add_u64 v[206:207], v[206:207], 0, s[16:17]
	s_mov_b32 m0, s46
	ds_read_b128 v[160:163], v248 offset:49152
	ds_read_b128 v[164:167], v248 offset:50176
	ds_read_b128 v[168:171], v248 offset:51200
	ds_read_b128 v[172:175], v248 offset:52224
	ds_read_b128 v[176:179], v248 offset:53248
	ds_read_b128 v[180:183], v248 offset:54272
	ds_read_b128 v[184:187], v248 offset:55296
	ds_read_b128 v[188:191], v248 offset:56320
	global_load_lds_dwordx4 v[206:207], off
	s_add_i32 m0, s46, 0x2000
	s_add_u32 s44, s44, 0x40080
	v_lshl_add_u64 v[206:207], v[208:209], 0, s[16:17]
	s_addc_u32 s45, s45, 0
	s_add_i32 s46, s70, s52
	global_load_lds_dwordx4 v[206:207], off
	v_lshl_add_u64 v[206:207], s[44:45], 0, v[194:195]
	s_mov_b32 m0, s46
	s_nop 0
	global_load_lds_dwordx4 v[206:207], off
	v_lshl_add_u64 v[206:207], s[44:45], 0, v[198:199]
	s_add_i32 m0, s46, 0x2000
	s_nop 0
	global_load_lds_dwordx4 v[206:207], off
	v_lshl_add_u64 v[206:207], v[210:211], 0, s[16:17]
	s_mov_b32 m0, s57
	s_nop 0
	global_load_lds_dwordx4 v[206:207], off
	v_lshl_add_u64 v[206:207], v[212:213], 0, s[16:17]
	s_mov_b32 m0, s58
	s_nop 0
	global_load_lds_dwordx4 v[206:207], off
	s_waitcnt vmcnt(8)
	s_waitcnt lgkmcnt(0)
	s_barrier
	s_setprio 1
	v_mfma_f32_16x16x32_bf16 v[60:63], v[112:115], v[160:163], v[60:63]
	v_mfma_f32_16x16x32_bf16 v[56:59], v[120:123], v[160:163], v[56:59]
	v_mfma_f32_16x16x32_bf16 v[44:47], v[112:115], v[168:171], v[44:47]
	v_mfma_f32_16x16x32_bf16 v[40:43], v[120:123], v[168:171], v[40:43]
	v_mfma_f32_16x16x32_bf16 v[28:31], v[112:115], v[176:179], v[28:31]
	v_mfma_f32_16x16x32_bf16 v[24:27], v[120:123], v[176:179], v[24:27]
	v_mfma_f32_16x16x32_bf16 v[12:15], v[112:115], v[184:187], v[12:15]
	v_mfma_f32_16x16x32_bf16 v[8:11], v[120:123], v[184:187], v[8:11]
	v_mfma_f32_16x16x32_bf16 v[60:63], v[116:119], v[164:167], v[60:63]
	v_mfma_f32_16x16x32_bf16 v[56:59], v[124:127], v[164:167], v[56:59]
	v_mfma_f32_16x16x32_bf16 v[44:47], v[116:119], v[172:175], v[44:47]
	v_mfma_f32_16x16x32_bf16 v[40:43], v[124:127], v[172:175], v[40:43]
	v_mfma_f32_16x16x32_bf16 v[28:31], v[116:119], v[180:183], v[28:31]
	v_mfma_f32_16x16x32_bf16 v[24:27], v[124:127], v[180:183], v[24:27]
	v_mfma_f32_16x16x32_bf16 v[12:15], v[116:119], v[188:191], v[12:15]
	v_mfma_f32_16x16x32_bf16 v[8:11], v[124:127], v[188:191], v[8:11]
	v_mfma_f32_16x16x32_bf16 v[52:55], v[136:139], v[160:163], v[52:55]
	v_mfma_f32_16x16x32_bf16 v[48:51], v[152:155], v[160:163], v[48:51]
	v_mfma_f32_16x16x32_bf16 v[36:39], v[136:139], v[168:171], v[36:39]
	v_mfma_f32_16x16x32_bf16 v[32:35], v[152:155], v[168:171], v[32:35]
	v_mfma_f32_16x16x32_bf16 v[20:23], v[136:139], v[176:179], v[20:23]
	v_mfma_f32_16x16x32_bf16 v[16:19], v[152:155], v[176:179], v[16:19]
	v_mfma_f32_16x16x32_bf16 v[4:7], v[136:139], v[184:187], v[4:7]
	v_mfma_f32_16x16x32_bf16 v[0:3], v[152:155], v[184:187], v[0:3]
	v_mfma_f32_16x16x32_bf16 v[52:55], v[140:143], v[164:167], v[52:55]
	v_mfma_f32_16x16x32_bf16 v[48:51], v[156:159], v[164:167], v[48:51]
	v_mfma_f32_16x16x32_bf16 v[36:39], v[140:143], v[172:175], v[36:39]
	v_mfma_f32_16x16x32_bf16 v[32:35], v[156:159], v[172:175], v[32:35]
	v_mfma_f32_16x16x32_bf16 v[20:23], v[140:143], v[180:183], v[20:23]
	v_mfma_f32_16x16x32_bf16 v[16:19], v[156:159], v[180:183], v[16:19]
	v_mfma_f32_16x16x32_bf16 v[4:7], v[140:143], v[188:191], v[4:7]
	v_mfma_f32_16x16x32_bf16 v[0:3], v[156:159], v[188:191], v[0:3]
	s_barrier
	s_setprio 0
	s_add_i32 s68, s68, 2
	s_add_u32 s42, s42, 0x100
	s_addc_u32 s43, s43, 0
	s_add_u32 s66, s66, 0x100
	s_addc_u32 s67, s67, 0

; #define PG8_BAR __builtin_amdgcn_s_barrier()
; template <class Epi, class Sched, bool ALIGN_EPI = false, bool SP2 = false>
; __device__ __forceinline__ void gemm_phase(PG8_LAS unsigned char* lds, const Gemm g, const Sched& S, const Epi& E) {
;     ...
;         if constexpr (!Epi::AFTER_DRAIN) { E(acc, cur, wr, wc, fr, fq); S.done(cur); }
;         if (!has_next) break;
; #pragma unroll
;         for (int a = 0; a < 2; ++a)
; #pragma unroll
;             for (int b = 0; b < 2; ++b)
; #pragma unroll
;                 for (int m = 0; m < 4; ++m)
; #pragma unroll
;                     for (int n = 0; n < 2; ++n) acc[a][b][m][n] = (f32x4){0.f, 0.f, 0.f, 0.f};
;         cur = nxt; cA = nA; cB = nB; ++ui;
;         if constexpr (ALIGN_EPI) { if (wr == 1) PG8_BAR; }
.LBB0_1031:
	s_or_b64 exec, exec, s[38:39]
	s_andn2_b64 vcc, exec, s[6:7]
	s_mov_b64 s[6:7], -1
	s_cbranch_vccnz .LBB0_1004
	s_andn2_b64 vcc, exec, s[8:9]
	s_cbranch_vccnz .LBB0_1003
	s_mov_b32 s99, 1
	s_branch .LBB0_1003

; #define PG8_STAGE(bufoff, gbase, voff) do { _Pragma("unroll") for (int _i = 0; _i < 2; ++_i) \
;         __builtin_amdgcn_global_load_lds((const unsigned*)((const char*)(gbase) + (voff)[_i]), (PG8_LAS unsigned*)(lds + (bufoff) + ldsw + _i * 8192), 16, 0, 0); } while (0)
; #define PG8_LDA(dst, b, h) do { _Pragma("unroll") for (int m = 0; m < 4; ++m) _Pragma("unroll") for (int k = 0; k < 2; ++k) dst[m][k] = *(const PG8_LAS bf16x8*)(lds + PG8_SA(b, h) + aoff + m * 2048 + k * 1024); } while (0)
; #define PG8_LDB(dst, b, h) do { _Pragma("unroll") for (int n = 0; n < 2; ++n) _Pragma("unroll") for (int k = 0; k < 2; ++k) dst[n][k] = *(const PG8_LAS bf16x8*)(lds + PG8_SB(b, h) + boff + n * 2048 + k * 1024); } while (0)
; #define PG8_MMA(ai, bj, At, Bt) do { __builtin_amdgcn_s_setprio(1); _Pragma("unroll") for (int m = 0; m < 4; ++m) _Pragma("unroll") for (int n = 0; n < 2; ++n) _Pragma("unroll") for (int k = 0; k < 2; ++k) \
;         acc[ai][bj][m][n] = __builtin_amdgcn_mfma_f32_16x16x32_bf16(Bt[n][k], At[m][k], acc[ai][bj][m][n], 0, 0, 0); __builtin_amdgcn_s_setprio(0); } while (0)
; #define PG8_WAIT_V(n) asm volatile("s_waitcnt vmcnt(" #n ")" ::: "memory")
; #define PG8_WAIT_L(n) asm volatile("s_waitcnt lgkmcnt(" #n ")" ::: "memory")
; #define PG8_BAR __builtin_amdgcn_s_barrier()
; #define PG8_SCHED __builtin_amdgcn_sched_barrier(0)
; template <class Epi, class Sched, bool ALIGN_EPI = false, bool SP2 = false>
; __device__ __forceinline__ void gemm_phase(PG8_LAS unsigned char* lds, const Gemm g, const Sched& S, const Epi& E) {
;     ...
;             PG8_LDB(B0, 0, 0); PG8_LDB(B1, 0, 1); PG8_SCHED; PG8_LDA(At, 0, 0); PG8_STAGE(PG8_SA(1, 1), a1 + hstep, voffA);
;             PG8_WAIT_V(8); PG8_WAIT_L(0); PG8_BAR; PG8_MMA(0, 0, At, B0); PG8_MMA(0, 1, At, B1); PG8_BAR; PG8_SCHED;
;             PG8_LDA(At, 0, 1); PG8_STAGE(PG8_SB(0, 0), b2, voffB); PG8_STAGE(PG8_SB(0, 1), b2 + hstep, voffB); PG8_STAGE(PG8_SA(0, 0), a2, voffA);
;             PG8_WAIT_V(8); PG8_WAIT_L(0); PG8_BAR; PG8_MMA(1, 0, At, B0); PG8_MMA(1, 1, At, B1); PG8_BAR; PG8_SCHED;
;             PG8_LDB(B0, 1, 0); PG8_LDB(B1, 1, 1); PG8_SCHED; PG8_LDA(At, 1, 0); PG8_STAGE(PG8_SA(0, 1), a2 + hstep, voffA);
.Lnobar_4:
	ds_read_b128 v[154:157], v149
	ds_read_b128 v[158:161], v149 offset:1024
	ds_read_b128 v[162:165], v149 offset:2048
	ds_read_b128 v[166:169], v149 offset:3072
	ds_read_b128 v[170:173], v150
	ds_read_b128 v[174:177], v150 offset:1024
	ds_read_b128 v[178:181], v150 offset:2048
	ds_read_b128 v[182:185], v150 offset:3072
	s_add_u32 s40, s38, 0xfffc0080
	s_addc_u32 s41, s39, -1
	s_cmp_eq_u32 s68, 12
	s_cselect_b32 s43, s21, s41
	s_cselect_b32 s42, s64, s40
	s_cselect_b32 s41, s19, s67
	s_cselect_b32 s40, s65, s66
	v_lshl_add_u64 v[144:145], s[38:39], 0, v[136:137]
	s_add_i32 m0, s37, 0xc000
	ds_read_b128 v[186:189], v151
	ds_read_b128 v[190:193], v151 offset:1024
	ds_read_b128 v[194:197], v151 offset:2048
	ds_read_b128 v[198:201], v151 offset:3072
	ds_read_b128 v[202:205], v151 offset:4096
	ds_read_b128 v[206:209], v151 offset:5120
	ds_read_b128 v[210:213], v151 offset:6144
	ds_read_b128 v[214:217], v151 offset:7168
	global_load_lds_dwordx4 v[144:145], off
	v_lshl_add_u64 v[144:145], s[38:39], 0, v[138:139]
	s_add_i32 m0, s37, 0xe000
	s_nop 0
	global_load_lds_dwordx4 v[144:145], off
	s_waitcnt vmcnt(8)
	s_waitcnt lgkmcnt(0)
	s_barrier
	s_setprio 1
	v_mfma_f32_16x16x32_bf16 v[120:123], v[154:157], v[186:189], 0
	v_mfma_f32_16x16x32_bf16 v[116:119], v[162:165], v[186:189], 0
	v_mfma_f32_16x16x32_bf16 v[108:111], v[154:157], v[194:197], 0
	v_mfma_f32_16x16x32_bf16 v[100:103], v[162:165], v[194:197], 0
	v_mfma_f32_16x16x32_bf16 v[92:95], v[154:157], v[202:205], 0
	v_mfma_f32_16x16x32_bf16 v[84:87], v[162:165], v[202:205], 0
	v_mfma_f32_16x16x32_bf16 v[76:79], v[154:157], v[210:213], 0
	v_mfma_f32_16x16x32_bf16 v[68:71], v[162:165], v[210:213], 0
	v_mfma_f32_16x16x32_bf16 v[120:123], v[158:161], v[190:193], v[120:123]
	v_mfma_f32_16x16x32_bf16 v[116:119], v[166:169], v[190:193], v[116:119]
	v_mfma_f32_16x16x32_bf16 v[108:111], v[158:161], v[198:201], v[108:111]
	v_mfma_f32_16x16x32_bf16 v[100:103], v[166:169], v[198:201], v[100:103]
	v_mfma_f32_16x16x32_bf16 v[92:95], v[158:161], v[206:209], v[92:95]
	v_mfma_f32_16x16x32_bf16 v[84:87], v[166:169], v[206:209], v[84:87]
	v_mfma_f32_16x16x32_bf16 v[76:79], v[158:161], v[214:217], v[76:79]
	v_mfma_f32_16x16x32_bf16 v[68:71], v[166:169], v[214:217], v[68:71]
	v_mfma_f32_16x16x32_bf16 v[124:127], v[170:173], v[186:189], 0
	v_mfma_f32_16x16x32_bf16 v[112:115], v[178:181], v[186:189], 0
	v_mfma_f32_16x16x32_bf16 v[104:107], v[170:173], v[194:197], 0
	v_mfma_f32_16x16x32_bf16 v[96:99], v[178:181], v[194:197], 0
	v_mfma_f32_16x16x32_bf16 v[88:91], v[170:173], v[202:205], 0
	v_mfma_f32_16x16x32_bf16 v[80:83], v[178:181], v[202:205], 0
	v_mfma_f32_16x16x32_bf16 v[72:75], v[170:173], v[210:213], 0
	v_mfma_f32_16x16x32_bf16 v[64:67], v[178:181], v[210:213], 0
	v_mfma_f32_16x16x32_bf16 v[124:127], v[174:177], v[190:193], v[124:127]
	v_mfma_f32_16x16x32_bf16 v[112:115], v[182:185], v[190:193], v[112:115]
	v_mfma_f32_16x16x32_bf16 v[104:107], v[174:177], v[198:201], v[104:107]
	v_mfma_f32_16x16x32_bf16 v[96:99], v[182:185], v[198:201], v[96:99]
	v_mfma_f32_16x16x32_bf16 v[88:91], v[174:177], v[206:209], v[88:91]
	v_mfma_f32_16x16x32_bf16 v[80:83], v[182:185], v[206:209], v[80:83]
	v_mfma_f32_16x16x32_bf16 v[72:75], v[174:177], v[214:217], v[72:75]
	v_mfma_f32_16x16x32_bf16 v[64:67], v[182:185], v[214:217], v[64:67]
	s_barrier
	s_setprio 0
	s_add_i32 s69, s57, s48
	v_lshl_add_u64 v[144:145], s[40:41], 0, v[132:133]
	s_mov_b32 m0, s69
	ds_read_b128 v[186:189], v151 offset:16384
	ds_read_b128 v[190:193], v151 offset:17408
	ds_read_b128 v[194:197], v151 offset:18432
	ds_read_b128 v[198:201], v151 offset:19456
	ds_read_b128 v[202:205], v151 offset:20480
	ds_read_b128 v[206:209], v151 offset:21504
	ds_read_b128 v[210:213], v151 offset:22528
	ds_read_b128 v[214:217], v151 offset:23552
	global_load_lds_dwordx4 v[144:145], off
	s_add_i32 m0, s69, 0x2000
	s_add_u32 s70, s40, 0x40000
	v_lshl_add_u64 v[218:219], s[40:41], 0, v[128:129]
	s_addc_u32 s71, s41, 0
	s_add_i32 s69, s58, s48
	global_load_lds_dwordx4 v[218:219], off
	v_lshl_add_u64 v[220:221], s[70:71], 0, v[132:133]
	s_mov_b32 m0, s69
	v_lshl_add_u64 v[222:223], s[42:43], 0, v[130:131]
	global_load_lds_dwordx4 v[220:221], off
	v_lshl_add_u64 v[220:221], s[70:71], 0, v[128:129]
	s_add_i32 m0, s69, 0x2000
	s_nop 0
	global_load_lds_dwordx4 v[220:221], off
	v_lshl_add_u64 v[220:221], s[42:43], 0, v[134:135]
	s_mov_b32 m0, s37
	s_nop 0
	global_load_lds_dwordx4 v[220:221], off
	s_mov_b32 m0, s50
	s_nop 0
	global_load_lds_dwordx4 v[222:223], off
	s_waitcnt vmcnt(8)
	s_waitcnt lgkmcnt(0)
	s_barrier
	s_setprio 1
	v_mfma_f32_16x16x32_bf16 v[60:63], v[154:157], v[186:189], 0
	v_mfma_f32_16x16x32_bf16 v[52:55], v[162:165], v[186:189], 0
	v_mfma_f32_16x16x32_bf16 v[44:47], v[154:157], v[194:197], 0
	v_mfma_f32_16x16x32_bf16 v[36:39], v[162:165], v[194:197], 0
	v_mfma_f32_16x16x32_bf16 v[28:31], v[154:157], v[202:205], 0
	v_mfma_f32_16x16x32_bf16 v[20:23], v[162:165], v[202:205], 0
	v_mfma_f32_16x16x32_bf16 v[12:15], v[154:157], v[210:213], 0
	v_mfma_f32_16x16x32_bf16 v[4:7], v[162:165], v[210:213], 0
	v_mfma_f32_16x16x32_bf16 v[60:63], v[158:161], v[190:193], v[60:63]
	v_mfma_f32_16x16x32_bf16 v[52:55], v[166:169], v[190:193], v[52:55]
	v_mfma_f32_16x16x32_bf16 v[44:47], v[158:161], v[198:201], v[44:47]
	v_mfma_f32_16x16x32_bf16 v[36:39], v[166:169], v[198:201], v[36:39]
	v_mfma_f32_16x16x32_bf16 v[28:31], v[158:161], v[206:209], v[28:31]
	v_mfma_f32_16x16x32_bf16 v[20:23], v[166:169], v[206:209], v[20:23]
	v_mfma_f32_16x16x32_bf16 v[12:15], v[158:161], v[214:217], v[12:15]
	v_mfma_f32_16x16x32_bf16 v[4:7], v[166:169], v[214:217], v[4:7]
	v_mfma_f32_16x16x32_bf16 v[56:59], v[170:173], v[186:189], 0
	v_mfma_f32_16x16x32_bf16 v[48:51], v[178:181], v[186:189], 0
	v_mfma_f32_16x16x32_bf16 v[40:43], v[170:173], v[194:197], 0
	v_mfma_f32_16x16x32_bf16 v[32:35], v[178:181], v[194:197], 0
	v_mfma_f32_16x16x32_bf16 v[24:27], v[170:173], v[202:205], 0
	v_mfma_f32_16x16x32_bf16 v[16:19], v[178:181], v[202:205], 0
	v_mfma_f32_16x16x32_bf16 v[8:11], v[170:173], v[210:213], 0
	v_mfma_f32_16x16x32_bf16 v[0:3], v[178:181], v[210:213], 0
	v_mfma_f32_16x16x32_bf16 v[56:59], v[174:177], v[190:193], v[56:59]
	v_mfma_f32_16x16x32_bf16 v[48:51], v[182:185], v[190:193], v[48:51]
	v_mfma_f32_16x16x32_bf16 v[40:43], v[174:177], v[198:201], v[40:43]
	v_mfma_f32_16x16x32_bf16 v[32:35], v[182:185], v[198:201], v[32:35]
	v_mfma_f32_16x16x32_bf16 v[24:27], v[174:177], v[206:209], v[24:27]
	v_mfma_f32_16x16x32_bf16 v[16:19], v[182:185], v[206:209], v[16:19]
	v_mfma_f32_16x16x32_bf16 v[8:11], v[174:177], v[214:217], v[8:11]
	v_mfma_f32_16x16x32_bf16 v[0:3], v[182:185], v[214:217], v[0:3]
	s_barrier
; #define PG8_STAGE(bufoff, gbase, voff) do { _Pragma("unroll") for (int _i = 0; _i < 2; ++_i) \
;         __builtin_amdgcn_global_load_lds((const unsigned*)((const char*)(gbase) + (voff)[_i]), (PG8_LAS unsigned*)(lds + (bufoff) + ldsw + _i * 8192), 16, 0, 0); } while (0)
; #define PG8_LDA(dst, b, h) do { _Pragma("unroll") for (int m = 0; m < 4; ++m) _Pragma("unroll") for (int k = 0; k < 2; ++k) dst[m][k] = *(const PG8_LAS bf16x8*)(lds + PG8_SA(b, h) + aoff + m * 2048 + k * 1024); } while (0)
; #define PG8_LDB(dst, b, h) do { _Pragma("unroll") for (int n = 0; n < 2; ++n) _Pragma("unroll") for (int k = 0; k < 2; ++k) dst[n][k] = *(const PG8_LAS bf16x8*)(lds + PG8_SB(b, h) + boff + n * 2048 + k * 1024); } while (0)
; #define PG8_MMA(ai, bj, At, Bt) do { __builtin_amdgcn_s_setprio(1); _Pragma("unroll") for (int m = 0; m < 4; ++m) _Pragma("unroll") for (int n = 0; n < 2; ++n) _Pragma("unroll") for (int k = 0; k < 2; ++k) \
;         acc[ai][bj][m][n] = __builtin_amdgcn_mfma_f32_16x16x32_bf16(Bt[n][k], At[m][k], acc[ai][bj][m][n], 0, 0, 0); __builtin_amdgcn_s_setprio(0); } while (0)
; #define PG8_WAIT_V(n) asm volatile("s_waitcnt vmcnt(" #n ")" ::: "memory")
; #define PG8_WAIT_L(n) asm volatile("s_waitcnt lgkmcnt(" #n ")" ::: "memory")
; #define PG8_BAR __builtin_amdgcn_s_barrier()
; #define PG8_SCHED __builtin_amdgcn_sched_barrier(0)
; template <class Epi, class Sched, bool ALIGN_EPI = false, bool SP2 = false>
; __device__ __forceinline__ void gemm_phase(PG8_LAS unsigned char* lds, const Gemm g, const Sched& S, const Epi& E) {
;     ...
;             PG8_LDB(B0, 1, 0); PG8_LDB(B1, 1, 1); PG8_SCHED; PG8_LDA(At, 1, 0); PG8_STAGE(PG8_SA(0, 1), a2 + hstep, voffA);
;             PG8_WAIT_V(8); PG8_WAIT_L(0); PG8_BAR; PG8_MMA(0, 0, At, B0); PG8_MMA(0, 1, At, B1); PG8_BAR; PG8_SCHED;
;             PG8_LDA(At, 1, 1); PG8_STAGE(PG8_SB(1, 0), b3, voffB); PG8_STAGE(PG8_SB(1, 1), b3 + hstep, voffB); PG8_STAGE(PG8_SA(1, 0), a3, voffA);
;             PG8_WAIT_V(8); PG8_WAIT_L(0); PG8_BAR; PG8_MMA(1, 0, At, B0); PG8_MMA(1, 1, At, B1); PG8_BAR; PG8_SCHED;
	s_setprio 0
	s_add_i32 s69, 0, 0x18000
	v_add_u32_e32 v153, s69, v147
	s_add_i32 s70, 0, 0x1c000
	ds_read_b128 v[154:157], v153
	ds_read_b128 v[158:161], v153 offset:1024
	ds_read_b128 v[162:165], v153 offset:2048
	ds_read_b128 v[166:169], v153 offset:3072
	v_add_u32_e32 v153, s70, v147
	ds_read_b128 v[170:173], v153
	ds_read_b128 v[174:177], v153 offset:1024
	ds_read_b128 v[178:181], v153 offset:2048
	ds_read_b128 v[182:185], v153 offset:3072
	s_add_u32 s42, s42, 0x40000
	s_addc_u32 s43, s43, 0
	s_mov_b32 m0, s51
	v_lshl_add_u64 v[224:225], s[42:43], 0, v[134:135]
	ds_read_b128 v[186:189], v151 offset:32768
	ds_read_b128 v[190:193], v151 offset:33792
	ds_read_b128 v[194:197], v151 offset:34816
	ds_read_b128 v[198:201], v151 offset:35840
	ds_read_b128 v[202:205], v151 offset:36864
	ds_read_b128 v[206:209], v151 offset:37888
	ds_read_b128 v[210:213], v151 offset:38912
	ds_read_b128 v[214:217], v151 offset:39936
	global_load_lds_dwordx4 v[224:225], off
	v_lshl_add_u64 v[224:225], s[42:43], 0, v[130:131]
	s_mov_b32 m0, s52
	s_nop 0
	global_load_lds_dwordx4 v[224:225], off
	s_waitcnt vmcnt(8)
	s_waitcnt lgkmcnt(0)
	s_barrier
	s_setprio 1
	v_mfma_f32_16x16x32_bf16 v[120:123], v[154:157], v[186:189], v[120:123]
	v_mfma_f32_16x16x32_bf16 v[116:119], v[162:165], v[186:189], v[116:119]
	v_mfma_f32_16x16x32_bf16 v[108:111], v[154:157], v[194:197], v[108:111]
	v_mfma_f32_16x16x32_bf16 v[100:103], v[162:165], v[194:197], v[100:103]
	v_mfma_f32_16x16x32_bf16 v[92:95], v[154:157], v[202:205], v[92:95]
	v_mfma_f32_16x16x32_bf16 v[84:87], v[162:165], v[202:205], v[84:87]
	v_mfma_f32_16x16x32_bf16 v[76:79], v[154:157], v[210:213], v[76:79]
	v_mfma_f32_16x16x32_bf16 v[68:71], v[162:165], v[210:213], v[68:71]
	v_mfma_f32_16x16x32_bf16 v[120:123], v[158:161], v[190:193], v[120:123]
	v_mfma_f32_16x16x32_bf16 v[116:119], v[166:169], v[190:193], v[116:119]
	v_mfma_f32_16x16x32_bf16 v[108:111], v[158:161], v[198:201], v[108:111]
	v_mfma_f32_16x16x32_bf16 v[100:103], v[166:169], v[198:201], v[100:103]
	v_mfma_f32_16x16x32_bf16 v[92:95], v[158:161], v[206:209], v[92:95]
	v_mfma_f32_16x16x32_bf16 v[84:87], v[166:169], v[206:209], v[84:87]
	v_mfma_f32_16x16x32_bf16 v[76:79], v[158:161], v[214:217], v[76:79]
	v_mfma_f32_16x16x32_bf16 v[68:71], v[166:169], v[214:217], v[68:71]
	v_mfma_f32_16x16x32_bf16 v[124:127], v[170:173], v[186:189], v[124:127]
	v_mfma_f32_16x16x32_bf16 v[112:115], v[178:181], v[186:189], v[112:115]
	v_mfma_f32_16x16x32_bf16 v[104:107], v[170:173], v[194:197], v[104:107]
	v_mfma_f32_16x16x32_bf16 v[96:99], v[178:181], v[194:197], v[96:99]
	v_mfma_f32_16x16x32_bf16 v[88:91], v[170:173], v[202:205], v[88:91]
	v_mfma_f32_16x16x32_bf16 v[80:83], v[178:181], v[202:205], v[80:83]
	v_mfma_f32_16x16x32_bf16 v[72:75], v[170:173], v[210:213], v[72:75]
	v_mfma_f32_16x16x32_bf16 v[64:67], v[178:181], v[210:213], v[64:67]
	v_mfma_f32_16x16x32_bf16 v[124:127], v[174:177], v[190:193], v[124:127]
	v_mfma_f32_16x16x32_bf16 v[112:115], v[182:185], v[190:193], v[112:115]
	v_mfma_f32_16x16x32_bf16 v[104:107], v[174:177], v[198:201], v[104:107]
	v_mfma_f32_16x16x32_bf16 v[96:99], v[182:185], v[198:201], v[96:99]
	v_mfma_f32_16x16x32_bf16 v[88:91], v[174:177], v[206:209], v[88:91]
	v_mfma_f32_16x16x32_bf16 v[80:83], v[182:185], v[206:209], v[80:83]
	v_mfma_f32_16x16x32_bf16 v[72:75], v[174:177], v[214:217], v[72:75]
	v_mfma_f32_16x16x32_bf16 v[64:67], v[182:185], v[214:217], v[64:67]
	s_barrier
	s_setprio 0
	s_add_i32 s42, s69, s48
	v_lshl_add_u64 v[144:145], v[144:145], 0, s[14:15]
	s_mov_b32 m0, s42
	ds_read_b128 v[186:189], v151 offset:49152
	ds_read_b128 v[190:193], v151 offset:50176
	ds_read_b128 v[194:197], v151 offset:51200
	ds_read_b128 v[198:201], v151 offset:52224
	ds_read_b128 v[202:205], v151 offset:53248
	ds_read_b128 v[206:209], v151 offset:54272
	ds_read_b128 v[210:213], v151 offset:55296
	ds_read_b128 v[214:217], v151 offset:56320
	global_load_lds_dwordx4 v[144:145], off
	s_add_i32 m0, s42, 0x2000
	s_add_u32 s40, s40, 0x40080
	v_lshl_add_u64 v[144:145], v[218:219], 0, s[14:15]
	s_addc_u32 s41, s41, 0
	s_add_i32 s42, s70, s48
	global_load_lds_dwordx4 v[144:145], off
	v_lshl_add_u64 v[144:145], s[40:41], 0, v[132:133]
	s_mov_b32 m0, s42
	s_nop 0
	global_load_lds_dwordx4 v[144:145], off
	v_lshl_add_u64 v[144:145], s[40:41], 0, v[128:129]
	s_add_i32 m0, s42, 0x2000
	s_nop 0
	global_load_lds_dwordx4 v[144:145], off
	v_lshl_add_u64 v[144:145], v[220:221], 0, s[14:15]
	s_mov_b32 m0, s53
	s_nop 0
	global_load_lds_dwordx4 v[144:145], off
	v_lshl_add_u64 v[144:145], v[222:223], 0, s[14:15]
	s_mov_b32 m0, s54
	s_nop 0
	global_load_lds_dwordx4 v[144:145], off
	s_waitcnt vmcnt(8)
	s_waitcnt lgkmcnt(0)
	s_barrier
	s_setprio 1
	v_mfma_f32_16x16x32_bf16 v[60:63], v[154:157], v[186:189], v[60:63]
	v_mfma_f32_16x16x32_bf16 v[52:55], v[162:165], v[186:189], v[52:55]
	v_mfma_f32_16x16x32_bf16 v[44:47], v[154:157], v[194:197], v[44:47]
	v_mfma_f32_16x16x32_bf16 v[36:39], v[162:165], v[194:197], v[36:39]
	v_mfma_f32_16x16x32_bf16 v[28:31], v[154:157], v[202:205], v[28:31]
	v_mfma_f32_16x16x32_bf16 v[20:23], v[162:165], v[202:205], v[20:23]
	v_mfma_f32_16x16x32_bf16 v[12:15], v[154:157], v[210:213], v[12:15]
	v_mfma_f32_16x16x32_bf16 v[4:7], v[162:165], v[210:213], v[4:7]
	v_mfma_f32_16x16x32_bf16 v[60:63], v[158:161], v[190:193], v[60:63]
	v_mfma_f32_16x16x32_bf16 v[52:55], v[166:169], v[190:193], v[52:55]
	v_mfma_f32_16x16x32_bf16 v[44:47], v[158:161], v[198:201], v[44:47]
	v_mfma_f32_16x16x32_bf16 v[36:39], v[166:169], v[198:201], v[36:39]
	v_mfma_f32_16x16x32_bf16 v[28:31], v[158:161], v[206:209], v[28:31]
	v_mfma_f32_16x16x32_bf16 v[20:23], v[166:169], v[206:209], v[20:23]
	v_mfma_f32_16x16x32_bf16 v[12:15], v[158:161], v[214:217], v[12:15]
	v_mfma_f32_16x16x32_bf16 v[4:7], v[166:169], v[214:217], v[4:7]
	v_mfma_f32_16x16x32_bf16 v[56:59], v[170:173], v[186:189], v[56:59]
	v_mfma_f32_16x16x32_bf16 v[48:51], v[178:181], v[186:189], v[48:51]
	v_mfma_f32_16x16x32_bf16 v[40:43], v[170:173], v[194:197], v[40:43]
	v_mfma_f32_16x16x32_bf16 v[32:35], v[178:181], v[194:197], v[32:35]
	v_mfma_f32_16x16x32_bf16 v[24:27], v[170:173], v[202:205], v[24:27]
	v_mfma_f32_16x16x32_bf16 v[16:19], v[178:181], v[202:205], v[16:19]
	v_mfma_f32_16x16x32_bf16 v[8:11], v[170:173], v[210:213], v[8:11]
	v_mfma_f32_16x16x32_bf16 v[0:3], v[178:181], v[210:213], v[0:3]
	v_mfma_f32_16x16x32_bf16 v[56:59], v[174:177], v[190:193], v[56:59]
	v_mfma_f32_16x16x32_bf16 v[48:51], v[182:185], v[190:193], v[48:51]
	v_mfma_f32_16x16x32_bf16 v[40:43], v[174:177], v[198:201], v[40:43]
	v_mfma_f32_16x16x32_bf16 v[32:35], v[182:185], v[198:201], v[32:35]
	v_mfma_f32_16x16x32_bf16 v[24:27], v[174:177], v[206:209], v[24:27]
	v_mfma_f32_16x16x32_bf16 v[16:19], v[182:185], v[206:209], v[16:19]
	v_mfma_f32_16x16x32_bf16 v[8:11], v[174:177], v[214:217], v[8:11]
	v_mfma_f32_16x16x32_bf16 v[0:3], v[182:185], v[214:217], v[0:3]
	s_barrier
	s_setprio 0
	s_add_i32 s68, s68, 2
	s_add_u32 s38, s38, 0x100
	s_addc_u32 s39, s39, 0
	s_add_u32 s66, s66, 0x100
	s_addc_u32 s67, s67, 0

; __device__ __forceinline__ unsigned cvt_pk_bf16(float lo, float hi) { unsigned r; asm volatile("v_cvt_pk_bf16_f32 %0, %1, %2" : "=v"(r) : "v"(lo), "v"(hi)); return r; }
; __device__ __forceinline__ float ld_agent(const rss_t* p) { return (float)__hip_atomic_load(p, __ATOMIC_RELAXED, __HIP_MEMORY_SCOPE_AGENT) * (1.0f / 16777216.0f); }
; __device__ __forceinline__ unsigned silu_pk(f32x2 g, f32x2 u, float k1, float k2) {
;     const f32x2 t = g * k1; f32x2 ex; ex.x = __builtin_amdgcn_exp2f(t.x); ex.y = __builtin_amdgcn_exp2f(t.y);
;     const f32x2 d = ex + 1.0f; f32x2 r; r.x = __builtin_amdgcn_rcpf(d.x); r.y = __builtin_amdgcn_rcpf(d.y);
;     const f32x2 o = (g * u) * (r * k2);
;     return cvt_pk_bf16(o.x, o.y);
; }
; __device__ __forceinline__ float silu_mul(float g, float u) { return g * __builtin_amdgcn_rcpf(1.0f + __builtin_amdgcn_exp2f(-1.4426950408889634f * g)) * u; }
;     __device__ __forceinline__ void operator()(const f32x4 (&acc)[2][2][4][2], const Unit& u, int wr, int wc, int fr, int fq) const {
;         const int row0 = u.pm * BM + wr * 64 + fr, col0 = u.pn * HALF + wc * 32 + 8 * fq;
;         float ssq[2][4];
; #pragma unroll
;         for (int ai = 0; ai < 2; ++ai)
; #pragma unroll
;             for (int m = 0; m < 4; ++m) ssq[ai][m] = ld_agent(rowss + row0 + ai * HALF + m * 16);
; #pragma unroll
;         for (int ai = 0; ai < 2; ++ai)
; #pragma unroll
;             for (int m = 0; m < 4; ++m) {
;                 const int row = row0 + ai * HALF + m * 16; const float rs = __builtin_amdgcn_rsqf(ssq[ai][m] * (1.0f / 1024.0f) + 1e-6f);
;                 const float k1 = -1.4426950408889634f * rs, k2 = rs * rs;
;                 u32x4 w;
; #pragma unroll
;                 for (int n = 0; n < 2; ++n) {
;                     const f32x4 gv = acc[ai][0][m][n], uv = acc[ai][1][m][n];
;                     const unsigned lo = silu_pk((f32x2){gv[0], gv[1]}, (f32x2){uv[0], uv[1]}, k1, k2), hi = silu_pk((f32x2){gv[2], gv[3]}, (f32x2){uv[2], uv[3]}, k1, k2);
;                     if (n == 0) { w.x = lo; w.y = hi; } else { w.z = lo; w.w = hi; }
;                 }
;                 *(u32x4*)(O + (size_t)row * ldc + col0) = w;
.LBB0_1197:
	v_lshl_add_u32 v144, s36, 8, v146
	v_ashrrev_i32_e32 v145, 31, v144
	v_lshl_add_u64 v[154:155], v[144:145], 3, s[12:13]
	global_load_dwordx2 v[156:157], v[154:155], off sc1
	global_load_dwordx2 v[158:159], v[154:155], off offset:128 sc1
	global_load_dwordx2 v[160:161], v[154:155], off offset:256 sc1
	global_load_dwordx2 v[162:163], v[154:155], off offset:384 sc1
	global_load_dwordx2 v[164:165], v[154:155], off offset:1024 sc1
	global_load_dwordx2 v[166:167], v[154:155], off offset:1152 sc1
	global_load_dwordx2 v[168:169], v[154:155], off offset:1280 sc1
	s_nop 0
	global_load_dwordx2 v[154:155], v[154:155], off offset:1408 sc1
	v_pk_mul_f32 v[172:173], v[120:121], v[124:125]
	v_pk_mul_f32 v[126:127], v[122:123], v[126:127]
	v_pk_mul_f32 v[112:113], v[116:117], v[112:113]
	v_pk_mul_f32 v[114:115], v[118:119], v[114:115]
	v_lshl_or_b32 v170, s63, 7, v148
	v_ashrrev_i32_e32 v171, 31, v170
	v_pk_mul_f32 v[104:105], v[108:109], v[104:105]
	v_pk_mul_f32 v[106:107], v[110:111], v[106:107]
	v_pk_mul_f32 v[96:97], v[100:101], v[96:97]
	v_pk_mul_f32 v[98:99], v[102:103], v[98:99]
	v_pk_mul_f32 v[88:89], v[92:93], v[88:89]
	v_pk_mul_f32 v[90:91], v[94:95], v[90:91]
	v_pk_mul_f32 v[80:81], v[84:85], v[80:81]
	v_pk_mul_f32 v[82:83], v[86:87], v[82:83]
	v_pk_mul_f32 v[72:73], v[76:77], v[72:73]
	v_pk_mul_f32 v[74:75], v[78:79], v[74:75]
	v_pk_mul_f32 v[64:65], v[68:69], v[64:65]
	v_pk_mul_f32 v[66:67], v[70:71], v[66:67]
	v_pk_mul_f32 v[56:57], v[60:61], v[56:57]
	v_pk_mul_f32 v[58:59], v[62:63], v[58:59]
	v_pk_mul_f32 v[48:49], v[52:53], v[48:49]
	v_pk_mul_f32 v[50:51], v[54:55], v[50:51]
	v_pk_mul_f32 v[40:41], v[44:45], v[40:41]
	v_pk_mul_f32 v[42:43], v[46:47], v[42:43]
	v_pk_mul_f32 v[32:33], v[36:37], v[32:33]
	v_pk_mul_f32 v[34:35], v[38:39], v[34:35]
	v_pk_mul_f32 v[24:25], v[28:29], v[24:25]
	v_pk_mul_f32 v[26:27], v[30:31], v[26:27]
	v_pk_mul_f32 v[16:17], v[20:21], v[16:17]
	v_pk_mul_f32 v[18:19], v[22:23], v[18:19]
	v_pk_mul_f32 v[8:9], v[12:13], v[8:9]
	v_pk_mul_f32 v[10:11], v[14:15], v[10:11]
	v_pk_mul_f32 v[0:1], v[4:5], v[0:1]
	v_pk_mul_f32 v[2:3], v[6:7], v[2:3]
	s_andn2_b64 vcc, exec, s[4:5]
	s_mov_b64 s[4:5], -1
	s_waitcnt vmcnt(0)
	v_ffbh_u32_e32 v124, v157
	v_ffbh_u32_e32 v125, v159
	v_min_u32_e32 v178, 32, v124
	v_min_u32_e32 v179, 32, v125
	v_lshlrev_b64 v[124:125], v178, v[156:157]
	v_ffbh_u32_e32 v145, v161
	v_ffbh_u32_e32 v153, v163
	v_ffbh_u32_e32 v174, v165
	v_ffbh_u32_e32 v175, v167
	v_min_u32_e32 v124, 1, v124
	v_ffbh_u32_e32 v177, v155
	v_min_u32_e32 v145, 32, v145
	v_min_u32_e32 v153, 32, v153
	v_min_u32_e32 v174, 32, v174
	v_min_u32_e32 v175, 32, v175
	v_or_b32_e32 v124, v125, v124
	v_min_u32_e32 v177, 32, v177
	v_lshlrev_b64 v[156:157], v179, v[158:159]
	v_lshlrev_b64 v[158:159], v145, v[160:161]
	v_lshlrev_b64 v[160:161], v153, v[162:163]
	v_lshlrev_b64 v[162:163], v174, v[164:165]
	v_lshlrev_b64 v[164:165], v175, v[166:167]
	v_cvt_f32_u32_e32 v124, v124
	v_lshlrev_b64 v[154:155], v177, v[154:155]
	v_min_u32_e32 v156, 1, v156
	v_min_u32_e32 v158, 1, v158
	v_min_u32_e32 v160, 1, v160
	v_min_u32_e32 v162, 1, v162
	v_min_u32_e32 v164, 1, v164
	v_min_u32_e32 v154, 1, v154
	v_or_b32_e32 v125, v157, v156
	v_or_b32_e32 v156, v159, v158
	v_or_b32_e32 v157, v161, v160
	v_or_b32_e32 v158, v163, v162
	v_or_b32_e32 v159, v165, v164
	v_sub_u32_e32 v178, 32, v178
	v_or_b32_e32 v154, v155, v154
	v_cvt_f32_u32_e32 v155, v156
	v_cvt_f32_u32_e32 v156, v157
	v_cvt_f32_u32_e32 v157, v158
	v_cvt_f32_u32_e32 v158, v159
	v_ldexp_f32 v124, v124, v178
	v_mul_f32_e32 v124, 0x33800000, v124
	v_sub_u32_e32 v153, 32, v153
	v_sub_u32_e32 v175, 32, v175
	v_cvt_f32_u32_e32 v154, v154
	v_fmamk_f32 v124, v124, 0x3a800000, v152
	v_ffbh_u32_e32 v176, v169
	v_ldexp_f32 v153, v156, v153
	v_ldexp_f32 v156, v158, v175
	v_rsq_f32_e32 v158, v124
	v_min_u32_e32 v176, 32, v176
	v_sub_u32_e32 v145, 32, v145
	v_sub_u32_e32 v174, 32, v174
	v_lshlrev_b64 v[166:167], v176, v[168:169]
	v_sub_u32_e32 v169, 32, v177
	v_ldexp_f32 v145, v155, v145
	v_ldexp_f32 v155, v157, v174
	v_ldexp_f32 v154, v154, v169
	v_mul_f32_e32 v155, 0x33800000, v155
	v_mul_f32_e32 v124, 0x33800000, v154
	v_mul_f32_e32 v154, 0xbfb8aa3b, v158
	v_pk_mul_f32 v[122:123], v[122:123], v[154:155] op_sel_hi:[1,0]
	v_min_u32_e32 v166, 1, v166
	v_exp_f32_e32 v122, v122
	v_exp_f32_e32 v123, v123
	v_or_b32_e32 v160, v167, v166
	v_pk_mul_f32 v[120:121], v[120:121], v[154:155] op_sel_hi:[1,0]
	v_cvt_f32_u32_e32 v125, v125
	v_cvt_f32_u32_e32 v159, v160
	v_exp_f32_e32 v120, v120
	v_exp_f32_e32 v121, v121
	v_pk_add_f32 v[122:123], v[122:123], 1.0 op_sel_hi:[1,0]
	v_sub_u32_e32 v179, 32, v179
	v_rcp_f32_e32 v122, v122
	v_rcp_f32_e32 v123, v123
	v_sub_u32_e32 v168, 32, v176
	v_ldexp_f32 v125, v125, v179
	v_ldexp_f32 v157, v159, v168
	v_pk_add_f32 v[120:121], v[120:121], 1.0 op_sel_hi:[1,0]
	v_mul_f32_e32 v159, 0x33800000, v125
	v_mul_f32_e32 v160, 0x33800000, v156
	v_mul_f32_e32 v125, 0x33800000, v157
	v_pk_mul_f32 v[156:157], v[116:117], v[154:155] op_sel_hi:[1,0]
	v_rcp_f32_e32 v120, v120
	v_rcp_f32_e32 v121, v121
	v_mul_f32_e32 v158, v158, v158
	v_exp_f32_e32 v156, v156
	v_exp_f32_e32 v157, v157
	v_pk_mul_f32 v[122:123], v[158:159], v[122:123] op_sel_hi:[0,1]
	v_pk_mul_f32 v[122:123], v[126:127], v[122:123]
	v_pk_mul_f32 v[126:127], v[118:119], v[154:155] op_sel_hi:[1,0]
	v_pk_mul_f32 v[120:121], v[158:159], v[120:121] op_sel_hi:[0,1]
	v_exp_f32_e32 v126, v126
	v_exp_f32_e32 v127, v127
	v_pk_add_f32 v[156:157], v[156:157], 1.0 op_sel_hi:[1,0]
	v_pk_mul_f32 v[120:121], v[172:173], v[120:121]
	v_mul_f32_e32 v145, 0x33800000, v145
	v_cvt_pk_bf16_f32 v120, v120, v121
	v_cvt_pk_bf16_f32 v121, v122, v123
; __device__ __forceinline__ unsigned cvt_pk_bf16(float lo, float hi) { unsigned r; asm volatile("v_cvt_pk_bf16_f32 %0, %1, %2" : "=v"(r) : "v"(lo), "v"(hi)); return r; }
; __device__ __forceinline__ float ld_agent(const rss_t* p) { return (float)__hip_atomic_load(p, __ATOMIC_RELAXED, __HIP_MEMORY_SCOPE_AGENT) * (1.0f / 16777216.0f); }
; __device__ __forceinline__ unsigned silu_pk(f32x2 g, f32x2 u, float k1, float k2) {
;     const f32x2 t = g * k1; f32x2 ex; ex.x = __builtin_amdgcn_exp2f(t.x); ex.y = __builtin_amdgcn_exp2f(t.y);
;     const f32x2 d = ex + 1.0f; f32x2 r; r.x = __builtin_amdgcn_rcpf(d.x); r.y = __builtin_amdgcn_rcpf(d.y);
;     const f32x2 o = (g * u) * (r * k2);
;     return cvt_pk_bf16(o.x, o.y);
; }
; __device__ __forceinline__ float silu_mul(float g, float u) { return g * __builtin_amdgcn_rcpf(1.0f + __builtin_amdgcn_exp2f(-1.4426950408889634f * g)) * u; }
;     __device__ __forceinline__ void operator()(const f32x4 (&acc)[2][2][4][2], const Unit& u, int wr, int wc, int fr, int fq) const {
;         const int row0 = u.pm * BM + wr * 64 + fr, col0 = u.pn * HALF + wc * 32 + 8 * fq;
;         float ssq[2][4];
; #pragma unroll
;         for (int ai = 0; ai < 2; ++ai)
; #pragma unroll
;             for (int m = 0; m < 4; ++m) ssq[ai][m] = ld_agent(rowss + row0 + ai * HALF + m * 16);
; #pragma unroll
;         for (int ai = 0; ai < 2; ++ai)
; #pragma unroll
;             for (int m = 0; m < 4; ++m) {
;                 const int row = row0 + ai * HALF + m * 16; const float rs = __builtin_amdgcn_rsqf(ssq[ai][m] * (1.0f / 1024.0f) + 1e-6f);
;                 const float k1 = -1.4426950408889634f * rs, k2 = rs * rs;
;                 u32x4 w;
; #pragma unroll
;                 for (int n = 0; n < 2; ++n) {
;                     const f32x4 gv = acc[ai][0][m][n], uv = acc[ai][1][m][n];
;                     const unsigned lo = silu_pk((f32x2){gv[0], gv[1]}, (f32x2){uv[0], uv[1]}, k1, k2), hi = silu_pk((f32x2){gv[2], gv[3]}, (f32x2){uv[2], uv[3]}, k1, k2);
;                     if (n == 0) { w.x = lo; w.y = hi; } else { w.z = lo; w.w = hi; }
;                 }
;                 *(u32x4*)(O + (size_t)row * ldc + col0) = w;
	v_rcp_f32_e32 v122, v156
	v_rcp_f32_e32 v123, v157
	v_pk_add_f32 v[116:117], v[126:127], 1.0 op_sel_hi:[1,0]
	v_mul_f32_e32 v153, 0x33800000, v153
	v_rcp_f32_e32 v116, v116
	v_rcp_f32_e32 v117, v117
	v_pk_mul_f32 v[118:119], v[158:159], v[122:123] op_sel_hi:[0,1]
	v_pk_mul_f32 v[112:113], v[112:113], v[118:119]
	s_nop 0
	v_cvt_pk_bf16_f32 v122, v112, v113
	v_pk_mul_f32 v[112:113], v[158:159], v[116:117] op_sel_hi:[0,1]
	v_pk_mul_f32 v[112:113], v[114:115], v[112:113]
	v_fmamk_f32 v114, v159, 0x3a800000, v152
	v_rsq_f32_e32 v119, v114
	v_cvt_pk_bf16_f32 v123, v112, v113
	v_mov_b64_e32 v[112:113], s[8:9]
	v_mad_i64_i32 v[116:117], s[38:39], v144, s59, v[112:113]
	v_mul_f32_e32 v118, 0xbfb8aa3b, v119
	v_pk_mul_f32 v[126:127], v[108:109], v[118:119] op_sel_hi:[1,0]
	v_pk_mul_f32 v[108:109], v[110:111], v[118:119] op_sel_hi:[1,0]
	v_exp_f32_e32 v126, v126
	v_exp_f32_e32 v127, v127
	v_lshlrev_b64 v[114:115], 1, v[170:171]
	v_exp_f32_e32 v108, v108
	v_exp_f32_e32 v109, v109
	v_lshl_add_u64 v[116:117], v[116:117], 0, v[114:115]
	global_store_dwordx4 v[116:117], v[120:123], off
	v_mul_f32_e32 v116, v119, v119
	v_pk_add_f32 v[108:109], v[108:109], 1.0 op_sel_hi:[1,0]
	v_pk_add_f32 v[120:121], v[126:127], 1.0 op_sel_hi:[1,0]
	v_rcp_f32_e32 v108, v108
	v_rcp_f32_e32 v120, v120
	v_rcp_f32_e32 v121, v121
	v_rcp_f32_e32 v109, v109
	v_pk_mul_f32 v[110:111], v[116:117], v[120:121] op_sel_hi:[0,1]
	v_pk_mul_f32 v[104:105], v[104:105], v[110:111]
	v_pk_mul_f32 v[110:111], v[100:101], v[118:119] op_sel_hi:[1,0]
	v_pk_mul_f32 v[108:109], v[116:117], v[108:109] op_sel_hi:[0,1]
	v_exp_f32_e32 v110, v110
	v_exp_f32_e32 v111, v111
	v_pk_mul_f32 v[106:107], v[106:107], v[108:109]
	v_pk_mul_f32 v[108:109], v[102:103], v[118:119] op_sel_hi:[1,0]
	v_cvt_pk_bf16_f32 v104, v104, v105
	v_cvt_pk_bf16_f32 v105, v106, v107
	v_pk_add_f32 v[106:107], v[110:111], 1.0 op_sel_hi:[1,0]
	v_exp_f32_e32 v108, v108
	v_exp_f32_e32 v109, v109
	v_rcp_f32_e32 v106, v106
	v_rcp_f32_e32 v107, v107
	v_pk_add_f32 v[100:101], v[108:109], 1.0 op_sel_hi:[1,0]
	s_nop 0
	v_rcp_f32_e32 v100, v100
	v_rcp_f32_e32 v101, v101
	v_pk_mul_f32 v[102:103], v[116:117], v[106:107] op_sel_hi:[0,1]
	v_pk_mul_f32 v[96:97], v[96:97], v[102:103]
	s_nop 0
	v_cvt_pk_bf16_f32 v106, v96, v97
	v_pk_mul_f32 v[96:97], v[116:117], v[100:101] op_sel_hi:[0,1]
	v_pk_mul_f32 v[96:97], v[98:99], v[96:97]
	s_nop 0
	v_cvt_pk_bf16_f32 v107, v96, v97
	v_fmamk_f32 v96, v145, 0x3a800000, v152
	v_rsq_f32_e32 v99, v96
	v_or_b32_e32 v96, 16, v144
	v_mad_i64_i32 v[96:97], s[38:39], v96, s59, v[112:113]
	v_mul_f32_e32 v98, 0xbfb8aa3b, v99
	v_pk_mul_f32 v[100:101], v[92:93], v[98:99] op_sel_hi:[1,0]
	v_pk_mul_f32 v[92:93], v[94:95], v[98:99] op_sel_hi:[1,0]
	v_exp_f32_e32 v100, v100
	v_exp_f32_e32 v101, v101
	v_exp_f32_e32 v92, v92
	v_exp_f32_e32 v93, v93
	v_lshl_add_u64 v[96:97], v[96:97], 0, v[114:115]
	v_pk_add_f32 v[100:101], v[100:101], 1.0 op_sel_hi:[1,0]
	global_store_dwordx4 v[96:97], v[104:107], off
	v_rcp_f32_e32 v100, v100
	v_rcp_f32_e32 v101, v101
	v_pk_add_f32 v[92:93], v[92:93], 1.0 op_sel_hi:[1,0]
	v_mul_f32_e32 v96, v99, v99
	v_rcp_f32_e32 v92, v92
	v_rcp_f32_e32 v93, v93
	v_pk_mul_f32 v[94:95], v[96:97], v[100:101] op_sel_hi:[0,1]
	v_pk_mul_f32 v[88:89], v[88:89], v[94:95]
	v_pk_mul_f32 v[94:95], v[84:85], v[98:99] op_sel_hi:[1,0]
	v_pk_mul_f32 v[92:93], v[96:97], v[92:93] op_sel_hi:[0,1]
	v_exp_f32_e32 v94, v94
	v_exp_f32_e32 v95, v95
	v_pk_mul_f32 v[90:91], v[90:91], v[92:93]
	v_pk_mul_f32 v[92:93], v[86:87], v[98:99] op_sel_hi:[1,0]
	v_cvt_pk_bf16_f32 v88, v88, v89
	v_cvt_pk_bf16_f32 v89, v90, v91
	v_pk_add_f32 v[90:91], v[94:95], 1.0 op_sel_hi:[1,0]
	v_exp_f32_e32 v92, v92
	v_exp_f32_e32 v93, v93
	v_rcp_f32_e32 v90, v90
	v_rcp_f32_e32 v91, v91
	v_pk_add_f32 v[84:85], v[92:93], 1.0 op_sel_hi:[1,0]
	s_nop 0
	v_rcp_f32_e32 v84, v84
	v_rcp_f32_e32 v85, v85
	v_pk_mul_f32 v[86:87], v[96:97], v[90:91] op_sel_hi:[0,1]
	v_pk_mul_f32 v[80:81], v[80:81], v[86:87]
	s_nop 0
	v_cvt_pk_bf16_f32 v90, v80, v81
	v_pk_mul_f32 v[80:81], v[96:97], v[84:85] op_sel_hi:[0,1]
	v_pk_mul_f32 v[80:81], v[82:83], v[80:81]
	s_nop 0
	v_cvt_pk_bf16_f32 v91, v80, v81
	v_fmamk_f32 v80, v153, 0x3a800000, v152
	v_rsq_f32_e32 v83, v80
	v_or_b32_e32 v80, 32, v144
	v_mad_i64_i32 v[80:81], s[38:39], v80, s59, v[112:113]
	v_mul_f32_e32 v82, 0xbfb8aa3b, v83
	v_pk_mul_f32 v[84:85], v[76:77], v[82:83] op_sel_hi:[1,0]
	v_pk_mul_f32 v[76:77], v[78:79], v[82:83] op_sel_hi:[1,0]
	v_exp_f32_e32 v84, v84
	v_exp_f32_e32 v85, v85
	v_exp_f32_e32 v76, v76
	v_exp_f32_e32 v77, v77
	v_lshl_add_u64 v[80:81], v[80:81], 0, v[114:115]
	v_pk_add_f32 v[84:85], v[84:85], 1.0 op_sel_hi:[1,0]
	global_store_dwordx4 v[80:81], v[88:91], off
	v_rcp_f32_e32 v84, v84
	v_rcp_f32_e32 v85, v85
	v_pk_add_f32 v[76:77], v[76:77], 1.0 op_sel_hi:[1,0]
	v_mul_f32_e32 v80, v83, v83
	v_rcp_f32_e32 v76, v76
	v_rcp_f32_e32 v77, v77
	v_pk_mul_f32 v[78:79], v[80:81], v[84:85] op_sel_hi:[0,1]
	v_pk_mul_f32 v[72:73], v[72:73], v[78:79]
	v_pk_mul_f32 v[78:79], v[68:69], v[82:83] op_sel_hi:[1,0]
	v_pk_mul_f32 v[76:77], v[80:81], v[76:77] op_sel_hi:[0,1]
	v_exp_f32_e32 v78, v78
	v_exp_f32_e32 v79, v79
	v_pk_mul_f32 v[74:75], v[74:75], v[76:77]
	v_pk_mul_f32 v[76:77], v[70:71], v[82:83] op_sel_hi:[1,0]
	v_cvt_pk_bf16_f32 v72, v72, v73
	v_cvt_pk_bf16_f32 v73, v74, v75
	v_pk_add_f32 v[74:75], v[78:79], 1.0 op_sel_hi:[1,0]
	v_exp_f32_e32 v76, v76
	v_exp_f32_e32 v77, v77
	v_rcp_f32_e32 v74, v74
	v_rcp_f32_e32 v75, v75
	v_pk_add_f32 v[68:69], v[76:77], 1.0 op_sel_hi:[1,0]
	s_nop 0
	v_rcp_f32_e32 v68, v68
	v_rcp_f32_e32 v69, v69
	v_pk_mul_f32 v[70:71], v[80:81], v[74:75] op_sel_hi:[0,1]
; __device__ __forceinline__ unsigned cvt_pk_bf16(float lo, float hi) { unsigned r; asm volatile("v_cvt_pk_bf16_f32 %0, %1, %2" : "=v"(r) : "v"(lo), "v"(hi)); return r; }
; __device__ __forceinline__ float ld_agent(const rss_t* p) { return (float)__hip_atomic_load(p, __ATOMIC_RELAXED, __HIP_MEMORY_SCOPE_AGENT) * (1.0f / 16777216.0f); }
; __device__ __forceinline__ unsigned silu_pk(f32x2 g, f32x2 u, float k1, float k2) {
;     const f32x2 t = g * k1; f32x2 ex; ex.x = __builtin_amdgcn_exp2f(t.x); ex.y = __builtin_amdgcn_exp2f(t.y);
;     const f32x2 d = ex + 1.0f; f32x2 r; r.x = __builtin_amdgcn_rcpf(d.x); r.y = __builtin_amdgcn_rcpf(d.y);
;     const f32x2 o = (g * u) * (r * k2);
;     return cvt_pk_bf16(o.x, o.y);
; }
; __device__ __forceinline__ float silu_mul(float g, float u) { return g * __builtin_amdgcn_rcpf(1.0f + __builtin_amdgcn_exp2f(-1.4426950408889634f * g)) * u; }
;     __device__ __forceinline__ void operator()(const f32x4 (&acc)[2][2][4][2], const Unit& u, int wr, int wc, int fr, int fq) const {
;         const int row0 = u.pm * BM + wr * 64 + fr, col0 = u.pn * HALF + wc * 32 + 8 * fq;
;         float ssq[2][4];
; #pragma unroll
;         for (int ai = 0; ai < 2; ++ai)
; #pragma unroll
;             for (int m = 0; m < 4; ++m) ssq[ai][m] = ld_agent(rowss + row0 + ai * HALF + m * 16);
; #pragma unroll
;         for (int ai = 0; ai < 2; ++ai)
; #pragma unroll
;             for (int m = 0; m < 4; ++m) {
;                 const int row = row0 + ai * HALF + m * 16; const float rs = __builtin_amdgcn_rsqf(ssq[ai][m] * (1.0f / 1024.0f) + 1e-6f);
;                 const float k1 = -1.4426950408889634f * rs, k2 = rs * rs;
;                 u32x4 w;
; #pragma unroll
;                 for (int n = 0; n < 2; ++n) {
;                     const f32x4 gv = acc[ai][0][m][n], uv = acc[ai][1][m][n];
;                     const unsigned lo = silu_pk((f32x2){gv[0], gv[1]}, (f32x2){uv[0], uv[1]}, k1, k2), hi = silu_pk((f32x2){gv[2], gv[3]}, (f32x2){uv[2], uv[3]}, k1, k2);
;                     if (n == 0) { w.x = lo; w.y = hi; } else { w.z = lo; w.w = hi; }
;                 }
;                 *(u32x4*)(O + (size_t)row * ldc + col0) = w;
	v_pk_mul_f32 v[64:65], v[64:65], v[70:71]
	s_nop 0
	v_cvt_pk_bf16_f32 v74, v64, v65
	v_pk_mul_f32 v[64:65], v[80:81], v[68:69] op_sel_hi:[0,1]
	v_pk_mul_f32 v[64:65], v[66:67], v[64:65]
	s_nop 0
	v_cvt_pk_bf16_f32 v75, v64, v65
	v_fmamk_f32 v65, v155, 0x3a800000, v152
	v_rsq_f32_e32 v67, v65
	v_or_b32_e32 v64, 48, v144
	v_mad_i64_i32 v[64:65], s[38:39], v64, s59, v[112:113]
	v_mul_f32_e32 v66, 0xbfb8aa3b, v67
	v_pk_mul_f32 v[68:69], v[60:61], v[66:67] op_sel_hi:[1,0]
	v_pk_mul_f32 v[60:61], v[62:63], v[66:67] op_sel_hi:[1,0]
	v_exp_f32_e32 v68, v68
	v_exp_f32_e32 v69, v69
	v_exp_f32_e32 v60, v60
	v_exp_f32_e32 v61, v61
	v_lshl_add_u64 v[64:65], v[64:65], 0, v[114:115]
	v_pk_add_f32 v[68:69], v[68:69], 1.0 op_sel_hi:[1,0]
	global_store_dwordx4 v[64:65], v[72:75], off
	v_rcp_f32_e32 v68, v68
	v_rcp_f32_e32 v69, v69
	v_pk_add_f32 v[60:61], v[60:61], 1.0 op_sel_hi:[1,0]
	v_add_u32_e32 v65, 0x80, v144
	v_rcp_f32_e32 v60, v60
	v_rcp_f32_e32 v61, v61
	v_mul_f32_e32 v64, v67, v67
	v_pk_mul_f32 v[62:63], v[64:65], v[68:69] op_sel_hi:[0,1]
	v_pk_mul_f32 v[56:57], v[56:57], v[62:63]
	v_pk_mul_f32 v[62:63], v[52:53], v[66:67] op_sel_hi:[1,0]
	v_pk_mul_f32 v[60:61], v[64:65], v[60:61] op_sel_hi:[0,1]
	v_exp_f32_e32 v62, v62
	v_exp_f32_e32 v63, v63
	v_pk_mul_f32 v[58:59], v[58:59], v[60:61]
	v_pk_mul_f32 v[60:61], v[54:55], v[66:67] op_sel_hi:[1,0]
	v_cvt_pk_bf16_f32 v56, v56, v57
	v_cvt_pk_bf16_f32 v57, v58, v59
	v_pk_add_f32 v[58:59], v[62:63], 1.0 op_sel_hi:[1,0]
	v_exp_f32_e32 v60, v60
	v_exp_f32_e32 v61, v61
	v_rcp_f32_e32 v58, v58
	v_rcp_f32_e32 v59, v59
	v_pk_add_f32 v[52:53], v[60:61], 1.0 op_sel_hi:[1,0]
	s_nop 0
	v_rcp_f32_e32 v52, v52
	v_rcp_f32_e32 v53, v53
	v_pk_mul_f32 v[54:55], v[64:65], v[58:59] op_sel_hi:[0,1]
	v_pk_mul_f32 v[48:49], v[48:49], v[54:55]
	s_nop 0
	v_cvt_pk_bf16_f32 v58, v48, v49
	v_pk_mul_f32 v[48:49], v[64:65], v[52:53] op_sel_hi:[0,1]
	v_pk_mul_f32 v[48:49], v[50:51], v[48:49]
	v_fmamk_f32 v50, v160, 0x3a800000, v152
	v_rsq_f32_e32 v51, v50
	v_cvt_pk_bf16_f32 v59, v48, v49
	v_mad_i64_i32 v[48:49], s[38:39], v65, s59, v[112:113]
	v_mul_f32_e32 v50, 0xbfb8aa3b, v51
	v_pk_mul_f32 v[52:53], v[44:45], v[50:51] op_sel_hi:[1,0]
	v_pk_mul_f32 v[44:45], v[46:47], v[50:51] op_sel_hi:[1,0]
	v_exp_f32_e32 v52, v52
	v_exp_f32_e32 v53, v53
	v_exp_f32_e32 v44, v44
	v_exp_f32_e32 v45, v45
	v_lshl_add_u64 v[48:49], v[48:49], 0, v[114:115]
	v_pk_add_f32 v[52:53], v[52:53], 1.0 op_sel_hi:[1,0]
	global_store_dwordx4 v[48:49], v[56:59], off
	v_rcp_f32_e32 v52, v52
	v_rcp_f32_e32 v53, v53
	v_pk_add_f32 v[44:45], v[44:45], 1.0 op_sel_hi:[1,0]
	v_mul_f32_e32 v48, v51, v51
	v_rcp_f32_e32 v44, v44
	v_rcp_f32_e32 v45, v45
	v_pk_mul_f32 v[46:47], v[48:49], v[52:53] op_sel_hi:[0,1]
	v_pk_mul_f32 v[40:41], v[40:41], v[46:47]
	v_pk_mul_f32 v[46:47], v[36:37], v[50:51] op_sel_hi:[1,0]
	v_pk_mul_f32 v[44:45], v[48:49], v[44:45] op_sel_hi:[0,1]
	v_exp_f32_e32 v46, v46
	v_exp_f32_e32 v47, v47
	v_pk_mul_f32 v[42:43], v[42:43], v[44:45]
	v_pk_mul_f32 v[44:45], v[38:39], v[50:51] op_sel_hi:[1,0]
	v_cvt_pk_bf16_f32 v40, v40, v41
	v_cvt_pk_bf16_f32 v41, v42, v43
	v_pk_add_f32 v[42:43], v[46:47], 1.0 op_sel_hi:[1,0]
	v_exp_f32_e32 v44, v44
	v_exp_f32_e32 v45, v45
	v_rcp_f32_e32 v42, v42
	v_rcp_f32_e32 v43, v43
	v_pk_add_f32 v[36:37], v[44:45], 1.0 op_sel_hi:[1,0]
	s_nop 0
	v_rcp_f32_e32 v36, v36
	v_rcp_f32_e32 v37, v37
	v_pk_mul_f32 v[38:39], v[48:49], v[42:43] op_sel_hi:[0,1]
	v_pk_mul_f32 v[32:33], v[32:33], v[38:39]
	s_nop 0
	v_cvt_pk_bf16_f32 v42, v32, v33
	v_pk_mul_f32 v[32:33], v[48:49], v[36:37] op_sel_hi:[0,1]
	v_pk_mul_f32 v[32:33], v[34:35], v[32:33]
	s_nop 0
	v_cvt_pk_bf16_f32 v43, v32, v33
; __device__ __forceinline__ unsigned silu_pk(f32x2 g, f32x2 u, float k1, float k2) {
;     const f32x2 t = g * k1; f32x2 ex; ex.x = __builtin_amdgcn_exp2f(t.x); ex.y = __builtin_amdgcn_exp2f(t.y);
;     const f32x2 d = ex + 1.0f; f32x2 r; r.x = __builtin_amdgcn_rcpf(d.x); r.y = __builtin_amdgcn_rcpf(d.y);
;     const f32x2 o = (g * u) * (r * k2);
;     return cvt_pk_bf16(o.x, o.y);
; }
; __device__ __forceinline__ float silu_mul(float g, float u) { return g * __builtin_amdgcn_rcpf(1.0f + __builtin_amdgcn_exp2f(-1.4426950408889634f * g)) * u; }
;     __device__ __forceinline__ void operator()(const f32x4 (&acc)[2][2][4][2], const Unit& u, int wr, int wc, int fr, int fq) const {
;         const int row0 = u.pm * BM + wr * 64 + fr, col0 = u.pn * HALF + wc * 32 + 8 * fq;
;         float ssq[2][4];
; #pragma unroll
;         for (int ai = 0; ai < 2; ++ai)
; #pragma unroll
;             for (int m = 0; m < 4; ++m) ssq[ai][m] = ld_agent(rowss + row0 + ai * HALF + m * 16);
; #pragma unroll
;         for (int ai = 0; ai < 2; ++ai)
; #pragma unroll
;             for (int m = 0; m < 4; ++m) {
;                 const int row = row0 + ai * HALF + m * 16; const float rs = __builtin_amdgcn_rsqf(ssq[ai][m] * (1.0f / 1024.0f) + 1e-6f);
;                 const float k1 = -1.4426950408889634f * rs, k2 = rs * rs;
;                 u32x4 w;
; #pragma unroll
;                 for (int n = 0; n < 2; ++n) {
;                     const f32x4 gv = acc[ai][0][m][n], uv = acc[ai][1][m][n];
;                     const unsigned lo = silu_pk((f32x2){gv[0], gv[1]}, (f32x2){uv[0], uv[1]}, k1, k2), hi = silu_pk((f32x2){gv[2], gv[3]}, (f32x2){uv[2], uv[3]}, k1, k2);
;                     if (n == 0) { w.x = lo; w.y = hi; } else { w.z = lo; w.w = hi; }
;                 }
;                 *(u32x4*)(O + (size_t)row * ldc + col0) = w;
; template <class Epi, class Sched, bool ALIGN_EPI = false, bool SP2 = false>
; __device__ __forceinline__ void gemm_phase(PG8_LAS unsigned char* lds, const Gemm g, const Sched& S, const Epi& E) {
;     ...
;         if constexpr (!Epi::AFTER_DRAIN) { E(acc, cur, wr, wc, fr, fq); S.done(cur); }
;         if (!has_next) break;
; #pragma unroll
;         for (int a = 0; a < 2; ++a)
; #pragma unroll
;             for (int b = 0; b < 2; ++b)
; #pragma unroll
;                 for (int m = 0; m < 4; ++m)
; #pragma unroll
	v_fmamk_f32 v32, v125, 0x3a800000, v152
	v_rsq_f32_e32 v35, v32
	v_add_u32_e32 v32, 0x90, v144
	v_mad_i64_i32 v[32:33], s[38:39], v32, s59, v[112:113]
	v_mul_f32_e32 v34, 0xbfb8aa3b, v35
	v_pk_mul_f32 v[36:37], v[28:29], v[34:35] op_sel_hi:[1,0]
	v_pk_mul_f32 v[28:29], v[30:31], v[34:35] op_sel_hi:[1,0]
	v_exp_f32_e32 v36, v36
	v_exp_f32_e32 v37, v37
	v_exp_f32_e32 v28, v28
	v_exp_f32_e32 v29, v29
	v_lshl_add_u64 v[32:33], v[32:33], 0, v[114:115]
	v_pk_add_f32 v[36:37], v[36:37], 1.0 op_sel_hi:[1,0]
	global_store_dwordx4 v[32:33], v[40:43], off
	v_rcp_f32_e32 v36, v36
	v_rcp_f32_e32 v37, v37
	v_pk_add_f32 v[28:29], v[28:29], 1.0 op_sel_hi:[1,0]
	v_mul_f32_e32 v32, v35, v35
	v_rcp_f32_e32 v28, v28
	v_rcp_f32_e32 v29, v29
	v_pk_mul_f32 v[30:31], v[32:33], v[36:37] op_sel_hi:[0,1]
	v_pk_mul_f32 v[24:25], v[24:25], v[30:31]
	v_pk_mul_f32 v[30:31], v[20:21], v[34:35] op_sel_hi:[1,0]
	v_pk_mul_f32 v[28:29], v[32:33], v[28:29] op_sel_hi:[0,1]
	v_exp_f32_e32 v30, v30
	v_exp_f32_e32 v31, v31
	v_pk_mul_f32 v[26:27], v[26:27], v[28:29]
	v_pk_mul_f32 v[28:29], v[22:23], v[34:35] op_sel_hi:[1,0]
	v_cvt_pk_bf16_f32 v24, v24, v25
	v_cvt_pk_bf16_f32 v25, v26, v27
	v_pk_add_f32 v[26:27], v[30:31], 1.0 op_sel_hi:[1,0]
	v_exp_f32_e32 v28, v28
	v_exp_f32_e32 v29, v29
	v_rcp_f32_e32 v26, v26
	v_rcp_f32_e32 v27, v27
	v_pk_add_f32 v[20:21], v[28:29], 1.0 op_sel_hi:[1,0]
	s_nop 0
	v_rcp_f32_e32 v20, v20
	v_rcp_f32_e32 v21, v21
	v_pk_mul_f32 v[22:23], v[32:33], v[26:27] op_sel_hi:[0,1]
	v_pk_mul_f32 v[16:17], v[16:17], v[22:23]
	s_nop 0
	v_cvt_pk_bf16_f32 v26, v16, v17
	v_pk_mul_f32 v[16:17], v[32:33], v[20:21] op_sel_hi:[0,1]
	v_pk_mul_f32 v[16:17], v[18:19], v[16:17]
	s_nop 0
	v_cvt_pk_bf16_f32 v27, v16, v17
	v_fmamk_f32 v16, v124, 0x3a800000, v152
	v_rsq_f32_e32 v19, v16
	v_add_u32_e32 v16, 0xa0, v144
	v_mad_i64_i32 v[16:17], s[38:39], v16, s59, v[112:113]
	v_mul_f32_e32 v18, 0xbfb8aa3b, v19
	v_pk_mul_f32 v[20:21], v[12:13], v[18:19] op_sel_hi:[1,0]
	v_pk_mul_f32 v[12:13], v[14:15], v[18:19] op_sel_hi:[1,0]
	v_exp_f32_e32 v20, v20
	v_exp_f32_e32 v21, v21
	v_exp_f32_e32 v12, v12
	v_exp_f32_e32 v13, v13
	v_lshl_add_u64 v[16:17], v[16:17], 0, v[114:115]
	v_pk_add_f32 v[20:21], v[20:21], 1.0 op_sel_hi:[1,0]
	global_store_dwordx4 v[16:17], v[24:27], off
	v_rcp_f32_e32 v20, v20
	v_rcp_f32_e32 v21, v21
	v_pk_add_f32 v[12:13], v[12:13], 1.0 op_sel_hi:[1,0]
	v_mul_f32_e32 v16, v19, v19
	v_rcp_f32_e32 v12, v12
	v_rcp_f32_e32 v13, v13
	v_pk_mul_f32 v[14:15], v[16:17], v[20:21] op_sel_hi:[0,1]
	v_pk_mul_f32 v[8:9], v[8:9], v[14:15]
	v_pk_mul_f32 v[14:15], v[4:5], v[18:19] op_sel_hi:[1,0]
	v_pk_mul_f32 v[12:13], v[16:17], v[12:13] op_sel_hi:[0,1]
	v_exp_f32_e32 v14, v14
	v_exp_f32_e32 v15, v15
	v_pk_mul_f32 v[10:11], v[10:11], v[12:13]
	v_pk_mul_f32 v[12:13], v[6:7], v[18:19] op_sel_hi:[1,0]
	v_cvt_pk_bf16_f32 v8, v8, v9
	v_cvt_pk_bf16_f32 v9, v10, v11
	v_pk_add_f32 v[10:11], v[14:15], 1.0 op_sel_hi:[1,0]
	v_exp_f32_e32 v12, v12
	v_exp_f32_e32 v13, v13
	v_rcp_f32_e32 v10, v10
	v_rcp_f32_e32 v11, v11
	v_pk_add_f32 v[4:5], v[12:13], 1.0 op_sel_hi:[1,0]
	s_nop 0
	v_rcp_f32_e32 v4, v4
	v_rcp_f32_e32 v5, v5
	v_pk_mul_f32 v[6:7], v[16:17], v[10:11] op_sel_hi:[0,1]
	v_pk_mul_f32 v[0:1], v[0:1], v[6:7]
	s_nop 0
	v_cvt_pk_bf16_f32 v10, v0, v1
	v_pk_mul_f32 v[0:1], v[16:17], v[4:5] op_sel_hi:[0,1]
	v_pk_mul_f32 v[0:1], v[2:3], v[0:1]
	s_nop 0
	v_cvt_pk_bf16_f32 v11, v0, v1
	v_add_u32_e32 v0, 0xb0, v144
	v_mad_i64_i32 v[0:1], s[38:39], v0, s59, v[112:113]
	v_lshl_add_u64 v[0:1], v[0:1], 0, v[114:115]
	global_store_dwordx4 v[0:1], v[8:11], off
	s_cbranch_vccnz .LBB0_1190
	s_andn2_b64 vcc, exec, s[6:7]
	s_cbranch_vccnz .LBB0_1189
	s_mov_b32 s99, 1
	s_branch .LBB0_1189

; #define PG8_STAGE(bufoff, gbase, voff) do { _Pragma("unroll") for (int _i = 0; _i < 2; ++_i) \
;         __builtin_amdgcn_global_load_lds((const unsigned*)((const char*)(gbase) + (voff)[_i]), (PG8_LAS unsigned*)(lds + (bufoff) + ldsw + _i * 8192), 16, 0, 0); } while (0)
; #define PG8_LDA(dst, b, h) do { _Pragma("unroll") for (int m = 0; m < 4; ++m) _Pragma("unroll") for (int k = 0; k < 2; ++k) dst[m][k] = *(const PG8_LAS bf16x8*)(lds + PG8_SA(b, h) + aoff + m * 2048 + k * 1024); } while (0)
; #define PG8_LDB(dst, b, h) do { _Pragma("unroll") for (int n = 0; n < 2; ++n) _Pragma("unroll") for (int k = 0; k < 2; ++k) dst[n][k] = *(const PG8_LAS bf16x8*)(lds + PG8_SB(b, h) + boff + n * 2048 + k * 1024); } while (0)
; #define PG8_MMA(ai, bj, At, Bt) do { __builtin_amdgcn_s_setprio(1); _Pragma("unroll") for (int m = 0; m < 4; ++m) _Pragma("unroll") for (int n = 0; n < 2; ++n) _Pragma("unroll") for (int k = 0; k < 2; ++k) \
;         acc[ai][bj][m][n] = __builtin_amdgcn_mfma_f32_16x16x32_bf16(Bt[n][k], At[m][k], acc[ai][bj][m][n], 0, 0, 0); __builtin_amdgcn_s_setprio(0); } while (0)
; #define PG8_WAIT_V(n) asm volatile("s_waitcnt vmcnt(" #n ")" ::: "memory")
; #define PG8_WAIT_L(n) asm volatile("s_waitcnt lgkmcnt(" #n ")" ::: "memory")
; #define PG8_BAR __builtin_amdgcn_s_barrier()
; #define PG8_SCHED __builtin_amdgcn_sched_barrier(0)
; template <class Epi, class Sched, bool ALIGN_EPI = false, bool SP2 = false>
; __device__ __forceinline__ void gemm_phase(PG8_LAS unsigned char* lds, const Gemm g, const Sched& S, const Epi& E) {
;     ...
;             PG8_LDB(B0, 0, 0); PG8_LDB(B1, 0, 1); PG8_SCHED; PG8_LDA(At, 0, 0); PG8_STAGE(PG8_SA(1, 1), a1 + hstep, voffA);
;             PG8_WAIT_V(8); PG8_WAIT_L(0); PG8_BAR; PG8_MMA(0, 0, At, B0); PG8_MMA(0, 1, At, B1); PG8_BAR; PG8_SCHED;
;             PG8_LDA(At, 0, 1); PG8_STAGE(PG8_SB(0, 0), b2, voffB); PG8_STAGE(PG8_SB(0, 1), b2 + hstep, voffB); PG8_STAGE(PG8_SA(0, 0), a2, voffA);
;             PG8_WAIT_V(8); PG8_WAIT_L(0); PG8_BAR; PG8_MMA(1, 0, At, B0); PG8_MMA(1, 1, At, B1); PG8_BAR; PG8_SCHED;
;             PG8_LDB(B0, 1, 0); PG8_LDB(B1, 1, 1); PG8_SCHED; PG8_LDA(At, 1, 0); PG8_STAGE(PG8_SA(0, 1), a2 + hstep, voffA);
.Lnobar_8:
	ds_read_b128 v[144:147], v151
	ds_read_b128 v[156:159], v151 offset:1024
	ds_read_b128 v[160:163], v151 offset:2048
	ds_read_b128 v[164:167], v151 offset:3072
	ds_read_b128 v[168:171], v152
	ds_read_b128 v[172:175], v152 offset:1024
	ds_read_b128 v[176:179], v152 offset:2048
	ds_read_b128 v[180:183], v152 offset:3072
	s_add_u32 s40, s38, 0xfffc0080
	s_addc_u32 s41, s39, -1
	s_cmp_eq_u32 s68, 12
	s_cselect_b32 s43, s21, s41
	s_cselect_b32 s42, s64, s40
	s_cselect_b32 s41, s19, s67
	s_cselect_b32 s40, s65, s66
	v_lshl_add_u64 v[216:217], s[38:39], 0, v[136:137]
	s_add_i32 m0, s37, 0xc000
	ds_read_b128 v[184:187], v153
	ds_read_b128 v[188:191], v153 offset:1024
	ds_read_b128 v[192:195], v153 offset:2048
	ds_read_b128 v[196:199], v153 offset:3072
	ds_read_b128 v[200:203], v153 offset:4096
	ds_read_b128 v[204:207], v153 offset:5120
	ds_read_b128 v[208:211], v153 offset:6144
	ds_read_b128 v[212:215], v153 offset:7168
	global_load_lds_dwordx4 v[216:217], off
	v_lshl_add_u64 v[216:217], s[38:39], 0, v[138:139]
	s_add_i32 m0, s37, 0xe000
	s_nop 0
	global_load_lds_dwordx4 v[216:217], off
	s_waitcnt vmcnt(8)
	s_waitcnt lgkmcnt(0)
	s_barrier
	s_setprio 1
	v_mfma_f32_16x16x32_bf16 v[124:127], v[144:147], v[184:187], 0
	v_mfma_f32_16x16x32_bf16 v[120:123], v[160:163], v[184:187], 0
	v_mfma_f32_16x16x32_bf16 v[108:111], v[144:147], v[192:195], 0
	v_mfma_f32_16x16x32_bf16 v[104:107], v[160:163], v[192:195], 0
	v_mfma_f32_16x16x32_bf16 v[92:95], v[144:147], v[200:203], 0
	v_mfma_f32_16x16x32_bf16 v[88:91], v[160:163], v[200:203], 0
	v_mfma_f32_16x16x32_bf16 v[76:79], v[144:147], v[208:211], 0
	v_mfma_f32_16x16x32_bf16 v[72:75], v[160:163], v[208:211], 0
	v_mfma_f32_16x16x32_bf16 v[124:127], v[156:159], v[188:191], v[124:127]
	v_mfma_f32_16x16x32_bf16 v[120:123], v[164:167], v[188:191], v[120:123]
	v_mfma_f32_16x16x32_bf16 v[108:111], v[156:159], v[196:199], v[108:111]
	v_mfma_f32_16x16x32_bf16 v[104:107], v[164:167], v[196:199], v[104:107]
	v_mfma_f32_16x16x32_bf16 v[92:95], v[156:159], v[204:207], v[92:95]
	v_mfma_f32_16x16x32_bf16 v[88:91], v[164:167], v[204:207], v[88:91]
	v_mfma_f32_16x16x32_bf16 v[76:79], v[156:159], v[212:215], v[76:79]
	v_mfma_f32_16x16x32_bf16 v[72:75], v[164:167], v[212:215], v[72:75]
	v_mfma_f32_16x16x32_bf16 v[116:119], v[168:171], v[184:187], 0
	v_mfma_f32_16x16x32_bf16 v[112:115], v[176:179], v[184:187], 0
	v_mfma_f32_16x16x32_bf16 v[100:103], v[168:171], v[192:195], 0
	v_mfma_f32_16x16x32_bf16 v[96:99], v[176:179], v[192:195], 0
	v_mfma_f32_16x16x32_bf16 v[84:87], v[168:171], v[200:203], 0
	v_mfma_f32_16x16x32_bf16 v[80:83], v[176:179], v[200:203], 0
	v_mfma_f32_16x16x32_bf16 v[68:71], v[168:171], v[208:211], 0
	v_mfma_f32_16x16x32_bf16 v[64:67], v[176:179], v[208:211], 0
	v_mfma_f32_16x16x32_bf16 v[116:119], v[172:175], v[188:191], v[116:119]
	v_mfma_f32_16x16x32_bf16 v[112:115], v[180:183], v[188:191], v[112:115]
	v_mfma_f32_16x16x32_bf16 v[100:103], v[172:175], v[196:199], v[100:103]
	v_mfma_f32_16x16x32_bf16 v[96:99], v[180:183], v[196:199], v[96:99]
	v_mfma_f32_16x16x32_bf16 v[84:87], v[172:175], v[204:207], v[84:87]
	v_mfma_f32_16x16x32_bf16 v[80:83], v[180:183], v[204:207], v[80:83]
	v_mfma_f32_16x16x32_bf16 v[68:71], v[172:175], v[212:215], v[68:71]
	v_mfma_f32_16x16x32_bf16 v[64:67], v[180:183], v[212:215], v[64:67]
	s_barrier
	s_setprio 0
	s_add_i32 s69, s57, s48
	v_lshl_add_u64 v[216:217], s[40:41], 0, v[132:133]
	s_mov_b32 m0, s69
	ds_read_b128 v[184:187], v153 offset:16384
	ds_read_b128 v[188:191], v153 offset:17408
	ds_read_b128 v[192:195], v153 offset:18432
	ds_read_b128 v[196:199], v153 offset:19456
	ds_read_b128 v[200:203], v153 offset:20480
	ds_read_b128 v[204:207], v153 offset:21504
	ds_read_b128 v[208:211], v153 offset:22528
	ds_read_b128 v[212:215], v153 offset:23552
	global_load_lds_dwordx4 v[216:217], off
	s_add_i32 m0, s69, 0x2000
	s_add_u32 s70, s40, 0x40000
	v_lshl_add_u64 v[218:219], s[40:41], 0, v[128:129]
	s_addc_u32 s71, s41, 0
	s_add_i32 s69, s58, s48
	global_load_lds_dwordx4 v[218:219], off
	v_lshl_add_u64 v[220:221], s[70:71], 0, v[132:133]
	s_mov_b32 m0, s69
	v_lshl_add_u64 v[222:223], s[42:43], 0, v[130:131]
	global_load_lds_dwordx4 v[220:221], off
	v_lshl_add_u64 v[220:221], s[70:71], 0, v[128:129]
	s_add_i32 m0, s69, 0x2000
	s_nop 0
	global_load_lds_dwordx4 v[220:221], off
	v_lshl_add_u64 v[220:221], s[42:43], 0, v[134:135]
	s_mov_b32 m0, s37
	s_nop 0
	global_load_lds_dwordx4 v[220:221], off
	s_mov_b32 m0, s50
	s_nop 0
	global_load_lds_dwordx4 v[222:223], off
	s_waitcnt vmcnt(8)
	s_waitcnt lgkmcnt(0)
	s_barrier
	s_setprio 1
	v_mfma_f32_16x16x32_bf16 v[60:63], v[144:147], v[184:187], 0
	v_mfma_f32_16x16x32_bf16 v[56:59], v[160:163], v[184:187], 0
	v_mfma_f32_16x16x32_bf16 v[44:47], v[144:147], v[192:195], 0
	v_mfma_f32_16x16x32_bf16 v[40:43], v[160:163], v[192:195], 0
	v_mfma_f32_16x16x32_bf16 v[28:31], v[144:147], v[200:203], 0
	v_mfma_f32_16x16x32_bf16 v[24:27], v[160:163], v[200:203], 0
	v_mfma_f32_16x16x32_bf16 v[12:15], v[144:147], v[208:211], 0
	v_mfma_f32_16x16x32_bf16 v[8:11], v[160:163], v[208:211], 0
	v_mfma_f32_16x16x32_bf16 v[60:63], v[156:159], v[188:191], v[60:63]
	v_mfma_f32_16x16x32_bf16 v[56:59], v[164:167], v[188:191], v[56:59]
	v_mfma_f32_16x16x32_bf16 v[44:47], v[156:159], v[196:199], v[44:47]
	v_mfma_f32_16x16x32_bf16 v[40:43], v[164:167], v[196:199], v[40:43]
	v_mfma_f32_16x16x32_bf16 v[28:31], v[156:159], v[204:207], v[28:31]
	v_mfma_f32_16x16x32_bf16 v[24:27], v[164:167], v[204:207], v[24:27]
	v_mfma_f32_16x16x32_bf16 v[12:15], v[156:159], v[212:215], v[12:15]
	v_mfma_f32_16x16x32_bf16 v[8:11], v[164:167], v[212:215], v[8:11]
	v_mfma_f32_16x16x32_bf16 v[52:55], v[168:171], v[184:187], 0
	v_mfma_f32_16x16x32_bf16 v[48:51], v[176:179], v[184:187], 0
	v_mfma_f32_16x16x32_bf16 v[36:39], v[168:171], v[192:195], 0
	v_mfma_f32_16x16x32_bf16 v[32:35], v[176:179], v[192:195], 0
	v_mfma_f32_16x16x32_bf16 v[20:23], v[168:171], v[200:203], 0
	v_mfma_f32_16x16x32_bf16 v[16:19], v[176:179], v[200:203], 0
	v_mfma_f32_16x16x32_bf16 v[4:7], v[168:171], v[208:211], 0
	v_mfma_f32_16x16x32_bf16 v[0:3], v[176:179], v[208:211], 0
	v_mfma_f32_16x16x32_bf16 v[52:55], v[172:175], v[188:191], v[52:55]
	v_mfma_f32_16x16x32_bf16 v[48:51], v[180:183], v[188:191], v[48:51]
	v_mfma_f32_16x16x32_bf16 v[36:39], v[172:175], v[196:199], v[36:39]
	v_mfma_f32_16x16x32_bf16 v[32:35], v[180:183], v[196:199], v[32:35]
	v_mfma_f32_16x16x32_bf16 v[20:23], v[172:175], v[204:207], v[20:23]
	v_mfma_f32_16x16x32_bf16 v[16:19], v[180:183], v[204:207], v[16:19]
	v_mfma_f32_16x16x32_bf16 v[4:7], v[172:175], v[212:215], v[4:7]
	v_mfma_f32_16x16x32_bf16 v[0:3], v[180:183], v[212:215], v[0:3]
	s_barrier
; #define PG8_STAGE(bufoff, gbase, voff) do { _Pragma("unroll") for (int _i = 0; _i < 2; ++_i) \
;         __builtin_amdgcn_global_load_lds((const unsigned*)((const char*)(gbase) + (voff)[_i]), (PG8_LAS unsigned*)(lds + (bufoff) + ldsw + _i * 8192), 16, 0, 0); } while (0)
; #define PG8_LDA(dst, b, h) do { _Pragma("unroll") for (int m = 0; m < 4; ++m) _Pragma("unroll") for (int k = 0; k < 2; ++k) dst[m][k] = *(const PG8_LAS bf16x8*)(lds + PG8_SA(b, h) + aoff + m * 2048 + k * 1024); } while (0)
; #define PG8_LDB(dst, b, h) do { _Pragma("unroll") for (int n = 0; n < 2; ++n) _Pragma("unroll") for (int k = 0; k < 2; ++k) dst[n][k] = *(const PG8_LAS bf16x8*)(lds + PG8_SB(b, h) + boff + n * 2048 + k * 1024); } while (0)
; #define PG8_MMA(ai, bj, At, Bt) do { __builtin_amdgcn_s_setprio(1); _Pragma("unroll") for (int m = 0; m < 4; ++m) _Pragma("unroll") for (int n = 0; n < 2; ++n) _Pragma("unroll") for (int k = 0; k < 2; ++k) \
;         acc[ai][bj][m][n] = __builtin_amdgcn_mfma_f32_16x16x32_bf16(Bt[n][k], At[m][k], acc[ai][bj][m][n], 0, 0, 0); __builtin_amdgcn_s_setprio(0); } while (0)
; #define PG8_WAIT_V(n) asm volatile("s_waitcnt vmcnt(" #n ")" ::: "memory")
; #define PG8_WAIT_L(n) asm volatile("s_waitcnt lgkmcnt(" #n ")" ::: "memory")
; #define PG8_BAR __builtin_amdgcn_s_barrier()
; #define PG8_SCHED __builtin_amdgcn_sched_barrier(0)
; template <class Epi, class Sched, bool ALIGN_EPI = false, bool SP2 = false>
; __device__ __forceinline__ void gemm_phase(PG8_LAS unsigned char* lds, const Gemm g, const Sched& S, const Epi& E) {
;     ...
;             PG8_LDB(B0, 1, 0); PG8_LDB(B1, 1, 1); PG8_SCHED; PG8_LDA(At, 1, 0); PG8_STAGE(PG8_SA(0, 1), a2 + hstep, voffA);
;             PG8_WAIT_V(8); PG8_WAIT_L(0); PG8_BAR; PG8_MMA(0, 0, At, B0); PG8_MMA(0, 1, At, B1); PG8_BAR; PG8_SCHED;
;             PG8_LDA(At, 1, 1); PG8_STAGE(PG8_SB(1, 0), b3, voffB); PG8_STAGE(PG8_SB(1, 1), b3 + hstep, voffB); PG8_STAGE(PG8_SA(1, 0), a3, voffA);
;             PG8_WAIT_V(8); PG8_WAIT_L(0); PG8_BAR; PG8_MMA(1, 0, At, B0); PG8_MMA(1, 1, At, B1); PG8_BAR; PG8_SCHED;
	s_setprio 0
	s_add_i32 s69, 0, 0x18000
	s_add_i32 s70, 0, 0x1c000
	v_add_u32_e32 v164, s69, v149
	v_add_u32_e32 v180, s70, v149
	ds_read_b128 v[144:147], v164
	ds_read_b128 v[156:159], v164 offset:1024
	ds_read_b128 v[160:163], v164 offset:2048
	ds_read_b128 v[164:167], v164 offset:3072
	ds_read_b128 v[168:171], v180
	ds_read_b128 v[172:175], v180 offset:1024
	ds_read_b128 v[176:179], v180 offset:2048
	ds_read_b128 v[180:183], v180 offset:3072
	s_add_u32 s42, s42, 0x40000
	s_addc_u32 s43, s43, 0
	s_mov_b32 m0, s51
	v_lshl_add_u64 v[224:225], s[42:43], 0, v[134:135]
	ds_read_b128 v[184:187], v153 offset:32768
	ds_read_b128 v[188:191], v153 offset:33792
	ds_read_b128 v[192:195], v153 offset:34816
	ds_read_b128 v[196:199], v153 offset:35840
	ds_read_b128 v[200:203], v153 offset:36864
	ds_read_b128 v[204:207], v153 offset:37888
	ds_read_b128 v[208:211], v153 offset:38912
	ds_read_b128 v[212:215], v153 offset:39936
	global_load_lds_dwordx4 v[224:225], off
	v_lshl_add_u64 v[224:225], s[42:43], 0, v[130:131]
	s_mov_b32 m0, s52
	s_nop 0
	global_load_lds_dwordx4 v[224:225], off
	s_waitcnt vmcnt(8)
	s_waitcnt lgkmcnt(0)
	s_barrier
	s_setprio 1
	v_mfma_f32_16x16x32_bf16 v[124:127], v[144:147], v[184:187], v[124:127]
	v_mfma_f32_16x16x32_bf16 v[120:123], v[160:163], v[184:187], v[120:123]
	v_mfma_f32_16x16x32_bf16 v[108:111], v[144:147], v[192:195], v[108:111]
	v_mfma_f32_16x16x32_bf16 v[104:107], v[160:163], v[192:195], v[104:107]
	v_mfma_f32_16x16x32_bf16 v[92:95], v[144:147], v[200:203], v[92:95]
	v_mfma_f32_16x16x32_bf16 v[88:91], v[160:163], v[200:203], v[88:91]
	v_mfma_f32_16x16x32_bf16 v[76:79], v[144:147], v[208:211], v[76:79]
	v_mfma_f32_16x16x32_bf16 v[72:75], v[160:163], v[208:211], v[72:75]
	v_mfma_f32_16x16x32_bf16 v[124:127], v[156:159], v[188:191], v[124:127]
	v_mfma_f32_16x16x32_bf16 v[120:123], v[164:167], v[188:191], v[120:123]
	v_mfma_f32_16x16x32_bf16 v[108:111], v[156:159], v[196:199], v[108:111]
	v_mfma_f32_16x16x32_bf16 v[104:107], v[164:167], v[196:199], v[104:107]
	v_mfma_f32_16x16x32_bf16 v[92:95], v[156:159], v[204:207], v[92:95]
	v_mfma_f32_16x16x32_bf16 v[88:91], v[164:167], v[204:207], v[88:91]
	v_mfma_f32_16x16x32_bf16 v[76:79], v[156:159], v[212:215], v[76:79]
	v_mfma_f32_16x16x32_bf16 v[72:75], v[164:167], v[212:215], v[72:75]
	v_mfma_f32_16x16x32_bf16 v[116:119], v[168:171], v[184:187], v[116:119]
	v_mfma_f32_16x16x32_bf16 v[112:115], v[176:179], v[184:187], v[112:115]
	v_mfma_f32_16x16x32_bf16 v[100:103], v[168:171], v[192:195], v[100:103]
	v_mfma_f32_16x16x32_bf16 v[96:99], v[176:179], v[192:195], v[96:99]
	v_mfma_f32_16x16x32_bf16 v[84:87], v[168:171], v[200:203], v[84:87]
	v_mfma_f32_16x16x32_bf16 v[80:83], v[176:179], v[200:203], v[80:83]
	v_mfma_f32_16x16x32_bf16 v[68:71], v[168:171], v[208:211], v[68:71]
	v_mfma_f32_16x16x32_bf16 v[64:67], v[176:179], v[208:211], v[64:67]
	v_mfma_f32_16x16x32_bf16 v[116:119], v[172:175], v[188:191], v[116:119]
	v_mfma_f32_16x16x32_bf16 v[112:115], v[180:183], v[188:191], v[112:115]
	v_mfma_f32_16x16x32_bf16 v[100:103], v[172:175], v[196:199], v[100:103]
	v_mfma_f32_16x16x32_bf16 v[96:99], v[180:183], v[196:199], v[96:99]
	v_mfma_f32_16x16x32_bf16 v[84:87], v[172:175], v[204:207], v[84:87]
	v_mfma_f32_16x16x32_bf16 v[80:83], v[180:183], v[204:207], v[80:83]
	v_mfma_f32_16x16x32_bf16 v[68:71], v[172:175], v[212:215], v[68:71]
	v_mfma_f32_16x16x32_bf16 v[64:67], v[180:183], v[212:215], v[64:67]
	s_barrier
	s_setprio 0
	s_add_i32 s42, s69, s48
	v_lshl_add_u64 v[216:217], v[216:217], 0, s[14:15]
	s_mov_b32 m0, s42
	ds_read_b128 v[184:187], v153 offset:49152
	ds_read_b128 v[188:191], v153 offset:50176
	ds_read_b128 v[192:195], v153 offset:51200
	ds_read_b128 v[196:199], v153 offset:52224
	ds_read_b128 v[200:203], v153 offset:53248
	ds_read_b128 v[204:207], v153 offset:54272
	ds_read_b128 v[208:211], v153 offset:55296
	ds_read_b128 v[212:215], v153 offset:56320
	global_load_lds_dwordx4 v[216:217], off
	s_add_i32 m0, s42, 0x2000
	s_add_u32 s40, s40, 0x40080
	v_lshl_add_u64 v[216:217], v[218:219], 0, s[14:15]
	s_addc_u32 s41, s41, 0
	s_add_i32 s42, s70, s48
	global_load_lds_dwordx4 v[216:217], off
	v_lshl_add_u64 v[216:217], s[40:41], 0, v[132:133]
	s_mov_b32 m0, s42
	s_nop 0
	global_load_lds_dwordx4 v[216:217], off
	v_lshl_add_u64 v[216:217], s[40:41], 0, v[128:129]
	s_add_i32 m0, s42, 0x2000
	s_nop 0
	global_load_lds_dwordx4 v[216:217], off
	v_lshl_add_u64 v[216:217], v[220:221], 0, s[14:15]
	s_mov_b32 m0, s53
	s_nop 0
	global_load_lds_dwordx4 v[216:217], off
	v_lshl_add_u64 v[216:217], v[222:223], 0, s[14:15]
	s_mov_b32 m0, s54
	s_nop 0
	global_load_lds_dwordx4 v[216:217], off
	s_waitcnt vmcnt(8)
	s_waitcnt lgkmcnt(0)
	s_barrier
	s_setprio 1
	v_mfma_f32_16x16x32_bf16 v[60:63], v[144:147], v[184:187], v[60:63]
	v_mfma_f32_16x16x32_bf16 v[56:59], v[160:163], v[184:187], v[56:59]
	v_mfma_f32_16x16x32_bf16 v[44:47], v[144:147], v[192:195], v[44:47]
	v_mfma_f32_16x16x32_bf16 v[40:43], v[160:163], v[192:195], v[40:43]
	v_mfma_f32_16x16x32_bf16 v[28:31], v[144:147], v[200:203], v[28:31]
	v_mfma_f32_16x16x32_bf16 v[24:27], v[160:163], v[200:203], v[24:27]
	v_mfma_f32_16x16x32_bf16 v[12:15], v[144:147], v[208:211], v[12:15]
	v_mfma_f32_16x16x32_bf16 v[8:11], v[160:163], v[208:211], v[8:11]
	v_mfma_f32_16x16x32_bf16 v[60:63], v[156:159], v[188:191], v[60:63]
	v_mfma_f32_16x16x32_bf16 v[56:59], v[164:167], v[188:191], v[56:59]
	v_mfma_f32_16x16x32_bf16 v[44:47], v[156:159], v[196:199], v[44:47]
	v_mfma_f32_16x16x32_bf16 v[40:43], v[164:167], v[196:199], v[40:43]
	v_mfma_f32_16x16x32_bf16 v[28:31], v[156:159], v[204:207], v[28:31]
	v_mfma_f32_16x16x32_bf16 v[24:27], v[164:167], v[204:207], v[24:27]
	v_mfma_f32_16x16x32_bf16 v[12:15], v[156:159], v[212:215], v[12:15]
	v_mfma_f32_16x16x32_bf16 v[8:11], v[164:167], v[212:215], v[8:11]
	v_mfma_f32_16x16x32_bf16 v[52:55], v[168:171], v[184:187], v[52:55]
	v_mfma_f32_16x16x32_bf16 v[48:51], v[176:179], v[184:187], v[48:51]
	v_mfma_f32_16x16x32_bf16 v[36:39], v[168:171], v[192:195], v[36:39]
	v_mfma_f32_16x16x32_bf16 v[32:35], v[176:179], v[192:195], v[32:35]
	v_mfma_f32_16x16x32_bf16 v[20:23], v[168:171], v[200:203], v[20:23]
	v_mfma_f32_16x16x32_bf16 v[16:19], v[176:179], v[200:203], v[16:19]
	v_mfma_f32_16x16x32_bf16 v[4:7], v[168:171], v[208:211], v[4:7]
	v_mfma_f32_16x16x32_bf16 v[0:3], v[176:179], v[208:211], v[0:3]
	v_mfma_f32_16x16x32_bf16 v[52:55], v[172:175], v[188:191], v[52:55]
	v_mfma_f32_16x16x32_bf16 v[48:51], v[180:183], v[188:191], v[48:51]
	v_mfma_f32_16x16x32_bf16 v[36:39], v[172:175], v[196:199], v[36:39]
	v_mfma_f32_16x16x32_bf16 v[32:35], v[180:183], v[196:199], v[32:35]
	v_mfma_f32_16x16x32_bf16 v[20:23], v[172:175], v[204:207], v[20:23]
	v_mfma_f32_16x16x32_bf16 v[16:19], v[180:183], v[204:207], v[16:19]
	v_mfma_f32_16x16x32_bf16 v[4:7], v[172:175], v[212:215], v[4:7]
	v_mfma_f32_16x16x32_bf16 v[0:3], v[180:183], v[212:215], v[0:3]
	s_barrier
	s_setprio 0
	s_add_i32 s68, s68, 2
	s_add_u32 s38, s38, 0x100
	s_addc_u32 s39, s39, 0
	s_add_u32 s66, s66, 0x100
	s_addc_u32 s67, s67, 0

; __device__ __forceinline__ unsigned cvt_pk_bf16(float lo, float hi) { unsigned r; asm volatile("v_cvt_pk_bf16_f32 %0, %1, %2" : "=v"(r) : "v"(lo), "v"(hi)); return r; }
; __device__ __forceinline__ float ld_agent(const rss_t* p) { return (float)__hip_atomic_load(p, __ATOMIC_RELAXED, __HIP_MEMORY_SCOPE_AGENT) * (1.0f / 16777216.0f); }
;     __device__ __forceinline__ void operator()(const f32x4 (&acc)[2][2][4][2], const Unit& u, int wr, int wc, int fr, int fq) const {
;         const int row0 = u.pm * BM + wr * 64 + fr; int colt = u.pn * BM; bf16_t* base = O;
;         if (split_cols) { const int t = colt / split_cols; base += (size_t)t * split_stride; colt -= t * split_cols; }
;         const float sc = (u.pn < qtiles) ? qscale : 1.0f;
;         const int col0 = colt + wc * 32 + 8 * fq;
;         float ssq[2][4];
; #pragma unroll
;         for (int ai = 0; ai < 2; ++ai)
; #pragma unroll
;             for (int m = 0; m < 4; ++m) ssq[ai][m] = ld_agent(rowss + row0 + ai * HALF + m * 16);
; #pragma unroll
;         for (int ai = 0; ai < 2; ++ai)
; #pragma unroll
;             for (int m = 0; m < 4; ++m) {
;                 const int row = row0 + ai * HALF + m * 16; const float rs = __builtin_amdgcn_rsqf(ssq[ai][m] * (1.0f / 1024.0f) + 1e-6f) * sc;
;                 bf16_t* rowp = base + (size_t)row * ldc + col0;
; #pragma unroll
;                 for (int bj = 0; bj < 2; ++bj) { const f32x4 v0 = acc[ai][bj][m][0] * rs, v1 = acc[ai][bj][m][1] * rs;
;                     u32x4 w; w.x = cvt_pk_bf16(v0[0], v0[1]); w.y = cvt_pk_bf16(v0[2], v0[3]); w.z = cvt_pk_bf16(v1[0], v1[1]); w.w = cvt_pk_bf16(v1[2], v1[3]);
;                     *(u32x4*)(rowp + bj * HALF) = w; }
.LBB0_1909:
	v_lshl_add_u32 v144, s36, 8, v148
	v_ashrrev_i32_e32 v145, 31, v144
	v_lshl_add_u64 v[146:147], v[144:145], 3, s[12:13]
	global_load_dwordx2 v[156:157], v[146:147], off sc1
	global_load_dwordx2 v[158:159], v[146:147], off offset:128 sc1
	global_load_dwordx2 v[160:161], v[146:147], off offset:256 sc1
	global_load_dwordx2 v[162:163], v[146:147], off offset:384 sc1
	global_load_dwordx2 v[164:165], v[146:147], off offset:1024 sc1
	global_load_dwordx2 v[166:167], v[146:147], off offset:1152 sc1
	global_load_dwordx2 v[168:169], v[146:147], off offset:1280 sc1
	global_load_dwordx2 v[170:171], v[146:147], off offset:1408 sc1
	s_cmp_lt_i32 s63, 4
	v_lshl_or_b32 v146, s63, 8, v150
	s_cselect_b64 vcc, -1, 0
	v_cndmask_b32_e32 v145, 1.0, v155, vcc
	v_ashrrev_i32_e32 v147, 31, v146
	v_lshl_add_u64 v[146:147], v[146:147], 1, s[8:9]
	v_mad_i64_i32 v[172:173], s[38:39], v144, s59, v[146:147]
	s_andn2_b64 vcc, exec, s[4:5]
	s_mov_b64 s[4:5], -1
	s_waitcnt vmcnt(0)
	v_ffbh_u32_e32 v174, v157
	v_min_u32_e32 v174, 32, v174
	v_lshlrev_b64 v[156:157], v174, v[156:157]
	v_min_u32_e32 v156, 1, v156
	v_or_b32_e32 v156, v157, v156
	v_cvt_f32_u32_e32 v156, v156
	v_ffbh_u32_e32 v175, v159
	v_ffbh_u32_e32 v176, v161
	v_ffbh_u32_e32 v177, v163
	v_min_u32_e32 v175, 32, v175
	v_min_u32_e32 v176, 32, v176
	v_min_u32_e32 v177, 32, v177
	v_sub_u32_e32 v174, 32, v174
	v_lshlrev_b64 v[158:159], v175, v[158:159]
	v_lshlrev_b64 v[160:161], v176, v[160:161]
	v_lshlrev_b64 v[162:163], v177, v[162:163]
	v_min_u32_e32 v158, 1, v158
	v_ldexp_f32 v156, v156, v174
	v_min_u32_e32 v160, 1, v160
	v_min_u32_e32 v162, 1, v162
	v_or_b32_e32 v157, v159, v158
	v_mul_f32_e32 v156, 0x33800000, v156
	v_or_b32_e32 v158, v161, v160
	v_or_b32_e32 v159, v163, v162
	v_cvt_f32_u32_e32 v157, v157
	v_fmamk_f32 v156, v156, 0x3a800000, v154
	v_cvt_f32_u32_e32 v158, v158
	v_cvt_f32_u32_e32 v159, v159
	v_rsq_f32_e32 v156, v156
	v_ffbh_u32_e32 v178, v165
	v_min_u32_e32 v178, 32, v178
	v_sub_u32_e32 v175, 32, v175
	v_sub_u32_e32 v176, 32, v176
	v_sub_u32_e32 v177, 32, v177
	v_lshlrev_b64 v[164:165], v178, v[164:165]
	v_ldexp_f32 v157, v157, v175
	v_min_u32_e32 v164, 1, v164
	v_ldexp_f32 v158, v158, v176
	v_ldexp_f32 v159, v159, v177
	v_mul_f32_e32 v157, 0x33800000, v157
	v_mul_f32_e32 v156, v145, v156
	v_or_b32_e32 v160, v165, v164
	v_mul_f32_e32 v164, 0x33800000, v158
	v_mul_f32_e32 v165, 0x33800000, v159
	v_pk_mul_f32 v[126:127], v[126:127], v[156:157] op_sel_hi:[1,0]
	v_pk_mul_f32 v[124:125], v[124:125], v[156:157] op_sel_hi:[1,0]
	v_pk_mul_f32 v[158:159], v[122:123], v[156:157] op_sel_hi:[1,0]
	v_pk_mul_f32 v[122:123], v[120:121], v[156:157] op_sel_hi:[1,0]
	v_cvt_pk_bf16_f32 v120, v124, v125
	v_cvt_pk_bf16_f32 v121, v126, v127
	v_pk_mul_f32 v[118:119], v[118:119], v[156:157] op_sel_hi:[1,0]
	v_cvt_pk_bf16_f32 v122, v122, v123
	v_cvt_pk_bf16_f32 v123, v158, v159
	global_store_dwordx4 v[172:173], v[120:123], off
	v_pk_mul_f32 v[116:117], v[116:117], v[156:157] op_sel_hi:[1,0]
	v_cvt_f32_u32_e32 v160, v160
	v_pk_mul_f32 v[120:121], v[114:115], v[156:157] op_sel_hi:[1,0]
	v_pk_mul_f32 v[114:115], v[112:113], v[156:157] op_sel_hi:[1,0]
	v_cvt_pk_bf16_f32 v112, v116, v117
	v_cvt_pk_bf16_f32 v113, v118, v119
	v_ffbh_u32_e32 v179, v167
	v_cvt_pk_bf16_f32 v114, v114, v115
	v_fmamk_f32 v115, v157, 0x3a800000, v154
	v_rsq_f32_e32 v116, v115
	v_cvt_pk_bf16_f32 v115, v120, v121
	global_store_dwordx4 v[172:173], v[112:115], off offset:256
	v_sub_u32_e32 v178, 32, v178
	v_min_u32_e32 v179, 32, v179
	v_or_b32_e32 v113, 16, v144
	v_mul_f32_e32 v112, v145, v116
	v_mad_i64_i32 v[114:115], s[38:39], v113, s59, v[146:147]
	v_pk_mul_f32 v[110:111], v[110:111], v[112:113] op_sel_hi:[1,0]
	v_pk_mul_f32 v[108:109], v[108:109], v[112:113] op_sel_hi:[1,0]
	v_pk_mul_f32 v[116:117], v[106:107], v[112:113] op_sel_hi:[1,0]
	v_pk_mul_f32 v[106:107], v[104:105], v[112:113] op_sel_hi:[1,0]
	v_cvt_pk_bf16_f32 v104, v108, v109
	v_cvt_pk_bf16_f32 v105, v110, v111
	v_pk_mul_f32 v[102:103], v[102:103], v[112:113] op_sel_hi:[1,0]
	v_cvt_pk_bf16_f32 v106, v106, v107
	v_cvt_pk_bf16_f32 v107, v116, v117
	global_store_dwordx4 v[114:115], v[104:107], off
	v_pk_mul_f32 v[100:101], v[100:101], v[112:113] op_sel_hi:[1,0]
	v_ldexp_f32 v160, v160, v178
	v_pk_mul_f32 v[104:105], v[98:99], v[112:113] op_sel_hi:[1,0]
	v_pk_mul_f32 v[98:99], v[96:97], v[112:113] op_sel_hi:[1,0]
	v_cvt_pk_bf16_f32 v96, v100, v101
	v_cvt_pk_bf16_f32 v97, v102, v103
	v_lshlrev_b64 v[166:167], v179, v[166:167]
	v_cvt_pk_bf16_f32 v98, v98, v99
	v_fmamk_f32 v99, v164, 0x3a800000, v154
	v_rsq_f32_e32 v100, v99
	v_cvt_pk_bf16_f32 v99, v104, v105
	global_store_dwordx4 v[114:115], v[96:99], off offset:256
	v_mul_f32_e32 v160, 0x33800000, v160
	v_min_u32_e32 v166, 1, v166
	v_or_b32_e32 v97, 32, v144
	v_mul_f32_e32 v96, v145, v100
	v_mad_i64_i32 v[98:99], s[38:39], v97, s59, v[146:147]
	v_pk_mul_f32 v[94:95], v[94:95], v[96:97] op_sel_hi:[1,0]
	v_pk_mul_f32 v[92:93], v[92:93], v[96:97] op_sel_hi:[1,0]
	v_pk_mul_f32 v[100:101], v[90:91], v[96:97] op_sel_hi:[1,0]
	v_pk_mul_f32 v[90:91], v[88:89], v[96:97] op_sel_hi:[1,0]
	v_cvt_pk_bf16_f32 v88, v92, v93
	v_cvt_pk_bf16_f32 v89, v94, v95
	v_pk_mul_f32 v[86:87], v[86:87], v[96:97] op_sel_hi:[1,0]
	v_cvt_pk_bf16_f32 v90, v90, v91
	v_cvt_pk_bf16_f32 v91, v100, v101
	global_store_dwordx4 v[98:99], v[88:91], off
	v_pk_mul_f32 v[84:85], v[84:85], v[96:97] op_sel_hi:[1,0]
	v_or_b32_e32 v161, v167, v166
	v_pk_mul_f32 v[88:89], v[82:83], v[96:97] op_sel_hi:[1,0]
	v_pk_mul_f32 v[82:83], v[80:81], v[96:97] op_sel_hi:[1,0]
	v_cvt_pk_bf16_f32 v80, v84, v85
	v_cvt_pk_bf16_f32 v81, v86, v87
	v_cvt_f32_u32_e32 v161, v161
; __device__ __forceinline__ unsigned cvt_pk_bf16(float lo, float hi) { unsigned r; asm volatile("v_cvt_pk_bf16_f32 %0, %1, %2" : "=v"(r) : "v"(lo), "v"(hi)); return r; }
; #define PG8_BAR __builtin_amdgcn_s_barrier()
;     __device__ __forceinline__ void operator()(const f32x4 (&acc)[2][2][4][2], const Unit& u, int wr, int wc, int fr, int fq) const {
;     ...
;         for (int ai = 0; ai < 2; ++ai)
; #pragma unroll
;             for (int m = 0; m < 4; ++m) {
;                 const int row = row0 + ai * HALF + m * 16; const float rs = __builtin_amdgcn_rsqf(ssq[ai][m] * (1.0f / 1024.0f) + 1e-6f) * sc;
;                 bf16_t* rowp = base + (size_t)row * ldc + col0;
; #pragma unroll
;                 for (int bj = 0; bj < 2; ++bj) { const f32x4 v0 = acc[ai][bj][m][0] * rs, v1 = acc[ai][bj][m][1] * rs;
;                     u32x4 w; w.x = cvt_pk_bf16(v0[0], v0[1]); w.y = cvt_pk_bf16(v0[2], v0[3]); w.z = cvt_pk_bf16(v1[0], v1[1]); w.w = cvt_pk_bf16(v1[2], v1[3]);
;                     *(u32x4*)(rowp + bj * HALF) = w; }
; template <class Epi, class Sched, bool ALIGN_EPI = false, bool SP2 = false>
; __device__ __forceinline__ void gemm_phase(PG8_LAS unsigned char* lds, const Gemm g, const Sched& S, const Epi& E) {
;     ...
;         if constexpr (!Epi::AFTER_DRAIN) { E(acc, cur, wr, wc, fr, fq); S.done(cur); }
;         if (!has_next) break;
; #pragma unroll
;         for (int a = 0; a < 2; ++a)
; #pragma unroll
;             for (int b = 0; b < 2; ++b)
; #pragma unroll
;                 for (int m = 0; m < 4; ++m)
; #pragma unroll
;                     for (int n = 0; n < 2; ++n) acc[a][b][m][n] = (f32x4){0.f, 0.f, 0.f, 0.f};
;         cur = nxt; cA = nA; cB = nB; ++ui;
;         if constexpr (ALIGN_EPI) { if (wr == 1) PG8_BAR; }
	v_cvt_pk_bf16_f32 v82, v82, v83
	v_fmamk_f32 v83, v165, 0x3a800000, v154
	v_rsq_f32_e32 v84, v83
	v_cvt_pk_bf16_f32 v83, v88, v89
	global_store_dwordx4 v[98:99], v[80:83], off offset:256
	v_ffbh_u32_e32 v180, v169
	v_sub_u32_e32 v179, 32, v179
	v_or_b32_e32 v81, 48, v144
	v_mul_f32_e32 v80, v145, v84
	v_mad_i64_i32 v[82:83], s[38:39], v81, s59, v[146:147]
	v_pk_mul_f32 v[78:79], v[78:79], v[80:81] op_sel_hi:[1,0]
	v_pk_mul_f32 v[76:77], v[76:77], v[80:81] op_sel_hi:[1,0]
	v_pk_mul_f32 v[84:85], v[74:75], v[80:81] op_sel_hi:[1,0]
	v_pk_mul_f32 v[74:75], v[72:73], v[80:81] op_sel_hi:[1,0]
	v_cvt_pk_bf16_f32 v72, v76, v77
	v_cvt_pk_bf16_f32 v73, v78, v79
	v_pk_mul_f32 v[70:71], v[70:71], v[80:81] op_sel_hi:[1,0]
	v_cvt_pk_bf16_f32 v74, v74, v75
	v_cvt_pk_bf16_f32 v75, v84, v85
	global_store_dwordx4 v[82:83], v[72:75], off
	v_pk_mul_f32 v[68:69], v[68:69], v[80:81] op_sel_hi:[1,0]
	v_min_u32_e32 v180, 32, v180
	v_pk_mul_f32 v[72:73], v[66:67], v[80:81] op_sel_hi:[1,0]
	v_pk_mul_f32 v[66:67], v[64:65], v[80:81] op_sel_hi:[1,0]
	v_cvt_pk_bf16_f32 v64, v68, v69
	v_cvt_pk_bf16_f32 v65, v70, v71
	v_ldexp_f32 v161, v161, v179
	v_cvt_pk_bf16_f32 v66, v66, v67
	v_fmamk_f32 v67, v160, 0x3a800000, v154
	v_rsq_f32_e32 v68, v67
	v_cvt_pk_bf16_f32 v67, v72, v73
	global_store_dwordx4 v[82:83], v[64:67], off offset:256
	v_lshlrev_b64 v[168:169], v180, v[168:169]
	v_mul_f32_e32 v161, 0x33800000, v161
	v_add_u32_e32 v65, 0x80, v144
	v_mul_f32_e32 v64, v145, v68
	v_mad_i64_i32 v[66:67], s[38:39], v65, s59, v[146:147]
	v_pk_mul_f32 v[62:63], v[62:63], v[64:65] op_sel_hi:[1,0]
	v_pk_mul_f32 v[60:61], v[60:61], v[64:65] op_sel_hi:[1,0]
	v_pk_mul_f32 v[68:69], v[58:59], v[64:65] op_sel_hi:[1,0]
	v_pk_mul_f32 v[58:59], v[56:57], v[64:65] op_sel_hi:[1,0]
	v_cvt_pk_bf16_f32 v56, v60, v61
	v_cvt_pk_bf16_f32 v57, v62, v63
	v_min_u32_e32 v168, 1, v168
	v_cvt_pk_bf16_f32 v58, v58, v59
	v_cvt_pk_bf16_f32 v59, v68, v69
	global_store_dwordx4 v[66:67], v[56:59], off
	v_pk_mul_f32 v[54:55], v[54:55], v[64:65] op_sel_hi:[1,0]
	v_pk_mul_f32 v[52:53], v[52:53], v[64:65] op_sel_hi:[1,0]
	v_pk_mul_f32 v[56:57], v[50:51], v[64:65] op_sel_hi:[1,0]
	v_pk_mul_f32 v[50:51], v[48:49], v[64:65] op_sel_hi:[1,0]
	v_cvt_pk_bf16_f32 v48, v52, v53
	v_cvt_pk_bf16_f32 v49, v54, v55
	v_or_b32_e32 v162, v169, v168
	v_cvt_pk_bf16_f32 v50, v50, v51
	v_fmamk_f32 v51, v161, 0x3a800000, v154
	v_rsq_f32_e32 v52, v51
	v_cvt_f32_u32_e32 v162, v162
	v_ffbh_u32_e32 v181, v171
	v_sub_u32_e32 v180, 32, v180
	v_cvt_pk_bf16_f32 v51, v56, v57
	global_store_dwordx4 v[66:67], v[48:51], off offset:256
	v_min_u32_e32 v181, 32, v181
	v_ldexp_f32 v162, v162, v180
	v_add_u32_e32 v49, 0x90, v144
	v_mul_f32_e32 v48, v145, v52
	v_mad_i64_i32 v[50:51], s[38:39], v49, s59, v[146:147]
	v_pk_mul_f32 v[46:47], v[46:47], v[48:49] op_sel_hi:[1,0]
	v_pk_mul_f32 v[44:45], v[44:45], v[48:49] op_sel_hi:[1,0]
	v_pk_mul_f32 v[52:53], v[42:43], v[48:49] op_sel_hi:[1,0]
	v_pk_mul_f32 v[42:43], v[40:41], v[48:49] op_sel_hi:[1,0]
	v_cvt_pk_bf16_f32 v40, v44, v45
	v_cvt_pk_bf16_f32 v41, v46, v47
	v_lshlrev_b64 v[170:171], v181, v[170:171]
	v_mul_f32_e32 v162, 0x33800000, v162
	v_cvt_pk_bf16_f32 v42, v42, v43
	v_cvt_pk_bf16_f32 v43, v52, v53
	global_store_dwordx4 v[50:51], v[40:43], off
	v_min_u32_e32 v170, 1, v170
	v_pk_mul_f32 v[38:39], v[38:39], v[48:49] op_sel_hi:[1,0]
	v_pk_mul_f32 v[40:41], v[34:35], v[48:49] op_sel_hi:[1,0]
	v_pk_mul_f32 v[34:35], v[32:33], v[48:49] op_sel_hi:[1,0]
	v_pk_mul_f32 v[36:37], v[36:37], v[48:49] op_sel_hi:[1,0]
	v_or_b32_e32 v163, v171, v170
	v_cvt_pk_bf16_f32 v32, v36, v37
	v_cvt_pk_bf16_f32 v33, v38, v39
	v_cvt_pk_bf16_f32 v34, v34, v35
	v_fmamk_f32 v35, v162, 0x3a800000, v154
	v_rsq_f32_e32 v36, v35
	v_cvt_f32_u32_e32 v163, v163
	v_sub_u32_e32 v181, 32, v181
	v_cvt_pk_bf16_f32 v35, v40, v41
	global_store_dwordx4 v[50:51], v[32:35], off offset:256
	v_ldexp_f32 v163, v163, v181
	v_mul_f32_e32 v163, 0x33800000, v163
	v_add_u32_e32 v33, 0xa0, v144
	v_mul_f32_e32 v32, v145, v36
	v_mad_i64_i32 v[34:35], s[38:39], v33, s59, v[146:147]
	v_pk_mul_f32 v[30:31], v[30:31], v[32:33] op_sel_hi:[1,0]
	v_pk_mul_f32 v[28:29], v[28:29], v[32:33] op_sel_hi:[1,0]
	v_pk_mul_f32 v[36:37], v[26:27], v[32:33] op_sel_hi:[1,0]
	v_pk_mul_f32 v[26:27], v[24:25], v[32:33] op_sel_hi:[1,0]
	v_cvt_pk_bf16_f32 v24, v28, v29
	v_cvt_pk_bf16_f32 v25, v30, v31
	v_pk_mul_f32 v[22:23], v[22:23], v[32:33] op_sel_hi:[1,0]
	v_cvt_pk_bf16_f32 v26, v26, v27
	v_cvt_pk_bf16_f32 v27, v36, v37
	global_store_dwordx4 v[34:35], v[24:27], off
	v_pk_mul_f32 v[20:21], v[20:21], v[32:33] op_sel_hi:[1,0]
	s_nop 0
	v_pk_mul_f32 v[24:25], v[18:19], v[32:33] op_sel_hi:[1,0]
	v_pk_mul_f32 v[18:19], v[16:17], v[32:33] op_sel_hi:[1,0]
	v_cvt_pk_bf16_f32 v16, v20, v21
	v_cvt_pk_bf16_f32 v17, v22, v23
	s_nop 0
	v_cvt_pk_bf16_f32 v18, v18, v19
	v_fmamk_f32 v19, v163, 0x3a800000, v154
	v_rsq_f32_e32 v20, v19
	v_cvt_pk_bf16_f32 v19, v24, v25
	global_store_dwordx4 v[34:35], v[16:19], off offset:256
	s_nop 1
	v_add_u32_e32 v17, 0xb0, v144
	v_mul_f32_e32 v16, v145, v20
	v_mad_i64_i32 v[18:19], s[38:39], v17, s59, v[146:147]
	v_pk_mul_f32 v[14:15], v[14:15], v[16:17] op_sel_hi:[1,0]
	v_pk_mul_f32 v[12:13], v[12:13], v[16:17] op_sel_hi:[1,0]
	v_pk_mul_f32 v[20:21], v[10:11], v[16:17] op_sel_hi:[1,0]
	v_pk_mul_f32 v[10:11], v[8:9], v[16:17] op_sel_hi:[1,0]
	v_cvt_pk_bf16_f32 v8, v12, v13
	v_cvt_pk_bf16_f32 v9, v14, v15
	v_pk_mul_f32 v[6:7], v[6:7], v[16:17] op_sel_hi:[1,0]
	v_cvt_pk_bf16_f32 v10, v10, v11
	v_cvt_pk_bf16_f32 v11, v20, v21
	global_store_dwordx4 v[18:19], v[8:11], off
	v_pk_mul_f32 v[4:5], v[4:5], v[16:17] op_sel_hi:[1,0]
	s_nop 0
	v_pk_mul_f32 v[8:9], v[2:3], v[16:17] op_sel_hi:[1,0]
	v_pk_mul_f32 v[2:3], v[0:1], v[16:17] op_sel_hi:[1,0]
	v_cvt_pk_bf16_f32 v0, v4, v5
	v_cvt_pk_bf16_f32 v1, v6, v7
	s_nop 0
	v_cvt_pk_bf16_f32 v2, v2, v3
	v_cvt_pk_bf16_f32 v3, v8, v9
	global_store_dwordx4 v[18:19], v[0:3], off offset:256
	s_cbranch_vccnz .LBB0_1902
	s_andn2_b64 vcc, exec, s[6:7]
	s_cbranch_vccnz .LBB0_1901
	s_mov_b32 s99, 1
	s_branch .LBB0_1901

; #define PG8_STAGE(bufoff, gbase, voff) do { _Pragma("unroll") for (int _i = 0; _i < 2; ++_i) \
;         __builtin_amdgcn_global_load_lds((const unsigned*)((const char*)(gbase) + (voff)[_i]), (PG8_LAS unsigned*)(lds + (bufoff) + ldsw + _i * 8192), 16, 0, 0); } while (0)
; #define PG8_LDA(dst, b, h) do { _Pragma("unroll") for (int m = 0; m < 4; ++m) _Pragma("unroll") for (int k = 0; k < 2; ++k) dst[m][k] = *(const PG8_LAS bf16x8*)(lds + PG8_SA(b, h) + aoff + m * 2048 + k * 1024); } while (0)
; #define PG8_LDB(dst, b, h) do { _Pragma("unroll") for (int n = 0; n < 2; ++n) _Pragma("unroll") for (int k = 0; k < 2; ++k) dst[n][k] = *(const PG8_LAS bf16x8*)(lds + PG8_SB(b, h) + boff + n * 2048 + k * 1024); } while (0)
; #define PG8_WAIT_V(n) asm volatile("s_waitcnt vmcnt(" #n ")" ::: "memory")
; #define PG8_BAR __builtin_amdgcn_s_barrier()
; template <class Epi, class Sched, bool ALIGN_EPI = false, bool SP2 = false>
; __device__ __forceinline__ void gemm_phase(PG8_LAS unsigned char* lds, const Gemm g, const Sched& S, const Epi& E) {
;     ...
;         const bool has_next = S.next(ui + 1, nxt);
;         const char* nA = has_next ? (const char*)g.A + (size_t)nxt.pm * tstep : cA; const char* nB = has_next ? (const char*)g.Bt + (size_t)nxt.pn * tstep : cB;
;         for (int t = 0; t < nt; t += 2) {
;             const bool last = (t == nt - 2);
;             if constexpr (Epi::PREFETCH) { if (t == nt - 4) E.prefetch(cur, lds + STAGE_BYTES + 1024, tid); }
;             const char* a1 = cA + (size_t)(t + 1) * kstep;
;             const char* a2 = last ? nA : cA + (size_t)(t + 2) * kstep; const char* b2 = last ? nB : cB + (size_t)(t + 2) * kstep;
;             const char* a3 = a2 + kstep; const char* b3 = b2 + kstep;
;             if (last && has_next) S.a_ready(nxt);
;             if constexpr (SP2) {
;             PG8_LDB(B0, 0, 0); PG8_LDB(B1, 0, 1); PG8_SCHED; PG8_LDA(At, 0, 0); PG8_STAGE(PG8_SA(1, 1), a1 + hstep, voffA);
;             PG8_WAIT_V(8); PG8_WAIT_L(0); PG8_BAR; PG8_MMA(0, 0, At, B0); PG8_MMA(0, 1, At, B1); PG8_BAR; PG8_SCHED;
;             PG8_LDA(At, 0, 1); PG8_STAGE(PG8_SB(0, 0), b2, voffB); PG8_STAGE(PG8_SB(0, 1), b2 + hstep, voffB); PG8_STAGE(PG8_SA(0, 0), a2, voffA);
;             PG8_WAIT_V(8); PG8_WAIT_L(0); PG8_BAR; PG8_MMA(1, 0, At, B0); PG8_MMA(1, 1, At, B1); PG8_BAR; PG8_SCHED;
;     ...
;         if constexpr (ALIGN_EPI) { if (wr == 1) PG8_BAR; }
.LBB0_2596:
	s_add_u32 s38, s38, 0xb0080
	s_addc_u32 s39, s39, 0
	s_add_u32 s66, s40, 0x100
	s_addc_u32 s67, s41, 0
	s_mov_b32 s68, -2
	s_cmp_eq_u32 s99, 0
	s_cbranch_scc1 .Lnobar_11
	s_mov_b32 s99, 0
	s_barrier
.Lnobar_11:
	ds_read_b128 v[128:131], v201
	ds_read_b128 v[132:135], v201 offset:1024
	ds_read_b128 v[136:139], v201 offset:2048
	ds_read_b128 v[140:143], v201 offset:3072
	ds_read_b128 v[144:147], v202
	ds_read_b128 v[148:151], v202 offset:1024
	ds_read_b128 v[152:155], v202 offset:2048
	ds_read_b128 v[156:159], v202 offset:3072
	s_add_u32 s40, s38, 0xfff50080
	s_addc_u32 s41, s39, -1
	s_cmp_eq_u32 s68, 40
	s_cselect_b32 s43, s7, s41
	s_cselect_b32 s42, s6, s40
	s_cselect_b32 s41, s37, s67
	s_cselect_b32 s40, s36, s66
	v_lshl_add_u64 v[196:197], s[38:39], 0, v[176:177]
	s_add_i32 m0, s49, 0xc000
	ds_read_b128 v[160:163], v203
	ds_read_b128 v[164:167], v203 offset:1024
	ds_read_b128 v[184:187], v203 offset:2048
	ds_read_b128 v[188:191], v203 offset:3072
	ds_read_b128 v[192:195], v203 offset:4096
	ds_read_b128 v[204:207], v203 offset:5120
	ds_read_b128 v[208:211], v203 offset:6144
	ds_read_b128 v[212:215], v203 offset:7168
	global_load_lds_dwordx4 v[196:197], off
	v_lshl_add_u64 v[196:197], s[38:39], 0, v[178:179]
	s_add_i32 m0, s49, 0xe000
	s_nop 0
	global_load_lds_dwordx4 v[196:197], off
	s_waitcnt vmcnt(8)
	s_waitcnt lgkmcnt(0)
	s_barrier
	s_setprio 1
	v_mfma_f32_16x16x32_bf16 v[124:127], v[128:131], v[160:163], 0
	v_mfma_f32_16x16x32_bf16 v[120:123], v[136:139], v[160:163], 0
	v_mfma_f32_16x16x32_bf16 v[116:119], v[128:131], v[184:187], 0
	v_mfma_f32_16x16x32_bf16 v[104:107], v[136:139], v[184:187], 0
	v_mfma_f32_16x16x32_bf16 v[92:95], v[128:131], v[192:195], 0
	v_mfma_f32_16x16x32_bf16 v[88:91], v[136:139], v[192:195], 0
	v_mfma_f32_16x16x32_bf16 v[76:79], v[128:131], v[208:211], 0
	v_mfma_f32_16x16x32_bf16 v[72:75], v[136:139], v[208:211], 0
	v_mfma_f32_16x16x32_bf16 v[124:127], v[132:135], v[164:167], v[124:127]
	v_mfma_f32_16x16x32_bf16 v[120:123], v[140:143], v[164:167], v[120:123]
	v_mfma_f32_16x16x32_bf16 v[116:119], v[132:135], v[188:191], v[116:119]
	v_mfma_f32_16x16x32_bf16 v[104:107], v[140:143], v[188:191], v[104:107]
	v_mfma_f32_16x16x32_bf16 v[92:95], v[132:135], v[204:207], v[92:95]
	v_mfma_f32_16x16x32_bf16 v[88:91], v[140:143], v[204:207], v[88:91]
	v_mfma_f32_16x16x32_bf16 v[76:79], v[132:135], v[212:215], v[76:79]
	v_mfma_f32_16x16x32_bf16 v[72:75], v[140:143], v[212:215], v[72:75]
	v_mfma_f32_16x16x32_bf16 v[112:115], v[144:147], v[160:163], 0
	v_mfma_f32_16x16x32_bf16 v[108:111], v[152:155], v[160:163], 0
	v_mfma_f32_16x16x32_bf16 v[100:103], v[144:147], v[184:187], 0
	v_mfma_f32_16x16x32_bf16 v[96:99], v[152:155], v[184:187], 0
	v_mfma_f32_16x16x32_bf16 v[84:87], v[144:147], v[192:195], 0
	v_mfma_f32_16x16x32_bf16 v[80:83], v[152:155], v[192:195], 0
	v_mfma_f32_16x16x32_bf16 v[68:71], v[144:147], v[208:211], 0
	v_mfma_f32_16x16x32_bf16 v[64:67], v[152:155], v[208:211], 0
	v_mfma_f32_16x16x32_bf16 v[112:115], v[148:151], v[164:167], v[112:115]
	v_mfma_f32_16x16x32_bf16 v[108:111], v[156:159], v[164:167], v[108:111]
	v_mfma_f32_16x16x32_bf16 v[100:103], v[148:151], v[188:191], v[100:103]
	v_mfma_f32_16x16x32_bf16 v[96:99], v[156:159], v[188:191], v[96:99]
	v_mfma_f32_16x16x32_bf16 v[84:87], v[148:151], v[204:207], v[84:87]
	v_mfma_f32_16x16x32_bf16 v[80:83], v[156:159], v[204:207], v[80:83]
	v_mfma_f32_16x16x32_bf16 v[68:71], v[148:151], v[212:215], v[68:71]
	v_mfma_f32_16x16x32_bf16 v[64:67], v[156:159], v[212:215], v[64:67]
	s_barrier
	s_setprio 0
	s_add_i32 s69, s57, s48
	v_lshl_add_u64 v[196:197], s[40:41], 0, v[170:171]
	s_mov_b32 m0, s69
	ds_read_b128 v[160:163], v203 offset:16384
	ds_read_b128 v[164:167], v203 offset:17408
	ds_read_b128 v[184:187], v203 offset:18432
	ds_read_b128 v[188:191], v203 offset:19456
	ds_read_b128 v[192:195], v203 offset:20480
	ds_read_b128 v[204:207], v203 offset:21504
	ds_read_b128 v[208:211], v203 offset:22528
	ds_read_b128 v[212:215], v203 offset:23552
	global_load_lds_dwordx4 v[196:197], off
	s_add_i32 m0, s69, 0x2000
	s_add_u32 s70, s40, 0xb0000
	v_lshl_add_u64 v[216:217], s[40:41], 0, v[174:175]
	s_addc_u32 s71, s41, 0
	s_add_i32 s69, s58, s48
	global_load_lds_dwordx4 v[216:217], off
	v_lshl_add_u64 v[218:219], s[70:71], 0, v[170:171]
	s_mov_b32 m0, s69
	v_lshl_add_u64 v[220:221], s[42:43], 0, v[172:173]
	global_load_lds_dwordx4 v[218:219], off
	v_lshl_add_u64 v[218:219], s[70:71], 0, v[174:175]
	s_add_i32 m0, s69, 0x2000
	s_nop 0
	global_load_lds_dwordx4 v[218:219], off
	v_lshl_add_u64 v[218:219], s[42:43], 0, v[168:169]
	s_mov_b32 m0, s49
	s_nop 0
	global_load_lds_dwordx4 v[218:219], off
	s_mov_b32 m0, s50
	s_nop 0
	global_load_lds_dwordx4 v[220:221], off
	s_waitcnt vmcnt(8)
	s_waitcnt lgkmcnt(0)
	s_barrier
; #define PG8_STAGE(bufoff, gbase, voff) do { _Pragma("unroll") for (int _i = 0; _i < 2; ++_i) \
;         __builtin_amdgcn_global_load_lds((const unsigned*)((const char*)(gbase) + (voff)[_i]), (PG8_LAS unsigned*)(lds + (bufoff) + ldsw + _i * 8192), 16, 0, 0); } while (0)
; #define PG8_LDA(dst, b, h) do { _Pragma("unroll") for (int m = 0; m < 4; ++m) _Pragma("unroll") for (int k = 0; k < 2; ++k) dst[m][k] = *(const PG8_LAS bf16x8*)(lds + PG8_SA(b, h) + aoff + m * 2048 + k * 1024); } while (0)
; #define PG8_LDB(dst, b, h) do { _Pragma("unroll") for (int n = 0; n < 2; ++n) _Pragma("unroll") for (int k = 0; k < 2; ++k) dst[n][k] = *(const PG8_LAS bf16x8*)(lds + PG8_SB(b, h) + boff + n * 2048 + k * 1024); } while (0)
; #define PG8_MMA(ai, bj, At, Bt) do { __builtin_amdgcn_s_setprio(1); _Pragma("unroll") for (int m = 0; m < 4; ++m) _Pragma("unroll") for (int n = 0; n < 2; ++n) _Pragma("unroll") for (int k = 0; k < 2; ++k) \
;         acc[ai][bj][m][n] = __builtin_amdgcn_mfma_f32_16x16x32_bf16(Bt[n][k], At[m][k], acc[ai][bj][m][n], 0, 0, 0); __builtin_amdgcn_s_setprio(0); } while (0)
; #define PG8_WAIT_V(n) asm volatile("s_waitcnt vmcnt(" #n ")" ::: "memory")
; #define PG8_WAIT_L(n) asm volatile("s_waitcnt lgkmcnt(" #n ")" ::: "memory")
; #define PG8_BAR __builtin_amdgcn_s_barrier()
; #define PG8_SCHED __builtin_amdgcn_sched_barrier(0)
; template <class Epi, class Sched, bool ALIGN_EPI = false, bool SP2 = false>
; __device__ __forceinline__ void gemm_phase(PG8_LAS unsigned char* lds, const Gemm g, const Sched& S, const Epi& E) {
;     ...
;             PG8_WAIT_V(8); PG8_WAIT_L(0); PG8_BAR; PG8_MMA(1, 0, At, B0); PG8_MMA(1, 1, At, B1); PG8_BAR; PG8_SCHED;
;             PG8_LDB(B0, 1, 0); PG8_LDB(B1, 1, 1); PG8_SCHED; PG8_LDA(At, 1, 0); PG8_STAGE(PG8_SA(0, 1), a2 + hstep, voffA);
;             PG8_WAIT_V(8); PG8_WAIT_L(0); PG8_BAR; PG8_MMA(0, 0, At, B0); PG8_MMA(0, 1, At, B1); PG8_BAR; PG8_SCHED;
;             PG8_LDA(At, 1, 1); PG8_STAGE(PG8_SB(1, 0), b3, voffB); PG8_STAGE(PG8_SB(1, 1), b3 + hstep, voffB); PG8_STAGE(PG8_SA(1, 0), a3, voffA);
	s_setprio 1
	v_mfma_f32_16x16x32_bf16 v[60:63], v[128:131], v[160:163], 0
	v_mfma_f32_16x16x32_bf16 v[56:59], v[136:139], v[160:163], 0
	v_mfma_f32_16x16x32_bf16 v[44:47], v[128:131], v[184:187], 0
	v_mfma_f32_16x16x32_bf16 v[40:43], v[136:139], v[184:187], 0
	v_mfma_f32_16x16x32_bf16 v[28:31], v[128:131], v[192:195], 0
	v_mfma_f32_16x16x32_bf16 v[24:27], v[136:139], v[192:195], 0
	v_mfma_f32_16x16x32_bf16 v[12:15], v[128:131], v[208:211], 0
	v_mfma_f32_16x16x32_bf16 v[8:11], v[136:139], v[208:211], 0
	v_mfma_f32_16x16x32_bf16 v[60:63], v[132:135], v[164:167], v[60:63]
	v_mfma_f32_16x16x32_bf16 v[56:59], v[140:143], v[164:167], v[56:59]
	v_mfma_f32_16x16x32_bf16 v[44:47], v[132:135], v[188:191], v[44:47]
	v_mfma_f32_16x16x32_bf16 v[40:43], v[140:143], v[188:191], v[40:43]
	v_mfma_f32_16x16x32_bf16 v[28:31], v[132:135], v[204:207], v[28:31]
	v_mfma_f32_16x16x32_bf16 v[24:27], v[140:143], v[204:207], v[24:27]
	v_mfma_f32_16x16x32_bf16 v[12:15], v[132:135], v[212:215], v[12:15]
	v_mfma_f32_16x16x32_bf16 v[8:11], v[140:143], v[212:215], v[8:11]
	v_mfma_f32_16x16x32_bf16 v[52:55], v[144:147], v[160:163], 0
	v_mfma_f32_16x16x32_bf16 v[48:51], v[152:155], v[160:163], 0
	v_mfma_f32_16x16x32_bf16 v[36:39], v[144:147], v[184:187], 0
	v_mfma_f32_16x16x32_bf16 v[32:35], v[152:155], v[184:187], 0
	v_mfma_f32_16x16x32_bf16 v[20:23], v[144:147], v[192:195], 0
	v_mfma_f32_16x16x32_bf16 v[16:19], v[152:155], v[192:195], 0
	v_mfma_f32_16x16x32_bf16 v[4:7], v[144:147], v[208:211], 0
	v_mfma_f32_16x16x32_bf16 v[0:3], v[152:155], v[208:211], 0
	v_mfma_f32_16x16x32_bf16 v[52:55], v[148:151], v[164:167], v[52:55]
	v_mfma_f32_16x16x32_bf16 v[48:51], v[156:159], v[164:167], v[48:51]
	v_mfma_f32_16x16x32_bf16 v[36:39], v[148:151], v[188:191], v[36:39]
	v_mfma_f32_16x16x32_bf16 v[32:35], v[156:159], v[188:191], v[32:35]
	v_mfma_f32_16x16x32_bf16 v[20:23], v[148:151], v[204:207], v[20:23]
	v_mfma_f32_16x16x32_bf16 v[16:19], v[156:159], v[204:207], v[16:19]
	v_mfma_f32_16x16x32_bf16 v[4:7], v[148:151], v[212:215], v[4:7]
	v_mfma_f32_16x16x32_bf16 v[0:3], v[156:159], v[212:215], v[0:3]
	s_barrier
	s_setprio 0
	s_add_i32 s69, 0, 0x18000
	s_add_i32 s70, 0, 0x1c000
	v_add_u32_e32 v140, s69, v199
	v_add_u32_e32 v156, s70, v199
	ds_read_b128 v[128:131], v140
	ds_read_b128 v[132:135], v140 offset:1024
	ds_read_b128 v[136:139], v140 offset:2048
	ds_read_b128 v[140:143], v140 offset:3072
	ds_read_b128 v[144:147], v156
	ds_read_b128 v[148:151], v156 offset:1024
	ds_read_b128 v[152:155], v156 offset:2048
	ds_read_b128 v[156:159], v156 offset:3072
	s_add_u32 s42, s42, 0xb0000
	s_addc_u32 s43, s43, 0
	s_mov_b32 m0, s51
	v_lshl_add_u64 v[222:223], s[42:43], 0, v[168:169]
	ds_read_b128 v[160:163], v203 offset:32768
	ds_read_b128 v[164:167], v203 offset:33792
	ds_read_b128 v[184:187], v203 offset:34816
	ds_read_b128 v[188:191], v203 offset:35840
	ds_read_b128 v[192:195], v203 offset:36864
	ds_read_b128 v[204:207], v203 offset:37888
	ds_read_b128 v[208:211], v203 offset:38912
	ds_read_b128 v[212:215], v203 offset:39936
	global_load_lds_dwordx4 v[222:223], off
	v_lshl_add_u64 v[222:223], s[42:43], 0, v[172:173]
	s_mov_b32 m0, s52
	s_nop 0
	global_load_lds_dwordx4 v[222:223], off
	s_waitcnt vmcnt(8)
	s_waitcnt lgkmcnt(0)
	s_barrier
	s_setprio 1
	v_mfma_f32_16x16x32_bf16 v[124:127], v[128:131], v[160:163], v[124:127]
	v_mfma_f32_16x16x32_bf16 v[120:123], v[136:139], v[160:163], v[120:123]
	v_mfma_f32_16x16x32_bf16 v[116:119], v[128:131], v[184:187], v[116:119]
	v_mfma_f32_16x16x32_bf16 v[104:107], v[136:139], v[184:187], v[104:107]
	v_mfma_f32_16x16x32_bf16 v[92:95], v[128:131], v[192:195], v[92:95]
	v_mfma_f32_16x16x32_bf16 v[88:91], v[136:139], v[192:195], v[88:91]
	v_mfma_f32_16x16x32_bf16 v[76:79], v[128:131], v[208:211], v[76:79]
	v_mfma_f32_16x16x32_bf16 v[72:75], v[136:139], v[208:211], v[72:75]
	v_mfma_f32_16x16x32_bf16 v[124:127], v[132:135], v[164:167], v[124:127]
	v_mfma_f32_16x16x32_bf16 v[120:123], v[140:143], v[164:167], v[120:123]
	v_mfma_f32_16x16x32_bf16 v[116:119], v[132:135], v[188:191], v[116:119]
	v_mfma_f32_16x16x32_bf16 v[104:107], v[140:143], v[188:191], v[104:107]
	v_mfma_f32_16x16x32_bf16 v[92:95], v[132:135], v[204:207], v[92:95]
	v_mfma_f32_16x16x32_bf16 v[88:91], v[140:143], v[204:207], v[88:91]
	v_mfma_f32_16x16x32_bf16 v[76:79], v[132:135], v[212:215], v[76:79]
	v_mfma_f32_16x16x32_bf16 v[72:75], v[140:143], v[212:215], v[72:75]
	v_mfma_f32_16x16x32_bf16 v[112:115], v[144:147], v[160:163], v[112:115]
	v_mfma_f32_16x16x32_bf16 v[108:111], v[152:155], v[160:163], v[108:111]
	v_mfma_f32_16x16x32_bf16 v[100:103], v[144:147], v[184:187], v[100:103]
	v_mfma_f32_16x16x32_bf16 v[96:99], v[152:155], v[184:187], v[96:99]
	v_mfma_f32_16x16x32_bf16 v[84:87], v[144:147], v[192:195], v[84:87]
	v_mfma_f32_16x16x32_bf16 v[80:83], v[152:155], v[192:195], v[80:83]
	v_mfma_f32_16x16x32_bf16 v[68:71], v[144:147], v[208:211], v[68:71]
	v_mfma_f32_16x16x32_bf16 v[64:67], v[152:155], v[208:211], v[64:67]
	v_mfma_f32_16x16x32_bf16 v[112:115], v[148:151], v[164:167], v[112:115]
	v_mfma_f32_16x16x32_bf16 v[108:111], v[156:159], v[164:167], v[108:111]
	v_mfma_f32_16x16x32_bf16 v[100:103], v[148:151], v[188:191], v[100:103]
	v_mfma_f32_16x16x32_bf16 v[96:99], v[156:159], v[188:191], v[96:99]
	v_mfma_f32_16x16x32_bf16 v[84:87], v[148:151], v[204:207], v[84:87]
	v_mfma_f32_16x16x32_bf16 v[80:83], v[156:159], v[204:207], v[80:83]
	v_mfma_f32_16x16x32_bf16 v[68:71], v[148:151], v[212:215], v[68:71]
	v_mfma_f32_16x16x32_bf16 v[64:67], v[156:159], v[212:215], v[64:67]
	s_barrier
; #define PG8_STAGE(bufoff, gbase, voff) do { _Pragma("unroll") for (int _i = 0; _i < 2; ++_i) \
;         __builtin_amdgcn_global_load_lds((const unsigned*)((const char*)(gbase) + (voff)[_i]), (PG8_LAS unsigned*)(lds + (bufoff) + ldsw + _i * 8192), 16, 0, 0); } while (0)
; #define PG8_LDA(dst, b, h) do { _Pragma("unroll") for (int m = 0; m < 4; ++m) _Pragma("unroll") for (int k = 0; k < 2; ++k) dst[m][k] = *(const PG8_LAS bf16x8*)(lds + PG8_SA(b, h) + aoff + m * 2048 + k * 1024); } while (0)
; #define PG8_MMA(ai, bj, At, Bt) do { __builtin_amdgcn_s_setprio(1); _Pragma("unroll") for (int m = 0; m < 4; ++m) _Pragma("unroll") for (int n = 0; n < 2; ++n) _Pragma("unroll") for (int k = 0; k < 2; ++k) \
;         acc[ai][bj][m][n] = __builtin_amdgcn_mfma_f32_16x16x32_bf16(Bt[n][k], At[m][k], acc[ai][bj][m][n], 0, 0, 0); __builtin_amdgcn_s_setprio(0); } while (0)
; #define PG8_WAIT_V(n) asm volatile("s_waitcnt vmcnt(" #n ")" ::: "memory")
; #define PG8_WAIT_L(n) asm volatile("s_waitcnt lgkmcnt(" #n ")" ::: "memory")
; #define PG8_BAR __builtin_amdgcn_s_barrier()
; #define PG8_SCHED __builtin_amdgcn_sched_barrier(0)
; template <class Epi, class Sched, bool ALIGN_EPI = false, bool SP2 = false>
; __device__ __forceinline__ void gemm_phase(PG8_LAS unsigned char* lds, const Gemm g, const Sched& S, const Epi& E) {
;     ...
;             PG8_LDA(At, 1, 1); PG8_STAGE(PG8_SB(1, 0), b3, voffB); PG8_STAGE(PG8_SB(1, 1), b3 + hstep, voffB); PG8_STAGE(PG8_SA(1, 0), a3, voffA);
;             PG8_WAIT_V(8); PG8_WAIT_L(0); PG8_BAR; PG8_MMA(1, 0, At, B0); PG8_MMA(1, 1, At, B1); PG8_BAR; PG8_SCHED;
	s_setprio 0
	s_add_i32 s42, s69, s48
	v_lshl_add_u64 v[196:197], v[196:197], 0, s[14:15]
	s_mov_b32 m0, s42
	ds_read_b128 v[160:163], v203 offset:49152
	ds_read_b128 v[164:167], v203 offset:50176
	ds_read_b128 v[184:187], v203 offset:51200
	ds_read_b128 v[188:191], v203 offset:52224
	ds_read_b128 v[192:195], v203 offset:53248
	ds_read_b128 v[204:207], v203 offset:54272
	ds_read_b128 v[208:211], v203 offset:55296
	ds_read_b128 v[212:215], v203 offset:56320
	global_load_lds_dwordx4 v[196:197], off
	s_add_i32 m0, s42, 0x2000
	s_add_u32 s40, s40, 0xb0080
	v_lshl_add_u64 v[196:197], v[216:217], 0, s[14:15]
	s_addc_u32 s41, s41, 0
	s_add_i32 s42, s70, s48
	global_load_lds_dwordx4 v[196:197], off
	v_lshl_add_u64 v[196:197], s[40:41], 0, v[170:171]
	s_mov_b32 m0, s42
	s_nop 0
	global_load_lds_dwordx4 v[196:197], off
	v_lshl_add_u64 v[196:197], s[40:41], 0, v[174:175]
	s_add_i32 m0, s42, 0x2000
	s_nop 0
	global_load_lds_dwordx4 v[196:197], off
	v_lshl_add_u64 v[196:197], v[218:219], 0, s[14:15]
	s_mov_b32 m0, s54
	s_nop 0
	global_load_lds_dwordx4 v[196:197], off
	v_lshl_add_u64 v[196:197], v[220:221], 0, s[14:15]
	s_mov_b32 m0, s55
	s_nop 0
	global_load_lds_dwordx4 v[196:197], off
	s_waitcnt vmcnt(8)
	s_waitcnt lgkmcnt(0)
	s_barrier
	s_setprio 1
	v_mfma_f32_16x16x32_bf16 v[60:63], v[128:131], v[160:163], v[60:63]
	v_mfma_f32_16x16x32_bf16 v[56:59], v[136:139], v[160:163], v[56:59]
	v_mfma_f32_16x16x32_bf16 v[44:47], v[128:131], v[184:187], v[44:47]
	v_mfma_f32_16x16x32_bf16 v[40:43], v[136:139], v[184:187], v[40:43]
	v_mfma_f32_16x16x32_bf16 v[28:31], v[128:131], v[192:195], v[28:31]
	v_mfma_f32_16x16x32_bf16 v[24:27], v[136:139], v[192:195], v[24:27]
	v_mfma_f32_16x16x32_bf16 v[12:15], v[128:131], v[208:211], v[12:15]
	v_mfma_f32_16x16x32_bf16 v[8:11], v[136:139], v[208:211], v[8:11]
	v_mfma_f32_16x16x32_bf16 v[60:63], v[132:135], v[164:167], v[60:63]
	v_mfma_f32_16x16x32_bf16 v[56:59], v[140:143], v[164:167], v[56:59]
	v_mfma_f32_16x16x32_bf16 v[44:47], v[132:135], v[188:191], v[44:47]
	v_mfma_f32_16x16x32_bf16 v[40:43], v[140:143], v[188:191], v[40:43]
	v_mfma_f32_16x16x32_bf16 v[28:31], v[132:135], v[204:207], v[28:31]
	v_mfma_f32_16x16x32_bf16 v[24:27], v[140:143], v[204:207], v[24:27]
	v_mfma_f32_16x16x32_bf16 v[12:15], v[132:135], v[212:215], v[12:15]
	v_mfma_f32_16x16x32_bf16 v[8:11], v[140:143], v[212:215], v[8:11]
	v_mfma_f32_16x16x32_bf16 v[52:55], v[144:147], v[160:163], v[52:55]
	v_mfma_f32_16x16x32_bf16 v[48:51], v[152:155], v[160:163], v[48:51]
	v_mfma_f32_16x16x32_bf16 v[36:39], v[144:147], v[184:187], v[36:39]
	v_mfma_f32_16x16x32_bf16 v[32:35], v[152:155], v[184:187], v[32:35]
	v_mfma_f32_16x16x32_bf16 v[20:23], v[144:147], v[192:195], v[20:23]
	v_mfma_f32_16x16x32_bf16 v[16:19], v[152:155], v[192:195], v[16:19]
	v_mfma_f32_16x16x32_bf16 v[4:7], v[144:147], v[208:211], v[4:7]
	v_mfma_f32_16x16x32_bf16 v[0:3], v[152:155], v[208:211], v[0:3]
	v_mfma_f32_16x16x32_bf16 v[52:55], v[148:151], v[164:167], v[52:55]
	v_mfma_f32_16x16x32_bf16 v[48:51], v[156:159], v[164:167], v[48:51]
	v_mfma_f32_16x16x32_bf16 v[36:39], v[148:151], v[188:191], v[36:39]
	v_mfma_f32_16x16x32_bf16 v[32:35], v[156:159], v[188:191], v[32:35]
	v_mfma_f32_16x16x32_bf16 v[20:23], v[148:151], v[204:207], v[20:23]
	v_mfma_f32_16x16x32_bf16 v[16:19], v[156:159], v[204:207], v[16:19]
	v_mfma_f32_16x16x32_bf16 v[4:7], v[148:151], v[212:215], v[4:7]
	v_mfma_f32_16x16x32_bf16 v[0:3], v[156:159], v[212:215], v[0:3]
	s_barrier
	s_setprio 0
	s_add_i32 s68, s68, 2
	s_add_u32 s38, s38, 0x100
	s_addc_u32 s39, s39, 0
	s_add_u32 s66, s66, 0x100
	s_addc_u32 s67, s67, 0

; __device__ __forceinline__ unsigned cvt_pk_bf16(float lo, float hi) { unsigned r; asm volatile("v_cvt_pk_bf16_f32 %0, %1, %2" : "=v"(r) : "v"(lo), "v"(hi)); return r; }
;     __device__ __forceinline__ void operator()(const f32x4 (&acc)[2][2][4][2], const Unit& u, int wr, int wc, int fr, int fq) const {
;     ...
;             u32x4 pre[2][4][2];
; #pragma unroll
;             for (int ai = 0; ai < 2; ++ai)
; #pragma unroll
;                 for (int m = 0; m < 4; ++m) { const size_t off = (size_t)(row0 + ai * HALF + m * 16) * 1024 + col0;
; #pragma unroll
;                     for (int bj = 0; bj < 2; ++bj) pre[ai][m][bj] = *(const u32x4*)(base16 + off + bj * HALF); }
;             asm volatile("" ::: "memory");
; #pragma unroll
;             for (int ai = 0; ai < 2; ++ai)
; #pragma unroll
;                 for (int m = 0; m < 4; ++m) {
;                     const int row = row0 + ai * HALF + m * 16; const size_t off = (size_t)row * 1024 + col0; float ss = 0.f;
; #pragma unroll
;                     for (int bj = 0; bj < 2; ++bj) { const u32x4 p = pre[ai][m][bj];
;                         const f32x4 b0 = {__uint_as_float(p.x << 16), __uint_as_float(p.x & 0xffff0000u), __uint_as_float(p.y << 16), __uint_as_float(p.y & 0xffff0000u)};
;                         const f32x4 b1 = {__uint_as_float(p.z << 16), __uint_as_float(p.z & 0xffff0000u), __uint_as_float(p.w << 16), __uint_as_float(p.w & 0xffff0000u)};
;                         const f32x4 v0 = b0 + acc[ai][bj][m][0] * alpha, v1 = b1 + acc[ai][bj][m][1] * alpha;
;                         store(off + bj * HALF, v0, v1, ss);
;                     }
;     __device__ __forceinline__ void store(size_t o, const f32x4& v0, const f32x4& v1, float& ss) const {
;         if (out32) { *(f32x4*)(out32 + o) = v0; *(f32x4*)(out32 + o + 4) = v1; }
;         ss += (v0[0] * v0[0] + v0[1] * v0[1]) + (v0[2] * v0[2] + v0[3] * v0[3]) + (v1[0] * v1[0] + v1[1] * v1[1]) + (v1[2] * v1[2] + v1[3] * v1[3]);
;         if (hb) { u32x4 w; w.x = cvt_pk_bf16(v0[0], v0[1]); w.y = cvt_pk_bf16(v0[2], v0[3]); w.z = cvt_pk_bf16(v1[0], v1[1]); w.w = cvt_pk_bf16(v1[2], v1[3]); *(u32x4*)(hb + o) = w; }
;     }
.LBB0_2600:
	v_lshl_or_b32 v130, s65, 8, v200
	v_lshl_add_u32 v128, s64, 8, v198
	v_ashrrev_i32_e32 v131, 31, v130
	v_lshlrev_b64 v[184:185], 1, v[130:131]
	v_ashrrev_i32_e32 v129, 31, v128
	v_lshl_add_u64 v[130:131], s[12:13], 0, v[184:185]
	v_lshlrev_b64 v[132:133], 11, v[128:129]
	v_lshl_add_u64 v[134:135], v[130:131], 0, v[132:133]
	global_load_dwordx4 v[204:207], v[134:135], off
	global_load_dwordx4 v[208:211], v[134:135], off offset:256
	v_or_b32_e32 v134, 16, v128
	v_ashrrev_i32_e32 v135, 31, v134
	v_lshlrev_b64 v[228:229], 11, v[134:135]
	v_lshl_add_u64 v[134:135], v[130:131], 0, v[228:229]
	global_load_dwordx4 v[212:215], v[134:135], off
	global_load_dwordx4 v[216:219], v[134:135], off offset:256
	v_or_b32_e32 v136, 32, v128
	v_or_b32_e32 v128, 48, v128
	v_ashrrev_i32_e32 v137, 31, v136
	v_ashrrev_i32_e32 v129, 31, v128
	v_lshlrev_b64 v[196:197], 11, v[136:137]
	v_lshlrev_b64 v[194:195], 11, v[128:129]
	v_lshl_add_u64 v[192:193], v[132:133], 0, s[18:19]
	v_lshl_add_u64 v[190:191], v[132:133], 0, s[20:21]
	v_lshl_add_u64 v[188:189], v[132:133], 0, s[22:23]
	v_lshl_add_u64 v[186:187], v[132:133], 0, s[34:35]
	v_lshl_add_u64 v[128:129], s[12:13], 0, v[132:133]
	v_lshl_add_u64 v[132:133], v[130:131], 0, v[196:197]
	v_lshl_add_u64 v[134:135], v[130:131], 0, v[194:195]
	v_lshl_add_u64 v[136:137], v[130:131], 0, v[192:193]
	v_lshl_add_u64 v[138:139], v[130:131], 0, v[190:191]
	v_lshl_add_u64 v[230:231], v[130:131], 0, v[188:189]
	v_lshl_add_u64 v[130:131], v[130:131], 0, v[186:187]
	v_lshl_add_u64 v[232:233], v[128:129], 0, v[184:185]
	global_load_dwordx4 v[220:223], v[132:133], off
	global_load_dwordx4 v[224:227], v[132:133], off offset:256
	global_load_dwordx4 v[164:167], v[134:135], off
	global_load_dwordx4 v[160:163], v[134:135], off offset:256
	global_load_dwordx4 v[156:159], v[136:137], off
	global_load_dwordx4 v[152:155], v[136:137], off offset:256
	global_load_dwordx4 v[148:151], v[138:139], off
	global_load_dwordx4 v[144:147], v[138:139], off offset:256
	global_load_dwordx4 v[140:143], v[230:231], off
	s_nop 0
	global_load_dwordx4 v[136:139], v[230:231], off offset:256
	global_load_dwordx4 v[132:135], v[130:131], off
	s_nop 0
	global_load_dwordx4 v[128:131], v[130:131], off offset:256
	s_and_b64 vcc, exec, s[4:5]
	s_mov_b64 s[4:5], -1
	s_waitcnt vmcnt(0)
	v_lshlrev_b32_e32 v230, 16, v204
	v_and_b32_e32 v231, 0xffff0000, v204
	v_lshlrev_b32_e32 v204, 16, v205
	v_and_b32_e32 v205, 0xffff0000, v205
	v_lshlrev_b32_e32 v234, 16, v206
	v_and_b32_e32 v235, 0xffff0000, v206
	v_lshlrev_b32_e32 v206, 16, v207
	v_and_b32_e32 v207, 0xffff0000, v207
	v_lshlrev_b32_e32 v238, 16, v210
	v_and_b32_e32 v239, 0xffff0000, v210
	v_lshlrev_b32_e32 v236, 16, v208
	v_and_b32_e32 v237, 0xffff0000, v208
	v_lshlrev_b32_e32 v208, 16, v209
	v_and_b32_e32 v209, 0xffff0000, v209
	v_lshlrev_b32_e32 v210, 16, v211
	v_and_b32_e32 v211, 0xffff0000, v211
	v_pk_fma_f32 v[126:127], v[126:127], 0.5, v[204:205] op_sel_hi:[1,0,1]
	v_pk_fma_f32 v[124:125], v[124:125], 0.5, v[230:231] op_sel_hi:[1,0,1]
	v_pk_fma_f32 v[122:123], v[122:123], 0.5, v[206:207] op_sel_hi:[1,0,1]
	v_pk_fma_f32 v[206:207], v[108:109], 0.5, v[238:239] op_sel_hi:[1,0,1]
	v_cvt_pk_bf16_f32 v108, v124, v125
	v_cvt_pk_bf16_f32 v109, v126, v127
	v_lshlrev_b32_e32 v240, 16, v212
	v_and_b32_e32 v241, 0xffff0000, v212
	v_pk_fma_f32 v[120:121], v[120:121], 0.5, v[234:235] op_sel_hi:[1,0,1]
	v_pk_fma_f32 v[114:115], v[114:115], 0.5, v[208:209] op_sel_hi:[1,0,1]
	v_pk_fma_f32 v[112:113], v[112:113], 0.5, v[236:237] op_sel_hi:[1,0,1]
	v_pk_fma_f32 v[204:205], v[110:111], 0.5, v[210:211] op_sel_hi:[1,0,1]
	v_cvt_pk_bf16_f32 v110, v120, v121
	v_cvt_pk_bf16_f32 v111, v122, v123
	global_store_dwordx4 v[232:233], v[108:111], off
	v_lshlrev_b32_e32 v244, 16, v214
	v_and_b32_e32 v245, 0xffff0000, v214
	v_cvt_pk_bf16_f32 v108, v112, v113
	v_cvt_pk_bf16_f32 v109, v114, v115
	v_lshlrev_b32_e32 v214, 16, v215
	v_and_b32_e32 v215, 0xffff0000, v215
	v_cvt_pk_bf16_f32 v110, v206, v207
	v_cvt_pk_bf16_f32 v111, v204, v205
	global_store_dwordx4 v[232:233], v[108:111], off offset:256
	v_lshlrev_b32_e32 v212, 16, v213
	v_and_b32_e32 v213, 0xffff0000, v213
	v_pk_fma_f32 v[108:109], v[116:117], 0.5, v[240:241] op_sel_hi:[1,0,1]
	v_pk_fma_f32 v[110:111], v[106:107], 0.5, v[214:215] op_sel_hi:[1,0,1]
	v_pk_fma_f32 v[106:107], v[104:105], 0.5, v[244:245] op_sel_hi:[1,0,1]
	v_cvt_pk_bf16_f32 v104, v108, v109
	v_lshl_add_u64 v[108:109], s[12:13], 0, v[228:229]
	v_pk_fma_f32 v[118:119], v[118:119], 0.5, v[212:213] op_sel_hi:[1,0,1]
	v_lshl_add_u64 v[108:109], v[108:109], 0, v[184:185]
	v_cvt_pk_bf16_f32 v105, v118, v119
	v_cvt_pk_bf16_f32 v106, v106, v107
	v_cvt_pk_bf16_f32 v107, v110, v111
	global_store_dwordx4 v[108:109], v[104:107], off
	v_lshlrev_b32_e32 v110, 16, v218
	v_and_b32_e32 v111, 0xffff0000, v218
	v_lshlrev_b32_e32 v104, 16, v216
	v_and_b32_e32 v105, 0xffff0000, v216
	v_lshlrev_b32_e32 v106, 16, v217
	v_and_b32_e32 v107, 0xffff0000, v217
	v_lshlrev_b32_e32 v112, 16, v219
	v_and_b32_e32 v113, 0xffff0000, v219
	v_pk_fma_f32 v[102:103], v[102:103], 0.5, v[106:107] op_sel_hi:[1,0,1]
	v_pk_fma_f32 v[100:101], v[100:101], 0.5, v[104:105] op_sel_hi:[1,0,1]
	v_pk_fma_f32 v[104:105], v[98:99], 0.5, v[112:113] op_sel_hi:[1,0,1]
	v_pk_fma_f32 v[98:99], v[96:97], 0.5, v[110:111] op_sel_hi:[1,0,1]
	v_cvt_pk_bf16_f32 v96, v100, v101
	v_cvt_pk_bf16_f32 v97, v102, v103
	v_lshlrev_b32_e32 v100, 16, v222
	v_cvt_pk_bf16_f32 v98, v98, v99
	v_cvt_pk_bf16_f32 v99, v104, v105
	global_store_dwordx4 v[108:109], v[96:99], off offset:256
	v_and_b32_e32 v101, 0xffff0000, v222
	v_lshlrev_b32_e32 v102, 16, v223
	v_lshlrev_b32_e32 v96, 16, v220
; __device__ __forceinline__ unsigned cvt_pk_bf16(float lo, float hi) { unsigned r; asm volatile("v_cvt_pk_bf16_f32 %0, %1, %2" : "=v"(r) : "v"(lo), "v"(hi)); return r; }
;     __device__ __forceinline__ void operator()(const f32x4 (&acc)[2][2][4][2], const Unit& u, int wr, int wc, int fr, int fq) const {
;     ...
;             for (int ai = 0; ai < 2; ++ai)
; #pragma unroll
;                 for (int m = 0; m < 4; ++m) {
;                     const int row = row0 + ai * HALF + m * 16; const size_t off = (size_t)row * 1024 + col0; float ss = 0.f;
; #pragma unroll
;                     for (int bj = 0; bj < 2; ++bj) { const u32x4 p = pre[ai][m][bj];
;                         const f32x4 b0 = {__uint_as_float(p.x << 16), __uint_as_float(p.x & 0xffff0000u), __uint_as_float(p.y << 16), __uint_as_float(p.y & 0xffff0000u)};
;                         const f32x4 b1 = {__uint_as_float(p.z << 16), __uint_as_float(p.z & 0xffff0000u), __uint_as_float(p.w << 16), __uint_as_float(p.w & 0xffff0000u)};
;                         const f32x4 v0 = b0 + acc[ai][bj][m][0] * alpha, v1 = b1 + acc[ai][bj][m][1] * alpha;
;                         store(off + bj * HALF, v0, v1, ss);
;                     }
;                     rowsum(row, ss, fq);
;                     if (m & 1) asm volatile("" ::: "memory");
;                 }
;         }
;     }
;     __device__ __forceinline__ void store(size_t o, const f32x4& v0, const f32x4& v1, float& ss) const {
;         if (out32) { *(f32x4*)(out32 + o) = v0; *(f32x4*)(out32 + o + 4) = v1; }
;         ss += (v0[0] * v0[0] + v0[1] * v0[1]) + (v0[2] * v0[2] + v0[3] * v0[3]) + (v1[0] * v1[0] + v1[1] * v1[1]) + (v1[2] * v1[2] + v1[3] * v1[3]);
;         if (hb) { u32x4 w; w.x = cvt_pk_bf16(v0[0], v0[1]); w.y = cvt_pk_bf16(v0[2], v0[3]); w.z = cvt_pk_bf16(v1[0], v1[1]); w.w = cvt_pk_bf16(v1[2], v1[3]); *(u32x4*)(hb + o) = w; }
;     }
	v_and_b32_e32 v97, 0xffff0000, v220
	v_and_b32_e32 v103, 0xffff0000, v223
	v_pk_fma_f32 v[92:93], v[92:93], 0.5, v[96:97] op_sel_hi:[1,0,1]
	v_lshlrev_b32_e32 v98, 16, v221
	v_and_b32_e32 v99, 0xffff0000, v221
	v_pk_fma_f32 v[96:97], v[90:91], 0.5, v[102:103] op_sel_hi:[1,0,1]
	v_pk_fma_f32 v[90:91], v[88:89], 0.5, v[100:101] op_sel_hi:[1,0,1]
	v_cvt_pk_bf16_f32 v88, v92, v93
	v_lshl_add_u64 v[92:93], s[12:13], 0, v[196:197]
	v_pk_fma_f32 v[94:95], v[94:95], 0.5, v[98:99] op_sel_hi:[1,0,1]
	v_lshl_add_u64 v[92:93], v[92:93], 0, v[184:185]
	v_cvt_pk_bf16_f32 v89, v94, v95
	v_cvt_pk_bf16_f32 v90, v90, v91
	v_cvt_pk_bf16_f32 v91, v96, v97
	global_store_dwordx4 v[92:93], v[88:91], off
	v_lshlrev_b32_e32 v94, 16, v226
	v_and_b32_e32 v95, 0xffff0000, v226
	v_lshlrev_b32_e32 v88, 16, v224
	v_and_b32_e32 v89, 0xffff0000, v224
	v_lshlrev_b32_e32 v90, 16, v225
	v_and_b32_e32 v91, 0xffff0000, v225
	v_lshlrev_b32_e32 v96, 16, v227
	v_and_b32_e32 v97, 0xffff0000, v227
	v_pk_fma_f32 v[86:87], v[86:87], 0.5, v[90:91] op_sel_hi:[1,0,1]
	v_pk_fma_f32 v[84:85], v[84:85], 0.5, v[88:89] op_sel_hi:[1,0,1]
	v_pk_fma_f32 v[88:89], v[82:83], 0.5, v[96:97] op_sel_hi:[1,0,1]
	v_pk_fma_f32 v[82:83], v[80:81], 0.5, v[94:95] op_sel_hi:[1,0,1]
	v_cvt_pk_bf16_f32 v80, v84, v85
	v_cvt_pk_bf16_f32 v81, v86, v87
	v_lshlrev_b32_e32 v84, 16, v166
	v_cvt_pk_bf16_f32 v82, v82, v83
	v_cvt_pk_bf16_f32 v83, v88, v89
	global_store_dwordx4 v[92:93], v[80:83], off offset:256
	v_and_b32_e32 v85, 0xffff0000, v166
	v_lshlrev_b32_e32 v86, 16, v167
	v_lshlrev_b32_e32 v80, 16, v164
	v_and_b32_e32 v81, 0xffff0000, v164
	v_and_b32_e32 v87, 0xffff0000, v167
	v_pk_fma_f32 v[76:77], v[76:77], 0.5, v[80:81] op_sel_hi:[1,0,1]
	v_lshlrev_b32_e32 v82, 16, v165
	v_and_b32_e32 v83, 0xffff0000, v165
	v_pk_fma_f32 v[80:81], v[74:75], 0.5, v[86:87] op_sel_hi:[1,0,1]
	v_pk_fma_f32 v[74:75], v[72:73], 0.5, v[84:85] op_sel_hi:[1,0,1]
	v_cvt_pk_bf16_f32 v72, v76, v77
	v_lshl_add_u64 v[76:77], s[12:13], 0, v[194:195]
	v_pk_fma_f32 v[78:79], v[78:79], 0.5, v[82:83] op_sel_hi:[1,0,1]
	v_lshl_add_u64 v[76:77], v[76:77], 0, v[184:185]
	v_cvt_pk_bf16_f32 v73, v78, v79
	v_cvt_pk_bf16_f32 v74, v74, v75
	v_cvt_pk_bf16_f32 v75, v80, v81
	global_store_dwordx4 v[76:77], v[72:75], off
	v_lshlrev_b32_e32 v78, 16, v162
	v_and_b32_e32 v79, 0xffff0000, v162
	v_lshlrev_b32_e32 v72, 16, v160
	v_and_b32_e32 v73, 0xffff0000, v160
	v_lshlrev_b32_e32 v74, 16, v161
	v_and_b32_e32 v75, 0xffff0000, v161
	v_lshlrev_b32_e32 v80, 16, v163
	v_and_b32_e32 v81, 0xffff0000, v163
	v_pk_fma_f32 v[70:71], v[70:71], 0.5, v[74:75] op_sel_hi:[1,0,1]
	v_pk_fma_f32 v[68:69], v[68:69], 0.5, v[72:73] op_sel_hi:[1,0,1]
	v_pk_fma_f32 v[72:73], v[66:67], 0.5, v[80:81] op_sel_hi:[1,0,1]
	v_pk_fma_f32 v[66:67], v[64:65], 0.5, v[78:79] op_sel_hi:[1,0,1]
	v_cvt_pk_bf16_f32 v64, v68, v69
	v_cvt_pk_bf16_f32 v65, v70, v71
	v_lshlrev_b32_e32 v68, 16, v158
	v_cvt_pk_bf16_f32 v66, v66, v67
	v_cvt_pk_bf16_f32 v67, v72, v73
	global_store_dwordx4 v[76:77], v[64:67], off offset:256
	v_and_b32_e32 v69, 0xffff0000, v158
	v_lshlrev_b32_e32 v70, 16, v159
	v_lshlrev_b32_e32 v64, 16, v156
	v_and_b32_e32 v65, 0xffff0000, v156
	v_and_b32_e32 v71, 0xffff0000, v159
	v_pk_fma_f32 v[60:61], v[60:61], 0.5, v[64:65] op_sel_hi:[1,0,1]
	v_lshlrev_b32_e32 v66, 16, v157
	v_and_b32_e32 v67, 0xffff0000, v157
	v_pk_fma_f32 v[64:65], v[58:59], 0.5, v[70:71] op_sel_hi:[1,0,1]
	v_pk_fma_f32 v[58:59], v[56:57], 0.5, v[68:69] op_sel_hi:[1,0,1]
	v_cvt_pk_bf16_f32 v56, v60, v61
	v_lshl_add_u64 v[60:61], s[12:13], 0, v[192:193]
	v_pk_fma_f32 v[62:63], v[62:63], 0.5, v[66:67] op_sel_hi:[1,0,1]
	v_lshl_add_u64 v[60:61], v[60:61], 0, v[184:185]
	v_cvt_pk_bf16_f32 v57, v62, v63
	v_cvt_pk_bf16_f32 v58, v58, v59
	v_cvt_pk_bf16_f32 v59, v64, v65
	global_store_dwordx4 v[60:61], v[56:59], off
	v_lshlrev_b32_e32 v62, 16, v154
	v_and_b32_e32 v63, 0xffff0000, v154
	v_lshlrev_b32_e32 v56, 16, v152
	v_and_b32_e32 v57, 0xffff0000, v152
	v_lshlrev_b32_e32 v58, 16, v153
	v_and_b32_e32 v59, 0xffff0000, v153
	v_lshlrev_b32_e32 v64, 16, v155
	v_and_b32_e32 v65, 0xffff0000, v155
	v_pk_fma_f32 v[54:55], v[54:55], 0.5, v[58:59] op_sel_hi:[1,0,1]
	v_pk_fma_f32 v[52:53], v[52:53], 0.5, v[56:57] op_sel_hi:[1,0,1]
	v_pk_fma_f32 v[56:57], v[50:51], 0.5, v[64:65] op_sel_hi:[1,0,1]
	v_pk_fma_f32 v[50:51], v[48:49], 0.5, v[62:63] op_sel_hi:[1,0,1]
	v_cvt_pk_bf16_f32 v48, v52, v53
	v_cvt_pk_bf16_f32 v49, v54, v55
	v_lshlrev_b32_e32 v52, 16, v150
	v_cvt_pk_bf16_f32 v50, v50, v51
	v_cvt_pk_bf16_f32 v51, v56, v57
	global_store_dwordx4 v[60:61], v[48:51], off offset:256
	v_and_b32_e32 v53, 0xffff0000, v150
	v_lshlrev_b32_e32 v54, 16, v151
;     __device__ __forceinline__ void operator()(const f32x4 (&acc)[2][2][4][2], const Unit& u, int wr, int wc, int fr, int fq) const {
;     ...
;             for (int ai = 0; ai < 2; ++ai)
; #pragma unroll
;                 for (int m = 0; m < 4; ++m) {
;                     const int row = row0 + ai * HALF + m * 16; const size_t off = (size_t)row * 1024 + col0; float ss = 0.f;
; #pragma unroll
;                     for (int bj = 0; bj < 2; ++bj) { const u32x4 p = pre[ai][m][bj];
;                         const f32x4 b0 = {__uint_as_float(p.x << 16), __uint_as_float(p.x & 0xffff0000u), __uint_as_float(p.y << 16), __uint_as_float(p.y & 0xffff0000u)};
;                         const f32x4 b1 = {__uint_as_float(p.z << 16), __uint_as_float(p.z & 0xffff0000u), __uint_as_float(p.w << 16), __uint_as_float(p.w & 0xffff0000u)};
;                         const f32x4 v0 = b0 + acc[ai][bj][m][0] * alpha, v1 = b1 + acc[ai][bj][m][1] * alpha;
;                         store(off + bj * HALF, v0, v1, ss);
;                     }
;                     rowsum(row, ss, fq);
;                     if (m & 1) asm volatile("" ::: "memory");
;                 }
;         }
;     }
;     __device__ __forceinline__ void store(size_t o, const f32x4& v0, const f32x4& v1, float& ss) const {
;         if (out32) { *(f32x4*)(out32 + o) = v0; *(f32x4*)(out32 + o + 4) = v1; }
;         ss += (v0[0] * v0[0] + v0[1] * v0[1]) + (v0[2] * v0[2] + v0[3] * v0[3]) + (v1[0] * v1[0] + v1[1] * v1[1]) + (v1[2] * v1[2] + v1[3] * v1[3]);
;         if (hb) { u32x4 w; w.x = cvt_pk_bf16(v0[0], v0[1]); w.y = cvt_pk_bf16(v0[2], v0[3]); w.z = cvt_pk_bf16(v1[0], v1[1]); w.w = cvt_pk_bf16(v1[2], v1[3]); *(u32x4*)(hb + o) = w; }
;     }
; template <class Epi, class Sched, bool ALIGN_EPI = false, bool SP2 = false>
; __device__ __forceinline__ void gemm_phase(PG8_LAS unsigned char* lds, const Gemm g, const Sched& S, const Epi& E) {
;     ...
;         if constexpr (!Epi::AFTER_DRAIN) { E(acc, cur, wr, wc, fr, fq); S.done(cur); }
;         if (!has_next) break;
; #pragma unroll
;         for (int a = 0; a < 2; ++a)
; #pragma unroll
;             for (int b = 0; b < 2; ++b)
; #pragma unroll
;                 for (int m = 0; m < 4; ++m)
; #pragma unroll
;                     for (int n = 0; n < 2; ++n) acc[a][b][m][n] = (f32x4){0.f, 0.f, 0.f, 0.f};
;         cur = nxt; cA = nA; cB = nB; ++ui;
	v_lshlrev_b32_e32 v48, 16, v148
	v_and_b32_e32 v49, 0xffff0000, v148
	v_and_b32_e32 v55, 0xffff0000, v151
	v_pk_fma_f32 v[44:45], v[44:45], 0.5, v[48:49] op_sel_hi:[1,0,1]
	v_lshlrev_b32_e32 v50, 16, v149
	v_and_b32_e32 v51, 0xffff0000, v149
	v_pk_fma_f32 v[48:49], v[42:43], 0.5, v[54:55] op_sel_hi:[1,0,1]
	v_pk_fma_f32 v[42:43], v[40:41], 0.5, v[52:53] op_sel_hi:[1,0,1]
	v_cvt_pk_bf16_f32 v40, v44, v45
	v_lshl_add_u64 v[44:45], s[12:13], 0, v[190:191]
	v_pk_fma_f32 v[46:47], v[46:47], 0.5, v[50:51] op_sel_hi:[1,0,1]
	v_lshl_add_u64 v[44:45], v[44:45], 0, v[184:185]
	v_cvt_pk_bf16_f32 v41, v46, v47
	v_cvt_pk_bf16_f32 v42, v42, v43
	v_cvt_pk_bf16_f32 v43, v48, v49
	global_store_dwordx4 v[44:45], v[40:43], off
	v_lshlrev_b32_e32 v46, 16, v146
	v_and_b32_e32 v47, 0xffff0000, v146
	v_lshlrev_b32_e32 v40, 16, v144
	v_and_b32_e32 v41, 0xffff0000, v144
	v_lshlrev_b32_e32 v42, 16, v145
	v_and_b32_e32 v43, 0xffff0000, v145
	v_lshlrev_b32_e32 v48, 16, v147
	v_and_b32_e32 v49, 0xffff0000, v147
	v_pk_fma_f32 v[38:39], v[38:39], 0.5, v[42:43] op_sel_hi:[1,0,1]
	v_pk_fma_f32 v[36:37], v[36:37], 0.5, v[40:41] op_sel_hi:[1,0,1]
	v_pk_fma_f32 v[40:41], v[34:35], 0.5, v[48:49] op_sel_hi:[1,0,1]
	v_pk_fma_f32 v[34:35], v[32:33], 0.5, v[46:47] op_sel_hi:[1,0,1]
	v_cvt_pk_bf16_f32 v32, v36, v37
	v_cvt_pk_bf16_f32 v33, v38, v39
	v_lshlrev_b32_e32 v36, 16, v142
	v_cvt_pk_bf16_f32 v34, v34, v35
	v_cvt_pk_bf16_f32 v35, v40, v41
	global_store_dwordx4 v[44:45], v[32:35], off offset:256
	v_and_b32_e32 v37, 0xffff0000, v142
	v_lshlrev_b32_e32 v38, 16, v143
	v_lshlrev_b32_e32 v32, 16, v140
	v_and_b32_e32 v33, 0xffff0000, v140
	v_and_b32_e32 v39, 0xffff0000, v143
	v_pk_fma_f32 v[28:29], v[28:29], 0.5, v[32:33] op_sel_hi:[1,0,1]
	v_lshlrev_b32_e32 v34, 16, v141
	v_and_b32_e32 v35, 0xffff0000, v141
	v_pk_fma_f32 v[32:33], v[26:27], 0.5, v[38:39] op_sel_hi:[1,0,1]
	v_pk_fma_f32 v[26:27], v[24:25], 0.5, v[36:37] op_sel_hi:[1,0,1]
	v_cvt_pk_bf16_f32 v24, v28, v29
	v_lshl_add_u64 v[28:29], s[12:13], 0, v[188:189]
	v_pk_fma_f32 v[30:31], v[30:31], 0.5, v[34:35] op_sel_hi:[1,0,1]
	v_lshl_add_u64 v[28:29], v[28:29], 0, v[184:185]
	v_cvt_pk_bf16_f32 v25, v30, v31
	v_cvt_pk_bf16_f32 v26, v26, v27
	v_cvt_pk_bf16_f32 v27, v32, v33
	global_store_dwordx4 v[28:29], v[24:27], off
	v_lshlrev_b32_e32 v30, 16, v138
	v_and_b32_e32 v31, 0xffff0000, v138
	v_lshlrev_b32_e32 v24, 16, v136
	v_and_b32_e32 v25, 0xffff0000, v136
	v_lshlrev_b32_e32 v26, 16, v137
	v_and_b32_e32 v27, 0xffff0000, v137
	v_lshlrev_b32_e32 v32, 16, v139
	v_and_b32_e32 v33, 0xffff0000, v139
	v_pk_fma_f32 v[22:23], v[22:23], 0.5, v[26:27] op_sel_hi:[1,0,1]
	v_pk_fma_f32 v[20:21], v[20:21], 0.5, v[24:25] op_sel_hi:[1,0,1]
	v_pk_fma_f32 v[24:25], v[18:19], 0.5, v[32:33] op_sel_hi:[1,0,1]
	v_pk_fma_f32 v[18:19], v[16:17], 0.5, v[30:31] op_sel_hi:[1,0,1]
	v_cvt_pk_bf16_f32 v16, v20, v21
	v_cvt_pk_bf16_f32 v17, v22, v23
	v_lshlrev_b32_e32 v20, 16, v134
	v_cvt_pk_bf16_f32 v18, v18, v19
	v_cvt_pk_bf16_f32 v19, v24, v25
	global_store_dwordx4 v[28:29], v[16:19], off offset:256
	v_and_b32_e32 v21, 0xffff0000, v134
	v_lshlrev_b32_e32 v22, 16, v135
	v_lshlrev_b32_e32 v16, 16, v132
	v_and_b32_e32 v17, 0xffff0000, v132
	v_and_b32_e32 v23, 0xffff0000, v135
	v_pk_fma_f32 v[12:13], v[12:13], 0.5, v[16:17] op_sel_hi:[1,0,1]
	v_lshlrev_b32_e32 v18, 16, v133
	v_and_b32_e32 v19, 0xffff0000, v133
	v_pk_fma_f32 v[16:17], v[10:11], 0.5, v[22:23] op_sel_hi:[1,0,1]
	v_pk_fma_f32 v[10:11], v[8:9], 0.5, v[20:21] op_sel_hi:[1,0,1]
	v_cvt_pk_bf16_f32 v8, v12, v13
	v_lshl_add_u64 v[12:13], s[12:13], 0, v[186:187]
	v_pk_fma_f32 v[14:15], v[14:15], 0.5, v[18:19] op_sel_hi:[1,0,1]
	v_lshl_add_u64 v[12:13], v[12:13], 0, v[184:185]
	v_cvt_pk_bf16_f32 v9, v14, v15
	v_cvt_pk_bf16_f32 v10, v10, v11
	v_cvt_pk_bf16_f32 v11, v16, v17
	global_store_dwordx4 v[12:13], v[8:11], off
	v_lshlrev_b32_e32 v14, 16, v130
	v_and_b32_e32 v15, 0xffff0000, v130
	v_lshlrev_b32_e32 v8, 16, v128
	v_and_b32_e32 v9, 0xffff0000, v128
	v_lshlrev_b32_e32 v16, 16, v131
	v_and_b32_e32 v17, 0xffff0000, v131
	v_lshlrev_b32_e32 v10, 16, v129
	v_and_b32_e32 v11, 0xffff0000, v129
	v_pk_fma_f32 v[4:5], v[4:5], 0.5, v[8:9] op_sel_hi:[1,0,1]
	v_pk_fma_f32 v[8:9], v[2:3], 0.5, v[16:17] op_sel_hi:[1,0,1]
	v_pk_fma_f32 v[2:3], v[0:1], 0.5, v[14:15] op_sel_hi:[1,0,1]
	v_pk_fma_f32 v[6:7], v[6:7], 0.5, v[10:11] op_sel_hi:[1,0,1]
	v_cvt_pk_bf16_f32 v0, v4, v5
	s_nop 0
	v_cvt_pk_bf16_f32 v1, v6, v7
	v_cvt_pk_bf16_f32 v2, v2, v3
	v_cvt_pk_bf16_f32 v3, v8, v9
	global_store_dwordx4 v[12:13], v[0:3], off offset:256
	s_cbranch_vccnz .LBB0_2585
	s_andn2_b64 vcc, exec, s[8:9]
	s_cbranch_vccnz .LBB0_2584
	s_mov_b32 s99, 1
	s_branch .LBB0_2584
